# sc0 cache-policy bit on the K-loop LDS-DMA staging loads (cache policy only; same bytes, same math) on top of the K-loop hand-off trim
# speedup vs baseline: 1.0029x; 1.0029x over previous
.LBB0_552:
	s_add_u32 s54, s44, 0xfff80080
	s_addc_u32 s55, s45, -1
	s_waitcnt lgkmcnt(0)
	s_add_i32 s82, 0, 0x10000
	s_cmp_eq_u32 s76, 28
	s_cselect_b32 s57, s41, s55
	s_cselect_b32 s56, s43, s54
	v_add_u32_e32 v161, s82, v159
	s_cselect_b32 s55, s35, s75
	s_cselect_b32 s54, s47, s74
	s_add_i32 vcc_lo, 0, 0x14000
	ds_read_b128 v[144:147], v161
	ds_read_b128 v[148:151], v161 offset:1024
	ds_read_b128 v[152:155], v161 offset:2048
	ds_read_b128 v[162:165], v161 offset:3072
	v_add_u32_e32 v161, vcc_lo, v159
	ds_read_b128 v[166:169], v161
	ds_read_b128 v[170:173], v161 offset:1024
	ds_read_b128 v[174:177], v161 offset:2048
	ds_read_b128 v[190:193], v161 offset:3072
	v_lshl_add_u64 v[178:179], s[44:45], 0, v[140:141]
	s_add_i32 m0, s58, 0xc000
	ds_read_b128 v[194:197], v160
	ds_read_b128 v[198:201], v160 offset:1024
	ds_read_b128 v[202:205], v160 offset:2048
	ds_read_b128 v[206:209], v160 offset:3072
	ds_read_b128 v[210:213], v160 offset:4096
	ds_read_b128 v[214:217], v160 offset:5120
	ds_read_b128 v[218:221], v160 offset:6144
	ds_read_b128 v[238:241], v160 offset:7168
	global_load_lds_dwordx4 v[178:179], off sc0
	v_lshl_add_u64 v[178:179], s[44:45], 0, v[142:143]
	s_add_i32 m0, s58, 0xe000
	s_nop 0
	global_load_lds_dwordx4 v[178:179], off sc0
	s_waitcnt vmcnt(8)
	s_waitcnt lgkmcnt(0)
	s_setprio 1
	s_barrier
	v_mfma_f32_16x16x32_bf16 v[126:129], v[144:147], v[194:197], v[126:129]
	v_mfma_f32_16x16x32_bf16 v[122:125], v[152:155], v[194:197], v[122:125]
	v_mfma_f32_16x16x32_bf16 v[110:113], v[144:147], v[202:205], v[110:113]
	v_mfma_f32_16x16x32_bf16 v[106:109], v[152:155], v[202:205], v[106:109]
	v_mfma_f32_16x16x32_bf16 v[94:97], v[144:147], v[210:213], v[94:97]
	v_mfma_f32_16x16x32_bf16 v[90:93], v[152:155], v[210:213], v[90:93]
	v_mfma_f32_16x16x32_bf16 v[78:81], v[144:147], v[218:221], v[78:81]
	v_mfma_f32_16x16x32_bf16 v[74:77], v[152:155], v[218:221], v[74:77]
	v_mfma_f32_16x16x32_bf16 v[126:129], v[148:151], v[198:201], v[126:129]
	v_mfma_f32_16x16x32_bf16 v[122:125], v[162:165], v[198:201], v[122:125]
	v_mfma_f32_16x16x32_bf16 v[110:113], v[148:151], v[206:209], v[110:113]
	v_mfma_f32_16x16x32_bf16 v[106:109], v[162:165], v[206:209], v[106:109]
	v_mfma_f32_16x16x32_bf16 v[94:97], v[148:151], v[214:217], v[94:97]
	v_mfma_f32_16x16x32_bf16 v[90:93], v[162:165], v[214:217], v[90:93]
	v_mfma_f32_16x16x32_bf16 v[78:81], v[148:151], v[238:241], v[78:81]
	v_mfma_f32_16x16x32_bf16 v[74:77], v[162:165], v[238:241], v[74:77]
	v_mfma_f32_16x16x32_bf16 v[118:121], v[166:169], v[194:197], v[118:121]
	v_mfma_f32_16x16x32_bf16 v[114:117], v[174:177], v[194:197], v[114:117]
	v_mfma_f32_16x16x32_bf16 v[102:105], v[166:169], v[202:205], v[102:105]
	v_mfma_f32_16x16x32_bf16 v[98:101], v[174:177], v[202:205], v[98:101]
	v_mfma_f32_16x16x32_bf16 v[86:89], v[166:169], v[210:213], v[86:89]
	v_mfma_f32_16x16x32_bf16 v[82:85], v[174:177], v[210:213], v[82:85]
	v_mfma_f32_16x16x32_bf16 v[70:73], v[166:169], v[218:221], v[70:73]
	v_mfma_f32_16x16x32_bf16 v[66:69], v[174:177], v[218:221], v[66:69]
	v_mfma_f32_16x16x32_bf16 v[118:121], v[170:173], v[198:201], v[118:121]
	v_mfma_f32_16x16x32_bf16 v[114:117], v[190:193], v[198:201], v[114:117]
	v_mfma_f32_16x16x32_bf16 v[102:105], v[170:173], v[206:209], v[102:105]
	v_mfma_f32_16x16x32_bf16 v[98:101], v[190:193], v[206:209], v[98:101]
	v_mfma_f32_16x16x32_bf16 v[86:89], v[170:173], v[214:217], v[86:89]
	v_mfma_f32_16x16x32_bf16 v[82:85], v[190:193], v[214:217], v[82:85]
	v_mfma_f32_16x16x32_bf16 v[70:73], v[170:173], v[238:241], v[70:73]
	v_mfma_f32_16x16x32_bf16 v[66:69], v[190:193], v[238:241], v[66:69]
	s_barrier
	s_setprio 0
	s_add_i32 s82, s82, s9
	v_lshl_add_u64 v[178:179], s[54:55], 0, v[134:135]
	s_mov_b32 m0, s82
	ds_read_b128 v[194:197], v160 offset:16384
	ds_read_b128 v[198:201], v160 offset:17408
	ds_read_b128 v[202:205], v160 offset:18432
	ds_read_b128 v[206:209], v160 offset:19456
	ds_read_b128 v[210:213], v160 offset:20480
	ds_read_b128 v[214:217], v160 offset:21504
	ds_read_b128 v[218:221], v160 offset:22528
	ds_read_b128 v[238:241], v160 offset:23552
	global_load_lds_dwordx4 v[178:179], off sc0
	s_add_i32 m0, s82, 0x2000
	s_add_u32 s82, s54, 0x80000
	v_lshl_add_u64 v[222:223], s[54:55], 0, v[138:139]
	s_addc_u32 s83, s55, 0
	s_add_i32 vcc_lo, vcc_lo, s9
	global_load_lds_dwordx4 v[222:223], off sc0
	v_lshl_add_u64 v[242:243], s[82:83], 0, v[134:135]
	s_mov_b32 m0, vcc_lo
	v_lshl_add_u64 v[244:245], s[56:57], 0, v[136:137]
	global_load_lds_dwordx4 v[242:243], off sc0
	v_lshl_add_u64 v[242:243], s[82:83], 0, v[138:139]
	s_add_i32 m0, vcc_lo, 0x2000
	s_nop 0
	global_load_lds_dwordx4 v[242:243], off sc0
	v_lshl_add_u64 v[242:243], s[56:57], 0, v[132:133]
	s_mov_b32 m0, s58
	s_nop 0
	global_load_lds_dwordx4 v[242:243], off sc0
	s_mov_b32 m0, s59
	s_nop 0
	global_load_lds_dwordx4 v[244:245], off sc0
	s_waitcnt vmcnt(8)
	s_waitcnt lgkmcnt(0)
	s_setprio 1
	s_barrier
	v_mfma_f32_16x16x32_bf16 v[62:65], v[144:147], v[194:197], v[62:65]
	v_mfma_f32_16x16x32_bf16 v[58:61], v[152:155], v[194:197], v[58:61]
	v_mfma_f32_16x16x32_bf16 v[46:49], v[144:147], v[202:205], v[46:49]
	v_mfma_f32_16x16x32_bf16 v[42:45], v[152:155], v[202:205], v[42:45]
	v_mfma_f32_16x16x32_bf16 v[30:33], v[144:147], v[210:213], v[30:33]
	v_mfma_f32_16x16x32_bf16 v[26:29], v[152:155], v[210:213], v[26:29]
	v_mfma_f32_16x16x32_bf16 v[14:17], v[144:147], v[218:221], v[14:17]
	v_mfma_f32_16x16x32_bf16 v[10:13], v[152:155], v[218:221], v[10:13]
	v_mfma_f32_16x16x32_bf16 v[62:65], v[148:151], v[198:201], v[62:65]
	v_mfma_f32_16x16x32_bf16 v[58:61], v[162:165], v[198:201], v[58:61]
	v_mfma_f32_16x16x32_bf16 v[46:49], v[148:151], v[206:209], v[46:49]
	v_mfma_f32_16x16x32_bf16 v[42:45], v[162:165], v[206:209], v[42:45]
	v_mfma_f32_16x16x32_bf16 v[30:33], v[148:151], v[214:217], v[30:33]
	v_mfma_f32_16x16x32_bf16 v[26:29], v[162:165], v[214:217], v[26:29]
	v_mfma_f32_16x16x32_bf16 v[14:17], v[148:151], v[238:241], v[14:17]
	v_mfma_f32_16x16x32_bf16 v[10:13], v[162:165], v[238:241], v[10:13]
	v_mfma_f32_16x16x32_bf16 v[54:57], v[166:169], v[194:197], v[54:57]
	v_mfma_f32_16x16x32_bf16 v[50:53], v[174:177], v[194:197], v[50:53]
	v_mfma_f32_16x16x32_bf16 v[38:41], v[166:169], v[202:205], v[38:41]
	v_mfma_f32_16x16x32_bf16 v[34:37], v[174:177], v[202:205], v[34:37]
	v_mfma_f32_16x16x32_bf16 v[22:25], v[166:169], v[210:213], v[22:25]
	v_mfma_f32_16x16x32_bf16 v[18:21], v[174:177], v[210:213], v[18:21]
	v_mfma_f32_16x16x32_bf16 v[6:9], v[166:169], v[218:221], v[6:9]
	v_mfma_f32_16x16x32_bf16 v[2:5], v[174:177], v[218:221], v[2:5]
	v_mfma_f32_16x16x32_bf16 v[54:57], v[170:173], v[198:201], v[54:57]
	v_mfma_f32_16x16x32_bf16 v[50:53], v[190:193], v[198:201], v[50:53]
	v_mfma_f32_16x16x32_bf16 v[38:41], v[170:173], v[206:209], v[38:41]
	v_mfma_f32_16x16x32_bf16 v[34:37], v[190:193], v[206:209], v[34:37]
	v_mfma_f32_16x16x32_bf16 v[22:25], v[170:173], v[214:217], v[22:25]
	v_mfma_f32_16x16x32_bf16 v[18:21], v[190:193], v[214:217], v[18:21]
	v_mfma_f32_16x16x32_bf16 v[6:9], v[170:173], v[238:241], v[6:9]
	v_mfma_f32_16x16x32_bf16 v[2:5], v[190:193], v[238:241], v[2:5]
	s_barrier
	s_setprio 0
	s_add_i32 s82, 0, 0x18000
	v_add_u32_e32 v161, s82, v159
	s_add_i32 s83, 0, 0x1c000
	ds_read_b128 v[144:147], v161
	ds_read_b128 v[148:151], v161 offset:1024
	ds_read_b128 v[152:155], v161 offset:2048
	ds_read_b128 v[162:165], v161 offset:3072
	v_add_u32_e32 v161, s83, v159
	ds_read_b128 v[166:169], v161
	ds_read_b128 v[170:173], v161 offset:1024
	ds_read_b128 v[174:177], v161 offset:2048
	ds_read_b128 v[190:193], v161 offset:3072
	s_add_u32 s56, s56, 0x80000
	s_addc_u32 s57, s57, 0
	s_mov_b32 m0, s60
	v_lshl_add_u64 v[246:247], s[56:57], 0, v[132:133]
	ds_read_b128 v[194:197], v160 offset:32768
	ds_read_b128 v[198:201], v160 offset:33792
	ds_read_b128 v[202:205], v160 offset:34816
	ds_read_b128 v[206:209], v160 offset:35840
	ds_read_b128 v[210:213], v160 offset:36864
	ds_read_b128 v[214:217], v160 offset:37888
	ds_read_b128 v[218:221], v160 offset:38912
	ds_read_b128 v[238:241], v160 offset:39936
	global_load_lds_dwordx4 v[246:247], off sc0
	v_lshl_add_u64 v[246:247], s[56:57], 0, v[136:137]
	s_mov_b32 m0, s61
	s_nop 0
	global_load_lds_dwordx4 v[246:247], off sc0
	s_waitcnt vmcnt(8)
	s_waitcnt lgkmcnt(0)
	s_setprio 1
	s_barrier
	v_mfma_f32_16x16x32_bf16 v[126:129], v[144:147], v[194:197], v[126:129]
	v_mfma_f32_16x16x32_bf16 v[122:125], v[152:155], v[194:197], v[122:125]
	v_mfma_f32_16x16x32_bf16 v[110:113], v[144:147], v[202:205], v[110:113]
	v_mfma_f32_16x16x32_bf16 v[106:109], v[152:155], v[202:205], v[106:109]
	v_mfma_f32_16x16x32_bf16 v[94:97], v[144:147], v[210:213], v[94:97]
	v_mfma_f32_16x16x32_bf16 v[90:93], v[152:155], v[210:213], v[90:93]
	v_mfma_f32_16x16x32_bf16 v[78:81], v[144:147], v[218:221], v[78:81]
	v_mfma_f32_16x16x32_bf16 v[74:77], v[152:155], v[218:221], v[74:77]
	v_mfma_f32_16x16x32_bf16 v[126:129], v[148:151], v[198:201], v[126:129]
	v_mfma_f32_16x16x32_bf16 v[122:125], v[162:165], v[198:201], v[122:125]
	v_mfma_f32_16x16x32_bf16 v[110:113], v[148:151], v[206:209], v[110:113]
	v_mfma_f32_16x16x32_bf16 v[106:109], v[162:165], v[206:209], v[106:109]
	v_mfma_f32_16x16x32_bf16 v[94:97], v[148:151], v[214:217], v[94:97]
	v_mfma_f32_16x16x32_bf16 v[90:93], v[162:165], v[214:217], v[90:93]
	v_mfma_f32_16x16x32_bf16 v[78:81], v[148:151], v[238:241], v[78:81]
	v_mfma_f32_16x16x32_bf16 v[74:77], v[162:165], v[238:241], v[74:77]
	v_mfma_f32_16x16x32_bf16 v[118:121], v[166:169], v[194:197], v[118:121]
	v_mfma_f32_16x16x32_bf16 v[114:117], v[174:177], v[194:197], v[114:117]
	v_mfma_f32_16x16x32_bf16 v[102:105], v[166:169], v[202:205], v[102:105]
	v_mfma_f32_16x16x32_bf16 v[98:101], v[174:177], v[202:205], v[98:101]
	v_mfma_f32_16x16x32_bf16 v[86:89], v[166:169], v[210:213], v[86:89]
	v_mfma_f32_16x16x32_bf16 v[82:85], v[174:177], v[210:213], v[82:85]
	v_mfma_f32_16x16x32_bf16 v[70:73], v[166:169], v[218:221], v[70:73]
	v_mfma_f32_16x16x32_bf16 v[66:69], v[174:177], v[218:221], v[66:69]
	v_mfma_f32_16x16x32_bf16 v[118:121], v[170:173], v[198:201], v[118:121]
	v_mfma_f32_16x16x32_bf16 v[114:117], v[190:193], v[198:201], v[114:117]
	v_mfma_f32_16x16x32_bf16 v[102:105], v[170:173], v[206:209], v[102:105]
	v_mfma_f32_16x16x32_bf16 v[98:101], v[190:193], v[206:209], v[98:101]
	v_mfma_f32_16x16x32_bf16 v[86:89], v[170:173], v[214:217], v[86:89]
	v_mfma_f32_16x16x32_bf16 v[82:85], v[190:193], v[214:217], v[82:85]
	v_mfma_f32_16x16x32_bf16 v[70:73], v[170:173], v[238:241], v[70:73]
	v_mfma_f32_16x16x32_bf16 v[66:69], v[190:193], v[238:241], v[66:69]
	s_barrier
	s_setprio 0
	s_add_i32 s56, s82, s9
	v_lshl_add_u64 v[178:179], v[178:179], 0, s[16:17]
	s_mov_b32 m0, s56
	ds_read_b128 v[194:197], v160 offset:49152
	ds_read_b128 v[198:201], v160 offset:50176
	ds_read_b128 v[202:205], v160 offset:51200
	ds_read_b128 v[206:209], v160 offset:52224
	ds_read_b128 v[210:213], v160 offset:53248
	ds_read_b128 v[214:217], v160 offset:54272
	ds_read_b128 v[218:221], v160 offset:55296
	ds_read_b128 v[238:241], v160 offset:56320
	global_load_lds_dwordx4 v[178:179], off sc0
	s_add_i32 m0, s56, 0x2000
	s_add_u32 s54, s54, 0x80080
	v_lshl_add_u64 v[178:179], v[222:223], 0, s[16:17]
	s_addc_u32 s55, s55, 0
	s_add_i32 s56, s83, s9
	global_load_lds_dwordx4 v[178:179], off sc0
	v_lshl_add_u64 v[178:179], s[54:55], 0, v[134:135]
	s_mov_b32 m0, s56
	s_nop 0
	global_load_lds_dwordx4 v[178:179], off sc0
	v_lshl_add_u64 v[178:179], s[54:55], 0, v[138:139]
	s_add_i32 m0, s56, 0x2000
	s_nop 0
	global_load_lds_dwordx4 v[178:179], off sc0
	v_lshl_add_u64 v[178:179], v[242:243], 0, s[16:17]
	s_mov_b32 m0, s64
	s_nop 0
	global_load_lds_dwordx4 v[178:179], off sc0
	v_lshl_add_u64 v[178:179], v[244:245], 0, s[16:17]
	s_mov_b32 m0, s69
	s_nop 0
	global_load_lds_dwordx4 v[178:179], off sc0
	s_waitcnt vmcnt(8)
	s_waitcnt lgkmcnt(0)
	s_setprio 1
	s_barrier
	v_mfma_f32_16x16x32_bf16 v[62:65], v[144:147], v[194:197], v[62:65]
	v_mfma_f32_16x16x32_bf16 v[58:61], v[152:155], v[194:197], v[58:61]
	v_mfma_f32_16x16x32_bf16 v[46:49], v[144:147], v[202:205], v[46:49]
	v_mfma_f32_16x16x32_bf16 v[42:45], v[152:155], v[202:205], v[42:45]
	v_mfma_f32_16x16x32_bf16 v[30:33], v[144:147], v[210:213], v[30:33]
	v_mfma_f32_16x16x32_bf16 v[26:29], v[152:155], v[210:213], v[26:29]
	v_mfma_f32_16x16x32_bf16 v[14:17], v[144:147], v[218:221], v[14:17]
	v_mfma_f32_16x16x32_bf16 v[10:13], v[152:155], v[218:221], v[10:13]
	v_mfma_f32_16x16x32_bf16 v[62:65], v[148:151], v[198:201], v[62:65]
	v_mfma_f32_16x16x32_bf16 v[58:61], v[162:165], v[198:201], v[58:61]
	v_mfma_f32_16x16x32_bf16 v[46:49], v[148:151], v[206:209], v[46:49]
	v_mfma_f32_16x16x32_bf16 v[42:45], v[162:165], v[206:209], v[42:45]
	v_mfma_f32_16x16x32_bf16 v[30:33], v[148:151], v[214:217], v[30:33]
	v_mfma_f32_16x16x32_bf16 v[26:29], v[162:165], v[214:217], v[26:29]
	v_mfma_f32_16x16x32_bf16 v[14:17], v[148:151], v[238:241], v[14:17]
	v_mfma_f32_16x16x32_bf16 v[10:13], v[162:165], v[238:241], v[10:13]
	v_mfma_f32_16x16x32_bf16 v[54:57], v[166:169], v[194:197], v[54:57]
	v_mfma_f32_16x16x32_bf16 v[50:53], v[174:177], v[194:197], v[50:53]
	v_mfma_f32_16x16x32_bf16 v[38:41], v[166:169], v[202:205], v[38:41]
	v_mfma_f32_16x16x32_bf16 v[34:37], v[174:177], v[202:205], v[34:37]
	v_mfma_f32_16x16x32_bf16 v[22:25], v[166:169], v[210:213], v[22:25]
	v_mfma_f32_16x16x32_bf16 v[18:21], v[174:177], v[210:213], v[18:21]
	v_mfma_f32_16x16x32_bf16 v[6:9], v[166:169], v[218:221], v[6:9]
	v_mfma_f32_16x16x32_bf16 v[2:5], v[174:177], v[218:221], v[2:5]
	v_mfma_f32_16x16x32_bf16 v[54:57], v[170:173], v[198:201], v[54:57]
	v_mfma_f32_16x16x32_bf16 v[50:53], v[190:193], v[198:201], v[50:53]
	v_mfma_f32_16x16x32_bf16 v[38:41], v[170:173], v[206:209], v[38:41]
	v_mfma_f32_16x16x32_bf16 v[34:37], v[190:193], v[206:209], v[34:37]
	v_mfma_f32_16x16x32_bf16 v[22:25], v[170:173], v[214:217], v[22:25]
	v_mfma_f32_16x16x32_bf16 v[18:21], v[190:193], v[214:217], v[18:21]
	v_mfma_f32_16x16x32_bf16 v[6:9], v[170:173], v[238:241], v[6:9]
	v_mfma_f32_16x16x32_bf16 v[2:5], v[190:193], v[238:241], v[2:5]
	s_barrier
	s_setprio 0
	s_add_i32 s76, s76, 2
	s_add_u32 s44, s44, 0x100
	s_addc_u32 s45, s45, 0
	s_add_u32 s74, s74, 0x100
	s_addc_u32 s75, s75, 0
	s_cmp_gt_u32 s76, 29
	s_cbranch_scc0 .LBB0_552
	s_and_b64 vcc, exec, s[30:31]
	s_cbranch_vccz .LBB0_555
	s_barrier

.LBB0_824:
	s_add_i32 s64, s40, 2
	s_add_u32 s69, s34, 0x80
	s_addc_u32 s41, s35, 0
	s_add_i32 s74, 0, 0x10000
	s_cmp_eq_u32 s57, s40
	s_cselect_b32 s41, s29, s41
	s_cselect_b32 s40, s28, s69
	v_add_u32_e32 v148, s74, v146
	s_cselect_b32 s71, s31, s63
	s_cselect_b32 s70, s30, s62
	s_add_i32 s69, 0, 0x14000
	ds_read_b128 v[154:157], v148
	ds_read_b128 v[158:161], v148 offset:1024
	ds_read_b128 v[162:165], v148 offset:2048
	ds_read_b128 v[166:169], v148 offset:3072
	v_add_u32_e32 v148, s69, v146
	ds_read_b128 v[170:173], v148
	ds_read_b128 v[174:177], v148 offset:1024
	ds_read_b128 v[190:193], v148 offset:2048
	ds_read_b128 v[194:197], v148 offset:3072
	v_lshl_add_u64 v[148:149], s[34:35], 0, v[140:141]
	s_add_i32 m0, s45, 0xc000
	ds_read_b128 v[198:201], v147
	ds_read_b128 v[202:205], v147 offset:1024
	ds_read_b128 v[206:209], v147 offset:2048
	ds_read_b128 v[210:213], v147 offset:3072
	ds_read_b128 v[214:217], v147 offset:4096
	ds_read_b128 v[218:221], v147 offset:5120
	ds_read_b128 v[238:241], v147 offset:6144
	ds_read_b128 v[242:245], v147 offset:7168
	global_load_lds_dwordx4 v[148:149], off sc0
	v_lshl_add_u64 v[148:149], s[34:35], 0, v[142:143]
	s_add_i32 m0, s45, 0xe000
	s_nop 0
	global_load_lds_dwordx4 v[148:149], off sc0
	s_waitcnt vmcnt(8)
	s_waitcnt lgkmcnt(0)
	s_setprio 1
	s_barrier
	v_mfma_f32_16x16x32_bf16 v[126:129], v[154:157], v[198:201], v[126:129]
	v_mfma_f32_16x16x32_bf16 v[122:125], v[162:165], v[198:201], v[122:125]
	v_mfma_f32_16x16x32_bf16 v[110:113], v[154:157], v[206:209], v[110:113]
	v_mfma_f32_16x16x32_bf16 v[106:109], v[162:165], v[206:209], v[106:109]
	v_mfma_f32_16x16x32_bf16 v[94:97], v[154:157], v[214:217], v[94:97]
	v_mfma_f32_16x16x32_bf16 v[90:93], v[162:165], v[214:217], v[90:93]
	v_mfma_f32_16x16x32_bf16 v[78:81], v[154:157], v[238:241], v[78:81]
	v_mfma_f32_16x16x32_bf16 v[74:77], v[162:165], v[238:241], v[74:77]
	v_mfma_f32_16x16x32_bf16 v[126:129], v[158:161], v[202:205], v[126:129]
	v_mfma_f32_16x16x32_bf16 v[122:125], v[166:169], v[202:205], v[122:125]
	v_mfma_f32_16x16x32_bf16 v[110:113], v[158:161], v[210:213], v[110:113]
	v_mfma_f32_16x16x32_bf16 v[106:109], v[166:169], v[210:213], v[106:109]
	v_mfma_f32_16x16x32_bf16 v[94:97], v[158:161], v[218:221], v[94:97]
	v_mfma_f32_16x16x32_bf16 v[90:93], v[166:169], v[218:221], v[90:93]
	v_mfma_f32_16x16x32_bf16 v[78:81], v[158:161], v[242:245], v[78:81]
	v_mfma_f32_16x16x32_bf16 v[74:77], v[166:169], v[242:245], v[74:77]
	v_mfma_f32_16x16x32_bf16 v[118:121], v[170:173], v[198:201], v[118:121]
	v_mfma_f32_16x16x32_bf16 v[114:117], v[190:193], v[198:201], v[114:117]
	v_mfma_f32_16x16x32_bf16 v[102:105], v[170:173], v[206:209], v[102:105]
	v_mfma_f32_16x16x32_bf16 v[98:101], v[190:193], v[206:209], v[98:101]
	v_mfma_f32_16x16x32_bf16 v[86:89], v[170:173], v[214:217], v[86:89]
	v_mfma_f32_16x16x32_bf16 v[82:85], v[190:193], v[214:217], v[82:85]
	v_mfma_f32_16x16x32_bf16 v[70:73], v[170:173], v[238:241], v[70:73]
	v_mfma_f32_16x16x32_bf16 v[66:69], v[190:193], v[238:241], v[66:69]
	v_mfma_f32_16x16x32_bf16 v[118:121], v[174:177], v[202:205], v[118:121]
	v_mfma_f32_16x16x32_bf16 v[114:117], v[194:197], v[202:205], v[114:117]
	v_mfma_f32_16x16x32_bf16 v[102:105], v[174:177], v[210:213], v[102:105]
	v_mfma_f32_16x16x32_bf16 v[98:101], v[194:197], v[210:213], v[98:101]
	v_mfma_f32_16x16x32_bf16 v[86:89], v[174:177], v[218:221], v[86:89]
	v_mfma_f32_16x16x32_bf16 v[82:85], v[194:197], v[218:221], v[82:85]
	v_mfma_f32_16x16x32_bf16 v[70:73], v[174:177], v[242:245], v[70:73]
	v_mfma_f32_16x16x32_bf16 v[66:69], v[194:197], v[242:245], v[66:69]
	s_barrier
	s_setprio 0
	s_add_i32 s74, s74, s44
	v_lshl_add_u64 v[148:149], s[70:71], 0, v[136:137]
	s_mov_b32 m0, s74
	ds_read_b128 v[198:201], v147 offset:16384
	ds_read_b128 v[202:205], v147 offset:17408
	ds_read_b128 v[206:209], v147 offset:18432
	ds_read_b128 v[210:213], v147 offset:19456
	ds_read_b128 v[214:217], v147 offset:20480
	ds_read_b128 v[218:221], v147 offset:21504
	ds_read_b128 v[238:241], v147 offset:22528
	ds_read_b128 v[242:245], v147 offset:23552
	global_load_lds_dwordx4 v[148:149], off sc0
	s_add_i32 m0, s74, 0x2000
	v_lshl_add_u64 v[178:179], s[70:71], 0, v[132:133]
	s_add_u32 s70, s70, s10
	s_addc_u32 s71, s71, s11
	s_add_i32 s69, s69, s44
	global_load_lds_dwordx4 v[178:179], off sc0
	v_lshl_add_u64 v[222:223], s[70:71], 0, v[136:137]
	s_mov_b32 m0, s69
	v_lshl_add_u64 v[246:247], s[70:71], 0, v[132:133]
	global_load_lds_dwordx4 v[222:223], off sc0
	s_add_i32 m0, s69, 0x2000
	v_lshl_add_u64 v[248:249], s[40:41], 0, v[138:139]
	global_load_lds_dwordx4 v[246:247], off sc0
	s_mov_b32 m0, s45
	v_lshl_add_u64 v[250:251], s[40:41], 0, v[134:135]
	global_load_lds_dwordx4 v[248:249], off sc0
	s_mov_b32 m0, s46
	s_nop 0
	global_load_lds_dwordx4 v[250:251], off sc0
	s_waitcnt vmcnt(8)
	s_waitcnt lgkmcnt(0)
	s_setprio 1
	s_barrier
	v_mfma_f32_16x16x32_bf16 v[62:65], v[154:157], v[198:201], v[62:65]
	v_mfma_f32_16x16x32_bf16 v[58:61], v[162:165], v[198:201], v[58:61]
	v_mfma_f32_16x16x32_bf16 v[46:49], v[154:157], v[206:209], v[46:49]
	v_mfma_f32_16x16x32_bf16 v[42:45], v[162:165], v[206:209], v[42:45]
	v_mfma_f32_16x16x32_bf16 v[30:33], v[154:157], v[214:217], v[30:33]
	v_mfma_f32_16x16x32_bf16 v[26:29], v[162:165], v[214:217], v[26:29]
	v_mfma_f32_16x16x32_bf16 v[14:17], v[154:157], v[238:241], v[14:17]
	v_mfma_f32_16x16x32_bf16 v[10:13], v[162:165], v[238:241], v[10:13]
	v_mfma_f32_16x16x32_bf16 v[62:65], v[158:161], v[202:205], v[62:65]
	v_mfma_f32_16x16x32_bf16 v[58:61], v[166:169], v[202:205], v[58:61]
	v_mfma_f32_16x16x32_bf16 v[46:49], v[158:161], v[210:213], v[46:49]
	v_mfma_f32_16x16x32_bf16 v[42:45], v[166:169], v[210:213], v[42:45]
	v_mfma_f32_16x16x32_bf16 v[30:33], v[158:161], v[218:221], v[30:33]
	v_mfma_f32_16x16x32_bf16 v[26:29], v[166:169], v[218:221], v[26:29]
	v_mfma_f32_16x16x32_bf16 v[14:17], v[158:161], v[242:245], v[14:17]
	v_mfma_f32_16x16x32_bf16 v[10:13], v[166:169], v[242:245], v[10:13]
	v_mfma_f32_16x16x32_bf16 v[54:57], v[170:173], v[198:201], v[54:57]
	v_mfma_f32_16x16x32_bf16 v[50:53], v[190:193], v[198:201], v[50:53]
	v_mfma_f32_16x16x32_bf16 v[38:41], v[170:173], v[206:209], v[38:41]
	v_mfma_f32_16x16x32_bf16 v[34:37], v[190:193], v[206:209], v[34:37]
	v_mfma_f32_16x16x32_bf16 v[22:25], v[170:173], v[214:217], v[22:25]
	v_mfma_f32_16x16x32_bf16 v[18:21], v[190:193], v[214:217], v[18:21]
	v_mfma_f32_16x16x32_bf16 v[6:9], v[170:173], v[238:241], v[6:9]
	v_mfma_f32_16x16x32_bf16 v[2:5], v[190:193], v[238:241], v[2:5]
	v_mfma_f32_16x16x32_bf16 v[54:57], v[174:177], v[202:205], v[54:57]
	v_mfma_f32_16x16x32_bf16 v[50:53], v[194:197], v[202:205], v[50:53]
	v_mfma_f32_16x16x32_bf16 v[38:41], v[174:177], v[210:213], v[38:41]
	v_mfma_f32_16x16x32_bf16 v[34:37], v[194:197], v[210:213], v[34:37]
	v_mfma_f32_16x16x32_bf16 v[22:25], v[174:177], v[218:221], v[22:25]
	v_mfma_f32_16x16x32_bf16 v[18:21], v[194:197], v[218:221], v[18:21]
	v_mfma_f32_16x16x32_bf16 v[6:9], v[174:177], v[242:245], v[6:9]
	v_mfma_f32_16x16x32_bf16 v[2:5], v[194:197], v[242:245], v[2:5]
	s_barrier
	s_setprio 0
	s_add_i32 s69, 0, 0x18000
	v_add_u32_e32 v151, s69, v146
	s_add_i32 s70, 0, 0x1c000
	ds_read_b128 v[154:157], v151
	ds_read_b128 v[158:161], v151 offset:1024
	ds_read_b128 v[162:165], v151 offset:2048
	ds_read_b128 v[166:169], v151 offset:3072
	v_add_u32_e32 v151, s70, v146
	ds_read_b128 v[170:173], v151
	ds_read_b128 v[174:177], v151 offset:1024
	ds_read_b128 v[190:193], v151 offset:2048
	ds_read_b128 v[194:197], v151 offset:3072
	s_add_u32 s40, s40, s10
	s_addc_u32 s41, s41, s11
	s_mov_b32 m0, s47
	v_lshl_add_u64 v[252:253], s[40:41], 0, v[138:139]
	ds_read_b128 v[198:201], v147 offset:32768
	ds_read_b128 v[202:205], v147 offset:33792
	ds_read_b128 v[206:209], v147 offset:34816
	ds_read_b128 v[210:213], v147 offset:35840
	ds_read_b128 v[214:217], v147 offset:36864
	ds_read_b128 v[218:221], v147 offset:37888
	ds_read_b128 v[238:241], v147 offset:38912
	ds_read_b128 v[242:245], v147 offset:39936
	global_load_lds_dwordx4 v[252:253], off sc0
	v_lshl_add_u64 v[252:253], s[40:41], 0, v[134:135]
	s_mov_b32 m0, s48
	s_nop 0
	global_load_lds_dwordx4 v[252:253], off sc0
	s_waitcnt vmcnt(8)
	s_waitcnt lgkmcnt(0)
	s_setprio 1
	s_barrier
	v_mfma_f32_16x16x32_bf16 v[126:129], v[154:157], v[198:201], v[126:129]
	v_mfma_f32_16x16x32_bf16 v[122:125], v[162:165], v[198:201], v[122:125]
	v_mfma_f32_16x16x32_bf16 v[110:113], v[154:157], v[206:209], v[110:113]
	v_mfma_f32_16x16x32_bf16 v[106:109], v[162:165], v[206:209], v[106:109]
	v_mfma_f32_16x16x32_bf16 v[94:97], v[154:157], v[214:217], v[94:97]
	v_mfma_f32_16x16x32_bf16 v[90:93], v[162:165], v[214:217], v[90:93]
	v_mfma_f32_16x16x32_bf16 v[78:81], v[154:157], v[238:241], v[78:81]
	v_mfma_f32_16x16x32_bf16 v[74:77], v[162:165], v[238:241], v[74:77]
	v_mfma_f32_16x16x32_bf16 v[126:129], v[158:161], v[202:205], v[126:129]
	v_mfma_f32_16x16x32_bf16 v[122:125], v[166:169], v[202:205], v[122:125]
	v_mfma_f32_16x16x32_bf16 v[110:113], v[158:161], v[210:213], v[110:113]
	v_mfma_f32_16x16x32_bf16 v[106:109], v[166:169], v[210:213], v[106:109]
	v_mfma_f32_16x16x32_bf16 v[94:97], v[158:161], v[218:221], v[94:97]
	v_mfma_f32_16x16x32_bf16 v[90:93], v[166:169], v[218:221], v[90:93]
	v_mfma_f32_16x16x32_bf16 v[78:81], v[158:161], v[242:245], v[78:81]
	v_mfma_f32_16x16x32_bf16 v[74:77], v[166:169], v[242:245], v[74:77]
	v_mfma_f32_16x16x32_bf16 v[118:121], v[170:173], v[198:201], v[118:121]
	v_mfma_f32_16x16x32_bf16 v[114:117], v[190:193], v[198:201], v[114:117]
	v_mfma_f32_16x16x32_bf16 v[102:105], v[170:173], v[206:209], v[102:105]
	v_mfma_f32_16x16x32_bf16 v[98:101], v[190:193], v[206:209], v[98:101]
	v_mfma_f32_16x16x32_bf16 v[86:89], v[170:173], v[214:217], v[86:89]
	v_mfma_f32_16x16x32_bf16 v[82:85], v[190:193], v[214:217], v[82:85]
	v_mfma_f32_16x16x32_bf16 v[70:73], v[170:173], v[238:241], v[70:73]
	v_mfma_f32_16x16x32_bf16 v[66:69], v[190:193], v[238:241], v[66:69]
	v_mfma_f32_16x16x32_bf16 v[118:121], v[174:177], v[202:205], v[118:121]
	v_mfma_f32_16x16x32_bf16 v[114:117], v[194:197], v[202:205], v[114:117]
	v_mfma_f32_16x16x32_bf16 v[102:105], v[174:177], v[210:213], v[102:105]
	v_mfma_f32_16x16x32_bf16 v[98:101], v[194:197], v[210:213], v[98:101]
	v_mfma_f32_16x16x32_bf16 v[86:89], v[174:177], v[218:221], v[86:89]
	v_mfma_f32_16x16x32_bf16 v[82:85], v[194:197], v[218:221], v[82:85]
	v_mfma_f32_16x16x32_bf16 v[70:73], v[174:177], v[242:245], v[70:73]
	v_mfma_f32_16x16x32_bf16 v[66:69], v[194:197], v[242:245], v[66:69]
	s_barrier
	s_setprio 0
	s_add_i32 s40, s69, s44
	v_lshl_add_u64 v[148:149], v[148:149], 0, s[16:17]
	s_mov_b32 m0, s40
	ds_read_b128 v[198:201], v147 offset:49152
	ds_read_b128 v[202:205], v147 offset:50176
	ds_read_b128 v[206:209], v147 offset:51200
	ds_read_b128 v[210:213], v147 offset:52224
	ds_read_b128 v[214:217], v147 offset:53248
	ds_read_b128 v[218:221], v147 offset:54272
	ds_read_b128 v[238:241], v147 offset:55296
	ds_read_b128 v[242:245], v147 offset:56320
	global_load_lds_dwordx4 v[148:149], off sc0
	v_lshl_add_u64 v[148:149], v[178:179], 0, s[16:17]
	s_add_i32 m0, s40, 0x2000
	s_add_i32 s40, s70, s44
	global_load_lds_dwordx4 v[148:149], off sc0
	v_lshl_add_u64 v[148:149], v[222:223], 0, s[16:17]
	s_mov_b32 m0, s40
	s_nop 0
	global_load_lds_dwordx4 v[148:149], off sc0
	v_lshl_add_u64 v[148:149], v[246:247], 0, s[16:17]
	s_add_i32 m0, s40, 0x2000
	s_nop 0
	global_load_lds_dwordx4 v[148:149], off sc0
	v_lshl_add_u64 v[148:149], v[248:249], 0, s[16:17]
	s_mov_b32 m0, s49
	s_nop 0
	global_load_lds_dwordx4 v[148:149], off sc0
	v_lshl_add_u64 v[148:149], v[250:251], 0, s[16:17]
	s_mov_b32 m0, s50
	s_nop 0
	global_load_lds_dwordx4 v[148:149], off sc0
	s_waitcnt vmcnt(8)
	s_waitcnt lgkmcnt(0)
	s_setprio 1
	s_barrier
	v_mfma_f32_16x16x32_bf16 v[62:65], v[154:157], v[198:201], v[62:65]
	v_mfma_f32_16x16x32_bf16 v[58:61], v[162:165], v[198:201], v[58:61]
	v_mfma_f32_16x16x32_bf16 v[46:49], v[154:157], v[206:209], v[46:49]
	v_mfma_f32_16x16x32_bf16 v[42:45], v[162:165], v[206:209], v[42:45]
	v_mfma_f32_16x16x32_bf16 v[30:33], v[154:157], v[214:217], v[30:33]
	v_mfma_f32_16x16x32_bf16 v[26:29], v[162:165], v[214:217], v[26:29]
	v_mfma_f32_16x16x32_bf16 v[14:17], v[154:157], v[238:241], v[14:17]
	v_mfma_f32_16x16x32_bf16 v[10:13], v[162:165], v[238:241], v[10:13]
	v_mfma_f32_16x16x32_bf16 v[62:65], v[158:161], v[202:205], v[62:65]
	v_mfma_f32_16x16x32_bf16 v[58:61], v[166:169], v[202:205], v[58:61]
	v_mfma_f32_16x16x32_bf16 v[46:49], v[158:161], v[210:213], v[46:49]
	v_mfma_f32_16x16x32_bf16 v[42:45], v[166:169], v[210:213], v[42:45]
	v_mfma_f32_16x16x32_bf16 v[30:33], v[158:161], v[218:221], v[30:33]
	v_mfma_f32_16x16x32_bf16 v[26:29], v[166:169], v[218:221], v[26:29]
	v_mfma_f32_16x16x32_bf16 v[14:17], v[158:161], v[242:245], v[14:17]
	v_mfma_f32_16x16x32_bf16 v[10:13], v[166:169], v[242:245], v[10:13]
	v_mfma_f32_16x16x32_bf16 v[54:57], v[170:173], v[198:201], v[54:57]
	v_mfma_f32_16x16x32_bf16 v[50:53], v[190:193], v[198:201], v[50:53]
	v_mfma_f32_16x16x32_bf16 v[38:41], v[170:173], v[206:209], v[38:41]
	v_mfma_f32_16x16x32_bf16 v[34:37], v[190:193], v[206:209], v[34:37]
	v_mfma_f32_16x16x32_bf16 v[22:25], v[170:173], v[214:217], v[22:25]
	v_mfma_f32_16x16x32_bf16 v[18:21], v[190:193], v[214:217], v[18:21]
	v_mfma_f32_16x16x32_bf16 v[6:9], v[170:173], v[238:241], v[6:9]
	v_mfma_f32_16x16x32_bf16 v[2:5], v[190:193], v[238:241], v[2:5]
	v_mfma_f32_16x16x32_bf16 v[54:57], v[174:177], v[202:205], v[54:57]
	v_mfma_f32_16x16x32_bf16 v[50:53], v[194:197], v[202:205], v[50:53]
	v_mfma_f32_16x16x32_bf16 v[38:41], v[174:177], v[210:213], v[38:41]
	v_mfma_f32_16x16x32_bf16 v[34:37], v[194:197], v[210:213], v[34:37]
	v_mfma_f32_16x16x32_bf16 v[22:25], v[174:177], v[218:221], v[22:25]
	v_mfma_f32_16x16x32_bf16 v[18:21], v[194:197], v[218:221], v[18:21]
	v_mfma_f32_16x16x32_bf16 v[6:9], v[174:177], v[242:245], v[6:9]
	v_mfma_f32_16x16x32_bf16 v[2:5], v[194:197], v[242:245], v[2:5]
	s_barrier
	s_setprio 0
	s_add_u32 s34, s34, 0x100
	s_addc_u32 s35, s35, 0
	s_add_u32 s62, s62, 0x100
	s_addc_u32 s63, s63, 0
	s_cmp_ge_i32 s64, s51
	s_mov_b32 s40, s64
	s_cbranch_scc0 .LBB0_824
	v_readlane_b32 s64, v255, 40
	s_mov_b32 s68, 0xff61b1e6
	s_mov_b32 s74, 0x24600000
	s_mov_b32 s69, 0xcf800000

.LBB0_937:
	s_add_u32 s34, s30, 0x100
	s_addc_u32 s35, s31, 0
	s_add_i32 s61, 0, 0x10000
	s_cmp_eq_u32 s60, 20
	s_cselect_b32 s43, s27, s35
	s_cselect_b32 s42, s26, s34
	s_cselect_b32 s41, s29, s59
	s_cselect_b32 s40, s28, s58
	s_add_i32 s62, 0, 0x14000
	v_add_u32_e32 v156, s61, v150
	v_add_u32_e32 v172, s62, v150
	ds_read_b128 v[140:143], v156
	ds_read_b128 v[144:147], v156 offset:1024
	ds_read_b128 v[152:155], v156 offset:2048
	ds_read_b128 v[156:159], v156 offset:3072
	ds_read_b128 v[160:163], v172
	ds_read_b128 v[164:167], v172 offset:1024
	ds_read_b128 v[168:171], v172 offset:2048
	ds_read_b128 v[172:175], v172 offset:3072
	v_lshl_add_u64 v[218:219], s[30:31], 0, v[136:137]
	s_add_i32 m0, s44, 0xc000
	ds_read_b128 v[176:179], v151
	ds_read_b128 v[190:193], v151 offset:1024
	ds_read_b128 v[194:197], v151 offset:2048
	ds_read_b128 v[198:201], v151 offset:3072
	ds_read_b128 v[202:205], v151 offset:4096
	ds_read_b128 v[206:209], v151 offset:5120
	ds_read_b128 v[210:213], v151 offset:6144
	ds_read_b128 v[214:217], v151 offset:7168
	global_load_lds_dwordx4 v[218:219], off sc0
	v_lshl_add_u64 v[218:219], s[30:31], 0, v[138:139]
	s_add_i32 m0, s44, 0xe000
	s_nop 0
	global_load_lds_dwordx4 v[218:219], off sc0
	s_waitcnt vmcnt(8)
	s_waitcnt lgkmcnt(0)
	s_setprio 1
	s_barrier
	v_mfma_f32_16x16x32_bf16 v[126:129], v[140:143], v[176:179], v[126:129]
	v_mfma_f32_16x16x32_bf16 v[122:125], v[152:155], v[176:179], v[122:125]
	v_mfma_f32_16x16x32_bf16 v[110:113], v[140:143], v[194:197], v[110:113]
	v_mfma_f32_16x16x32_bf16 v[106:109], v[152:155], v[194:197], v[106:109]
	v_mfma_f32_16x16x32_bf16 v[94:97], v[140:143], v[202:205], v[94:97]
	v_mfma_f32_16x16x32_bf16 v[90:93], v[152:155], v[202:205], v[90:93]
	v_mfma_f32_16x16x32_bf16 v[78:81], v[140:143], v[210:213], v[78:81]
	v_mfma_f32_16x16x32_bf16 v[74:77], v[152:155], v[210:213], v[74:77]
	v_mfma_f32_16x16x32_bf16 v[126:129], v[144:147], v[190:193], v[126:129]
	v_mfma_f32_16x16x32_bf16 v[122:125], v[156:159], v[190:193], v[122:125]
	v_mfma_f32_16x16x32_bf16 v[110:113], v[144:147], v[198:201], v[110:113]
	v_mfma_f32_16x16x32_bf16 v[106:109], v[156:159], v[198:201], v[106:109]
	v_mfma_f32_16x16x32_bf16 v[94:97], v[144:147], v[206:209], v[94:97]
	v_mfma_f32_16x16x32_bf16 v[90:93], v[156:159], v[206:209], v[90:93]
	v_mfma_f32_16x16x32_bf16 v[78:81], v[144:147], v[214:217], v[78:81]
	v_mfma_f32_16x16x32_bf16 v[74:77], v[156:159], v[214:217], v[74:77]
	v_mfma_f32_16x16x32_bf16 v[118:121], v[160:163], v[176:179], v[118:121]
	v_mfma_f32_16x16x32_bf16 v[114:117], v[168:171], v[176:179], v[114:117]
	v_mfma_f32_16x16x32_bf16 v[102:105], v[160:163], v[194:197], v[102:105]
	v_mfma_f32_16x16x32_bf16 v[98:101], v[168:171], v[194:197], v[98:101]
	v_mfma_f32_16x16x32_bf16 v[86:89], v[160:163], v[202:205], v[86:89]
	v_mfma_f32_16x16x32_bf16 v[82:85], v[168:171], v[202:205], v[82:85]
	v_mfma_f32_16x16x32_bf16 v[70:73], v[160:163], v[210:213], v[70:73]
	v_mfma_f32_16x16x32_bf16 v[66:69], v[168:171], v[210:213], v[66:69]
	v_mfma_f32_16x16x32_bf16 v[118:121], v[164:167], v[190:193], v[118:121]
	v_mfma_f32_16x16x32_bf16 v[114:117], v[172:175], v[190:193], v[114:117]
	v_mfma_f32_16x16x32_bf16 v[102:105], v[164:167], v[198:201], v[102:105]
	v_mfma_f32_16x16x32_bf16 v[98:101], v[172:175], v[198:201], v[98:101]
	v_mfma_f32_16x16x32_bf16 v[86:89], v[164:167], v[206:209], v[86:89]
	v_mfma_f32_16x16x32_bf16 v[82:85], v[172:175], v[206:209], v[82:85]
	v_mfma_f32_16x16x32_bf16 v[70:73], v[164:167], v[214:217], v[70:73]
	v_mfma_f32_16x16x32_bf16 v[66:69], v[172:175], v[214:217], v[66:69]
	s_barrier
	s_setprio 0
	s_add_i32 s30, s61, s21
	v_lshl_add_u64 v[218:219], s[40:41], 0, v[180:181]
	s_mov_b32 m0, s30
	ds_read_b128 v[176:179], v151 offset:16384
	ds_read_b128 v[190:193], v151 offset:17408
	ds_read_b128 v[194:197], v151 offset:18432
	ds_read_b128 v[198:201], v151 offset:19456
	ds_read_b128 v[202:205], v151 offset:20480
	ds_read_b128 v[206:209], v151 offset:21504
	ds_read_b128 v[210:213], v151 offset:22528
	ds_read_b128 v[214:217], v151 offset:23552
	global_load_lds_dwordx4 v[218:219], off sc0
	s_add_i32 m0, s30, 0x2000
	s_add_u32 s30, s40, 0x60000
	v_lshl_add_u64 v[220:221], s[40:41], 0, v[134:135]
	s_addc_u32 s31, s41, 0
	s_add_i32 s61, s62, s21
	global_load_lds_dwordx4 v[220:221], off sc0
	v_lshl_add_u64 v[222:223], s[30:31], 0, v[180:181]
	s_mov_b32 m0, s61
	v_lshl_add_u64 v[238:239], s[42:43], 0, v[132:133]
	global_load_lds_dwordx4 v[222:223], off sc0
	v_lshl_add_u64 v[222:223], s[30:31], 0, v[134:135]
	s_add_i32 m0, s61, 0x2000
	s_nop 0
	global_load_lds_dwordx4 v[222:223], off sc0
	v_lshl_add_u64 v[222:223], s[42:43], 0, v[130:131]
	s_mov_b32 m0, s44
	s_nop 0
	global_load_lds_dwordx4 v[222:223], off sc0
	s_mov_b32 m0, s45
	s_nop 0
	global_load_lds_dwordx4 v[238:239], off sc0
	s_waitcnt vmcnt(8)
	s_waitcnt lgkmcnt(0)
	s_setprio 1
	s_barrier
	v_mfma_f32_16x16x32_bf16 v[62:65], v[140:143], v[176:179], v[62:65]
	v_mfma_f32_16x16x32_bf16 v[58:61], v[152:155], v[176:179], v[58:61]
	v_mfma_f32_16x16x32_bf16 v[46:49], v[140:143], v[194:197], v[46:49]
	v_mfma_f32_16x16x32_bf16 v[42:45], v[152:155], v[194:197], v[42:45]
	v_mfma_f32_16x16x32_bf16 v[30:33], v[140:143], v[202:205], v[30:33]
	v_mfma_f32_16x16x32_bf16 v[26:29], v[152:155], v[202:205], v[26:29]
	v_mfma_f32_16x16x32_bf16 v[14:17], v[140:143], v[210:213], v[14:17]
	v_mfma_f32_16x16x32_bf16 v[10:13], v[152:155], v[210:213], v[10:13]
	v_mfma_f32_16x16x32_bf16 v[62:65], v[144:147], v[190:193], v[62:65]
	v_mfma_f32_16x16x32_bf16 v[58:61], v[156:159], v[190:193], v[58:61]
	v_mfma_f32_16x16x32_bf16 v[46:49], v[144:147], v[198:201], v[46:49]
	v_mfma_f32_16x16x32_bf16 v[42:45], v[156:159], v[198:201], v[42:45]
	v_mfma_f32_16x16x32_bf16 v[30:33], v[144:147], v[206:209], v[30:33]
	v_mfma_f32_16x16x32_bf16 v[26:29], v[156:159], v[206:209], v[26:29]
	v_mfma_f32_16x16x32_bf16 v[14:17], v[144:147], v[214:217], v[14:17]
	v_mfma_f32_16x16x32_bf16 v[10:13], v[156:159], v[214:217], v[10:13]
	v_mfma_f32_16x16x32_bf16 v[54:57], v[160:163], v[176:179], v[54:57]
	v_mfma_f32_16x16x32_bf16 v[50:53], v[168:171], v[176:179], v[50:53]
	v_mfma_f32_16x16x32_bf16 v[38:41], v[160:163], v[194:197], v[38:41]
	v_mfma_f32_16x16x32_bf16 v[34:37], v[168:171], v[194:197], v[34:37]
	v_mfma_f32_16x16x32_bf16 v[22:25], v[160:163], v[202:205], v[22:25]
	v_mfma_f32_16x16x32_bf16 v[18:21], v[168:171], v[202:205], v[18:21]
	v_mfma_f32_16x16x32_bf16 v[6:9], v[160:163], v[210:213], v[6:9]
	v_mfma_f32_16x16x32_bf16 v[2:5], v[168:171], v[210:213], v[2:5]
	v_mfma_f32_16x16x32_bf16 v[54:57], v[164:167], v[190:193], v[54:57]
	v_mfma_f32_16x16x32_bf16 v[50:53], v[172:175], v[190:193], v[50:53]
	v_mfma_f32_16x16x32_bf16 v[38:41], v[164:167], v[198:201], v[38:41]
	v_mfma_f32_16x16x32_bf16 v[34:37], v[172:175], v[198:201], v[34:37]
	v_mfma_f32_16x16x32_bf16 v[22:25], v[164:167], v[206:209], v[22:25]
	v_mfma_f32_16x16x32_bf16 v[18:21], v[172:175], v[206:209], v[18:21]
	v_mfma_f32_16x16x32_bf16 v[6:9], v[164:167], v[214:217], v[6:9]
	v_mfma_f32_16x16x32_bf16 v[2:5], v[172:175], v[214:217], v[2:5]
	s_barrier
	s_setprio 0
	s_add_i32 s61, 0, 0x18000
	s_add_i32 s62, 0, 0x1c000
	v_add_u32_e32 v156, s61, v150
	v_add_u32_e32 v172, s62, v150
	ds_read_b128 v[140:143], v156
	ds_read_b128 v[144:147], v156 offset:1024
	ds_read_b128 v[152:155], v156 offset:2048
	ds_read_b128 v[156:159], v156 offset:3072
	ds_read_b128 v[160:163], v172
	ds_read_b128 v[164:167], v172 offset:1024
	ds_read_b128 v[168:171], v172 offset:2048
	ds_read_b128 v[172:175], v172 offset:3072
	s_add_u32 s30, s42, 0x60000
	s_addc_u32 s31, s43, 0
	s_mov_b32 m0, s46
	v_lshl_add_u64 v[240:241], s[30:31], 0, v[130:131]
	ds_read_b128 v[176:179], v151 offset:32768
	ds_read_b128 v[190:193], v151 offset:33792
	ds_read_b128 v[194:197], v151 offset:34816
	ds_read_b128 v[198:201], v151 offset:35840
	ds_read_b128 v[202:205], v151 offset:36864
	ds_read_b128 v[206:209], v151 offset:37888
	ds_read_b128 v[210:213], v151 offset:38912
	ds_read_b128 v[214:217], v151 offset:39936
	global_load_lds_dwordx4 v[240:241], off sc0
	v_lshl_add_u64 v[240:241], s[30:31], 0, v[132:133]
	s_mov_b32 m0, s47
	s_nop 0
	global_load_lds_dwordx4 v[240:241], off sc0
	s_waitcnt vmcnt(8)
	s_waitcnt lgkmcnt(0)
	s_setprio 1
	s_barrier
	v_mfma_f32_16x16x32_bf16 v[126:129], v[140:143], v[176:179], v[126:129]
	v_mfma_f32_16x16x32_bf16 v[122:125], v[152:155], v[176:179], v[122:125]
	v_mfma_f32_16x16x32_bf16 v[110:113], v[140:143], v[194:197], v[110:113]
	v_mfma_f32_16x16x32_bf16 v[106:109], v[152:155], v[194:197], v[106:109]
	v_mfma_f32_16x16x32_bf16 v[94:97], v[140:143], v[202:205], v[94:97]
	v_mfma_f32_16x16x32_bf16 v[90:93], v[152:155], v[202:205], v[90:93]
	v_mfma_f32_16x16x32_bf16 v[78:81], v[140:143], v[210:213], v[78:81]
	v_mfma_f32_16x16x32_bf16 v[74:77], v[152:155], v[210:213], v[74:77]
	v_mfma_f32_16x16x32_bf16 v[126:129], v[144:147], v[190:193], v[126:129]
	v_mfma_f32_16x16x32_bf16 v[122:125], v[156:159], v[190:193], v[122:125]
	v_mfma_f32_16x16x32_bf16 v[110:113], v[144:147], v[198:201], v[110:113]
	v_mfma_f32_16x16x32_bf16 v[106:109], v[156:159], v[198:201], v[106:109]
	v_mfma_f32_16x16x32_bf16 v[94:97], v[144:147], v[206:209], v[94:97]
	v_mfma_f32_16x16x32_bf16 v[90:93], v[156:159], v[206:209], v[90:93]
	v_mfma_f32_16x16x32_bf16 v[78:81], v[144:147], v[214:217], v[78:81]
	v_mfma_f32_16x16x32_bf16 v[74:77], v[156:159], v[214:217], v[74:77]
	v_mfma_f32_16x16x32_bf16 v[118:121], v[160:163], v[176:179], v[118:121]
	v_mfma_f32_16x16x32_bf16 v[114:117], v[168:171], v[176:179], v[114:117]
	v_mfma_f32_16x16x32_bf16 v[102:105], v[160:163], v[194:197], v[102:105]
	v_mfma_f32_16x16x32_bf16 v[98:101], v[168:171], v[194:197], v[98:101]
	v_mfma_f32_16x16x32_bf16 v[86:89], v[160:163], v[202:205], v[86:89]
	v_mfma_f32_16x16x32_bf16 v[82:85], v[168:171], v[202:205], v[82:85]
	v_mfma_f32_16x16x32_bf16 v[70:73], v[160:163], v[210:213], v[70:73]
	v_mfma_f32_16x16x32_bf16 v[66:69], v[168:171], v[210:213], v[66:69]
	v_mfma_f32_16x16x32_bf16 v[118:121], v[164:167], v[190:193], v[118:121]
	v_mfma_f32_16x16x32_bf16 v[114:117], v[172:175], v[190:193], v[114:117]
	v_mfma_f32_16x16x32_bf16 v[102:105], v[164:167], v[198:201], v[102:105]
	v_mfma_f32_16x16x32_bf16 v[98:101], v[172:175], v[198:201], v[98:101]
	v_mfma_f32_16x16x32_bf16 v[86:89], v[164:167], v[206:209], v[86:89]
	v_mfma_f32_16x16x32_bf16 v[82:85], v[172:175], v[206:209], v[82:85]
	v_mfma_f32_16x16x32_bf16 v[70:73], v[164:167], v[214:217], v[70:73]
	v_mfma_f32_16x16x32_bf16 v[66:69], v[172:175], v[214:217], v[66:69]
	s_barrier
	s_setprio 0
	s_add_i32 s30, s61, s21
	v_lshl_add_u64 v[218:219], v[218:219], 0, s[16:17]
	s_mov_b32 m0, s30
	ds_read_b128 v[176:179], v151 offset:49152
	ds_read_b128 v[190:193], v151 offset:50176
	ds_read_b128 v[194:197], v151 offset:51200
	ds_read_b128 v[198:201], v151 offset:52224
	ds_read_b128 v[202:205], v151 offset:53248
	ds_read_b128 v[206:209], v151 offset:54272
	ds_read_b128 v[210:213], v151 offset:55296
	ds_read_b128 v[214:217], v151 offset:56320
	global_load_lds_dwordx4 v[218:219], off sc0
	s_add_i32 m0, s30, 0x2000
	s_add_u32 s30, s40, 0x60080
	v_lshl_add_u64 v[218:219], v[220:221], 0, s[16:17]
	s_addc_u32 s31, s41, 0
	s_add_i32 s40, s62, s21
	global_load_lds_dwordx4 v[218:219], off sc0
	v_lshl_add_u64 v[218:219], s[30:31], 0, v[180:181]
	s_mov_b32 m0, s40
	s_nop 0
	global_load_lds_dwordx4 v[218:219], off sc0
	v_lshl_add_u64 v[218:219], s[30:31], 0, v[134:135]
	s_add_i32 m0, s40, 0x2000
	s_nop 0
	global_load_lds_dwordx4 v[218:219], off sc0
	v_lshl_add_u64 v[218:219], v[222:223], 0, s[16:17]
	s_mov_b32 m0, s49
	s_nop 0
	global_load_lds_dwordx4 v[218:219], off sc0
	v_lshl_add_u64 v[218:219], v[238:239], 0, s[16:17]
	s_mov_b32 m0, s50
	s_nop 0
	global_load_lds_dwordx4 v[218:219], off sc0
	s_waitcnt vmcnt(8)
	s_waitcnt lgkmcnt(0)
	s_setprio 1
	s_barrier
	v_mfma_f32_16x16x32_bf16 v[62:65], v[140:143], v[176:179], v[62:65]
	v_mfma_f32_16x16x32_bf16 v[58:61], v[152:155], v[176:179], v[58:61]
	v_mfma_f32_16x16x32_bf16 v[46:49], v[140:143], v[194:197], v[46:49]
	v_mfma_f32_16x16x32_bf16 v[42:45], v[152:155], v[194:197], v[42:45]
	v_mfma_f32_16x16x32_bf16 v[30:33], v[140:143], v[202:205], v[30:33]
	v_mfma_f32_16x16x32_bf16 v[26:29], v[152:155], v[202:205], v[26:29]
	v_mfma_f32_16x16x32_bf16 v[14:17], v[140:143], v[210:213], v[14:17]
	v_mfma_f32_16x16x32_bf16 v[10:13], v[152:155], v[210:213], v[10:13]
	v_mfma_f32_16x16x32_bf16 v[62:65], v[144:147], v[190:193], v[62:65]
	v_mfma_f32_16x16x32_bf16 v[58:61], v[156:159], v[190:193], v[58:61]
	v_mfma_f32_16x16x32_bf16 v[46:49], v[144:147], v[198:201], v[46:49]
	v_mfma_f32_16x16x32_bf16 v[42:45], v[156:159], v[198:201], v[42:45]
	v_mfma_f32_16x16x32_bf16 v[30:33], v[144:147], v[206:209], v[30:33]
	v_mfma_f32_16x16x32_bf16 v[26:29], v[156:159], v[206:209], v[26:29]
	v_mfma_f32_16x16x32_bf16 v[14:17], v[144:147], v[214:217], v[14:17]
	v_mfma_f32_16x16x32_bf16 v[10:13], v[156:159], v[214:217], v[10:13]
	v_mfma_f32_16x16x32_bf16 v[54:57], v[160:163], v[176:179], v[54:57]
	v_mfma_f32_16x16x32_bf16 v[50:53], v[168:171], v[176:179], v[50:53]
	v_mfma_f32_16x16x32_bf16 v[38:41], v[160:163], v[194:197], v[38:41]
	v_mfma_f32_16x16x32_bf16 v[34:37], v[168:171], v[194:197], v[34:37]
	v_mfma_f32_16x16x32_bf16 v[22:25], v[160:163], v[202:205], v[22:25]
	v_mfma_f32_16x16x32_bf16 v[18:21], v[168:171], v[202:205], v[18:21]
	v_mfma_f32_16x16x32_bf16 v[6:9], v[160:163], v[210:213], v[6:9]
	v_mfma_f32_16x16x32_bf16 v[2:5], v[168:171], v[210:213], v[2:5]
	v_mfma_f32_16x16x32_bf16 v[54:57], v[164:167], v[190:193], v[54:57]
	v_mfma_f32_16x16x32_bf16 v[50:53], v[172:175], v[190:193], v[50:53]
	v_mfma_f32_16x16x32_bf16 v[38:41], v[164:167], v[198:201], v[38:41]
	v_mfma_f32_16x16x32_bf16 v[34:37], v[172:175], v[198:201], v[34:37]
	v_mfma_f32_16x16x32_bf16 v[22:25], v[164:167], v[206:209], v[22:25]
	v_mfma_f32_16x16x32_bf16 v[18:21], v[172:175], v[206:209], v[18:21]
	v_mfma_f32_16x16x32_bf16 v[6:9], v[164:167], v[214:217], v[6:9]
	v_mfma_f32_16x16x32_bf16 v[2:5], v[172:175], v[214:217], v[2:5]
	s_barrier
	s_setprio 0
	s_add_i32 s60, s60, 2
	s_add_u32 s58, s58, 0x100
	s_addc_u32 s59, s59, 0
	s_cmp_gt_u32 s60, 21
	s_mov_b64 s[30:31], s[34:35]
	s_cbranch_scc0 .LBB0_937
	s_and_b64 vcc, exec, s[24:25]
	s_cbranch_vccz .LBB0_940
	s_barrier

.LBB0_1018:
	s_add_u32 s40, s38, 0xfff80080
	s_addc_u32 s41, s39, -1
	s_add_i32 s51, 0, 0x10000
	s_cmp_eq_u32 s49, 28
	s_cselect_b32 s43, s11, s41
	s_cselect_b32 s42, s37, s40
	s_cselect_b32 s41, s44, s47
	s_cselect_b32 s40, s45, s46
	s_add_i32 s83, 0, 0x14000
	v_add_u32_e32 v154, s51, v159
	v_add_u32_e32 v161, s83, v159
	ds_read_b128 v[142:145], v154
	ds_read_b128 v[146:149], v154 offset:1024
	ds_read_b128 v[150:153], v154 offset:2048
	ds_read_b128 v[154:157], v154 offset:3072
	ds_read_b128 v[162:165], v161
	ds_read_b128 v[166:169], v161 offset:1024
	ds_read_b128 v[170:173], v161 offset:2048
	ds_read_b128 v[174:177], v161 offset:3072
	v_lshl_add_u64 v[178:179], s[38:39], 0, v[138:139]
	s_add_i32 m0, s61, 0xc000
	ds_read_b128 v[190:193], v160
	ds_read_b128 v[194:197], v160 offset:1024
	ds_read_b128 v[198:201], v160 offset:2048
	ds_read_b128 v[202:205], v160 offset:3072
	ds_read_b128 v[206:209], v160 offset:4096
	ds_read_b128 v[210:213], v160 offset:5120
	ds_read_b128 v[214:217], v160 offset:6144
	ds_read_b128 v[218:221], v160 offset:7168
	global_load_lds_dwordx4 v[178:179], off sc0
	v_lshl_add_u64 v[178:179], s[38:39], 0, v[140:141]
	s_add_i32 m0, s61, 0xe000
	s_nop 0
	global_load_lds_dwordx4 v[178:179], off sc0
	s_waitcnt vmcnt(8)
	s_waitcnt lgkmcnt(0)
	s_setprio 1
	s_barrier
	v_mfma_f32_16x16x32_bf16 v[126:129], v[142:145], v[190:193], v[126:129]
	v_mfma_f32_16x16x32_bf16 v[122:125], v[150:153], v[190:193], v[122:125]
	v_mfma_f32_16x16x32_bf16 v[110:113], v[142:145], v[198:201], v[110:113]
	v_mfma_f32_16x16x32_bf16 v[106:109], v[150:153], v[198:201], v[106:109]
	v_mfma_f32_16x16x32_bf16 v[94:97], v[142:145], v[206:209], v[94:97]
	v_mfma_f32_16x16x32_bf16 v[90:93], v[150:153], v[206:209], v[90:93]
	v_mfma_f32_16x16x32_bf16 v[78:81], v[142:145], v[214:217], v[78:81]
	v_mfma_f32_16x16x32_bf16 v[74:77], v[150:153], v[214:217], v[74:77]
	v_mfma_f32_16x16x32_bf16 v[126:129], v[146:149], v[194:197], v[126:129]
	v_mfma_f32_16x16x32_bf16 v[122:125], v[154:157], v[194:197], v[122:125]
	v_mfma_f32_16x16x32_bf16 v[110:113], v[146:149], v[202:205], v[110:113]
	v_mfma_f32_16x16x32_bf16 v[106:109], v[154:157], v[202:205], v[106:109]
	v_mfma_f32_16x16x32_bf16 v[94:97], v[146:149], v[210:213], v[94:97]
	v_mfma_f32_16x16x32_bf16 v[90:93], v[154:157], v[210:213], v[90:93]
	v_mfma_f32_16x16x32_bf16 v[78:81], v[146:149], v[218:221], v[78:81]
	v_mfma_f32_16x16x32_bf16 v[74:77], v[154:157], v[218:221], v[74:77]
	v_mfma_f32_16x16x32_bf16 v[118:121], v[162:165], v[190:193], v[118:121]
	v_mfma_f32_16x16x32_bf16 v[114:117], v[170:173], v[190:193], v[114:117]
	v_mfma_f32_16x16x32_bf16 v[102:105], v[162:165], v[198:201], v[102:105]
	v_mfma_f32_16x16x32_bf16 v[98:101], v[170:173], v[198:201], v[98:101]
	v_mfma_f32_16x16x32_bf16 v[86:89], v[162:165], v[206:209], v[86:89]
	v_mfma_f32_16x16x32_bf16 v[82:85], v[170:173], v[206:209], v[82:85]
	v_mfma_f32_16x16x32_bf16 v[70:73], v[162:165], v[214:217], v[70:73]
	v_mfma_f32_16x16x32_bf16 v[66:69], v[170:173], v[214:217], v[66:69]
	v_mfma_f32_16x16x32_bf16 v[118:121], v[166:169], v[194:197], v[118:121]
	v_mfma_f32_16x16x32_bf16 v[114:117], v[174:177], v[194:197], v[114:117]
	v_mfma_f32_16x16x32_bf16 v[102:105], v[166:169], v[202:205], v[102:105]
	v_mfma_f32_16x16x32_bf16 v[98:101], v[174:177], v[202:205], v[98:101]
	v_mfma_f32_16x16x32_bf16 v[86:89], v[166:169], v[210:213], v[86:89]
	v_mfma_f32_16x16x32_bf16 v[82:85], v[174:177], v[210:213], v[82:85]
	v_mfma_f32_16x16x32_bf16 v[70:73], v[166:169], v[218:221], v[70:73]
	v_mfma_f32_16x16x32_bf16 v[66:69], v[174:177], v[218:221], v[66:69]
	s_barrier
	s_setprio 0
	s_add_i32 s51, s51, s60
	v_lshl_add_u64 v[178:179], s[40:41], 0, v[180:181]
	s_mov_b32 m0, s51
	ds_read_b128 v[190:193], v160 offset:16384
	ds_read_b128 v[194:197], v160 offset:17408
	ds_read_b128 v[198:201], v160 offset:18432
	ds_read_b128 v[202:205], v160 offset:19456
	ds_read_b128 v[206:209], v160 offset:20480
	ds_read_b128 v[210:213], v160 offset:21504
	ds_read_b128 v[214:217], v160 offset:22528
	ds_read_b128 v[218:221], v160 offset:23552
	global_load_lds_dwordx4 v[178:179], off sc0
	s_add_i32 m0, s51, 0x2000
	s_add_u32 vcc_lo, s40, 0x80000
	v_lshl_add_u64 v[222:223], s[40:41], 0, v[136:137]
	s_addc_u32 vcc_hi, s41, 0
	s_add_i32 s51, s83, s60
	global_load_lds_dwordx4 v[222:223], off sc0
	v_lshl_add_u64 v[238:239], vcc, 0, v[180:181]
	s_mov_b32 m0, s51
	v_lshl_add_u64 v[240:241], s[42:43], 0, v[134:135]
	global_load_lds_dwordx4 v[238:239], off sc0
	v_lshl_add_u64 v[238:239], vcc, 0, v[136:137]
	s_add_i32 m0, s51, 0x2000
	s_nop 0
	global_load_lds_dwordx4 v[238:239], off sc0
	v_lshl_add_u64 v[238:239], s[42:43], 0, v[132:133]
	s_mov_b32 m0, s61
	s_nop 0
	global_load_lds_dwordx4 v[238:239], off sc0
	s_mov_b32 m0, s62
	s_nop 0
	global_load_lds_dwordx4 v[240:241], off sc0
	s_waitcnt vmcnt(8)
	s_waitcnt lgkmcnt(0)
	s_setprio 1
	s_barrier
	v_mfma_f32_16x16x32_bf16 v[62:65], v[142:145], v[190:193], v[62:65]
	v_mfma_f32_16x16x32_bf16 v[58:61], v[150:153], v[190:193], v[58:61]
	v_mfma_f32_16x16x32_bf16 v[46:49], v[142:145], v[198:201], v[46:49]
	v_mfma_f32_16x16x32_bf16 v[42:45], v[150:153], v[198:201], v[42:45]
	v_mfma_f32_16x16x32_bf16 v[30:33], v[142:145], v[206:209], v[30:33]
	v_mfma_f32_16x16x32_bf16 v[26:29], v[150:153], v[206:209], v[26:29]
	v_mfma_f32_16x16x32_bf16 v[14:17], v[142:145], v[214:217], v[14:17]
	v_mfma_f32_16x16x32_bf16 v[10:13], v[150:153], v[214:217], v[10:13]
	v_mfma_f32_16x16x32_bf16 v[62:65], v[146:149], v[194:197], v[62:65]
	v_mfma_f32_16x16x32_bf16 v[58:61], v[154:157], v[194:197], v[58:61]
	v_mfma_f32_16x16x32_bf16 v[46:49], v[146:149], v[202:205], v[46:49]
	v_mfma_f32_16x16x32_bf16 v[42:45], v[154:157], v[202:205], v[42:45]
	v_mfma_f32_16x16x32_bf16 v[30:33], v[146:149], v[210:213], v[30:33]
	v_mfma_f32_16x16x32_bf16 v[26:29], v[154:157], v[210:213], v[26:29]
	v_mfma_f32_16x16x32_bf16 v[14:17], v[146:149], v[218:221], v[14:17]
	v_mfma_f32_16x16x32_bf16 v[10:13], v[154:157], v[218:221], v[10:13]
	v_mfma_f32_16x16x32_bf16 v[54:57], v[162:165], v[190:193], v[54:57]
	v_mfma_f32_16x16x32_bf16 v[50:53], v[170:173], v[190:193], v[50:53]
	v_mfma_f32_16x16x32_bf16 v[38:41], v[162:165], v[198:201], v[38:41]
	v_mfma_f32_16x16x32_bf16 v[34:37], v[170:173], v[198:201], v[34:37]
	v_mfma_f32_16x16x32_bf16 v[22:25], v[162:165], v[206:209], v[22:25]
	v_mfma_f32_16x16x32_bf16 v[18:21], v[170:173], v[206:209], v[18:21]
	v_mfma_f32_16x16x32_bf16 v[6:9], v[162:165], v[214:217], v[6:9]
	v_mfma_f32_16x16x32_bf16 v[2:5], v[170:173], v[214:217], v[2:5]
	v_mfma_f32_16x16x32_bf16 v[54:57], v[166:169], v[194:197], v[54:57]
	v_mfma_f32_16x16x32_bf16 v[50:53], v[174:177], v[194:197], v[50:53]
	v_mfma_f32_16x16x32_bf16 v[38:41], v[166:169], v[202:205], v[38:41]
	v_mfma_f32_16x16x32_bf16 v[34:37], v[174:177], v[202:205], v[34:37]
	v_mfma_f32_16x16x32_bf16 v[22:25], v[166:169], v[210:213], v[22:25]
	v_mfma_f32_16x16x32_bf16 v[18:21], v[174:177], v[210:213], v[18:21]
	v_mfma_f32_16x16x32_bf16 v[6:9], v[166:169], v[218:221], v[6:9]
	v_mfma_f32_16x16x32_bf16 v[2:5], v[174:177], v[218:221], v[2:5]
	s_barrier
	s_setprio 0
	s_add_i32 s51, 0, 0x18000
	s_add_i32 s83, 0, 0x1c000
	v_add_u32_e32 v154, s51, v159
	v_add_u32_e32 v161, s83, v159
	ds_read_b128 v[142:145], v154
	ds_read_b128 v[146:149], v154 offset:1024
	ds_read_b128 v[150:153], v154 offset:2048
	ds_read_b128 v[154:157], v154 offset:3072
	ds_read_b128 v[162:165], v161
	ds_read_b128 v[166:169], v161 offset:1024
	ds_read_b128 v[170:173], v161 offset:2048
	ds_read_b128 v[174:177], v161 offset:3072
	s_add_u32 s42, s42, 0x80000
	s_addc_u32 s43, s43, 0
	s_mov_b32 m0, s63
	v_lshl_add_u64 v[242:243], s[42:43], 0, v[132:133]
	ds_read_b128 v[190:193], v160 offset:32768
	ds_read_b128 v[194:197], v160 offset:33792
	ds_read_b128 v[198:201], v160 offset:34816
	ds_read_b128 v[202:205], v160 offset:35840
	ds_read_b128 v[206:209], v160 offset:36864
	ds_read_b128 v[210:213], v160 offset:37888
	ds_read_b128 v[214:217], v160 offset:38912
	ds_read_b128 v[218:221], v160 offset:39936
	global_load_lds_dwordx4 v[242:243], off sc0
	v_lshl_add_u64 v[242:243], s[42:43], 0, v[134:135]
	s_mov_b32 m0, s64
	s_nop 0
	global_load_lds_dwordx4 v[242:243], off sc0
	s_waitcnt vmcnt(8)
	s_waitcnt lgkmcnt(0)
	s_setprio 1
	s_barrier
	v_mfma_f32_16x16x32_bf16 v[126:129], v[142:145], v[190:193], v[126:129]
	v_mfma_f32_16x16x32_bf16 v[122:125], v[150:153], v[190:193], v[122:125]
	v_mfma_f32_16x16x32_bf16 v[110:113], v[142:145], v[198:201], v[110:113]
	v_mfma_f32_16x16x32_bf16 v[106:109], v[150:153], v[198:201], v[106:109]
	v_mfma_f32_16x16x32_bf16 v[94:97], v[142:145], v[206:209], v[94:97]
	v_mfma_f32_16x16x32_bf16 v[90:93], v[150:153], v[206:209], v[90:93]
	v_mfma_f32_16x16x32_bf16 v[78:81], v[142:145], v[214:217], v[78:81]
	v_mfma_f32_16x16x32_bf16 v[74:77], v[150:153], v[214:217], v[74:77]
	v_mfma_f32_16x16x32_bf16 v[126:129], v[146:149], v[194:197], v[126:129]
	v_mfma_f32_16x16x32_bf16 v[122:125], v[154:157], v[194:197], v[122:125]
	v_mfma_f32_16x16x32_bf16 v[110:113], v[146:149], v[202:205], v[110:113]
	v_mfma_f32_16x16x32_bf16 v[106:109], v[154:157], v[202:205], v[106:109]
	v_mfma_f32_16x16x32_bf16 v[94:97], v[146:149], v[210:213], v[94:97]
	v_mfma_f32_16x16x32_bf16 v[90:93], v[154:157], v[210:213], v[90:93]
	v_mfma_f32_16x16x32_bf16 v[78:81], v[146:149], v[218:221], v[78:81]
	v_mfma_f32_16x16x32_bf16 v[74:77], v[154:157], v[218:221], v[74:77]
	v_mfma_f32_16x16x32_bf16 v[118:121], v[162:165], v[190:193], v[118:121]
	v_mfma_f32_16x16x32_bf16 v[114:117], v[170:173], v[190:193], v[114:117]
	v_mfma_f32_16x16x32_bf16 v[102:105], v[162:165], v[198:201], v[102:105]
	v_mfma_f32_16x16x32_bf16 v[98:101], v[170:173], v[198:201], v[98:101]
	v_mfma_f32_16x16x32_bf16 v[86:89], v[162:165], v[206:209], v[86:89]
	v_mfma_f32_16x16x32_bf16 v[82:85], v[170:173], v[206:209], v[82:85]
	v_mfma_f32_16x16x32_bf16 v[70:73], v[162:165], v[214:217], v[70:73]
	v_mfma_f32_16x16x32_bf16 v[66:69], v[170:173], v[214:217], v[66:69]
	v_mfma_f32_16x16x32_bf16 v[118:121], v[166:169], v[194:197], v[118:121]
	v_mfma_f32_16x16x32_bf16 v[114:117], v[174:177], v[194:197], v[114:117]
	v_mfma_f32_16x16x32_bf16 v[102:105], v[166:169], v[202:205], v[102:105]
	v_mfma_f32_16x16x32_bf16 v[98:101], v[174:177], v[202:205], v[98:101]
	v_mfma_f32_16x16x32_bf16 v[86:89], v[166:169], v[210:213], v[86:89]
	v_mfma_f32_16x16x32_bf16 v[82:85], v[174:177], v[210:213], v[82:85]
	v_mfma_f32_16x16x32_bf16 v[70:73], v[166:169], v[218:221], v[70:73]
	v_mfma_f32_16x16x32_bf16 v[66:69], v[174:177], v[218:221], v[66:69]
	s_barrier
	s_setprio 0
	s_add_i32 s42, s51, s60
	v_lshl_add_u64 v[178:179], v[178:179], 0, s[16:17]
	s_mov_b32 m0, s42
	ds_read_b128 v[190:193], v160 offset:49152
	ds_read_b128 v[194:197], v160 offset:50176
	ds_read_b128 v[198:201], v160 offset:51200
	ds_read_b128 v[202:205], v160 offset:52224
	ds_read_b128 v[206:209], v160 offset:53248
	ds_read_b128 v[210:213], v160 offset:54272
	ds_read_b128 v[214:217], v160 offset:55296
	ds_read_b128 v[218:221], v160 offset:56320
	global_load_lds_dwordx4 v[178:179], off sc0
	s_add_i32 m0, s42, 0x2000
	s_add_u32 s40, s40, 0x80080
	v_lshl_add_u64 v[178:179], v[222:223], 0, s[16:17]
	s_addc_u32 s41, s41, 0
	s_add_i32 s42, s83, s60
	global_load_lds_dwordx4 v[178:179], off sc0
	v_lshl_add_u64 v[178:179], s[40:41], 0, v[180:181]
	s_mov_b32 m0, s42
	s_nop 0
	global_load_lds_dwordx4 v[178:179], off sc0
	v_lshl_add_u64 v[178:179], s[40:41], 0, v[136:137]
	s_add_i32 m0, s42, 0x2000
	s_nop 0
	global_load_lds_dwordx4 v[178:179], off sc0
	v_lshl_add_u64 v[178:179], v[238:239], 0, s[16:17]
	s_mov_b32 m0, s74
	s_nop 0
	global_load_lds_dwordx4 v[178:179], off sc0
	v_lshl_add_u64 v[178:179], v[240:241], 0, s[16:17]
	s_mov_b32 m0, s75
	s_nop 0
	global_load_lds_dwordx4 v[178:179], off sc0
	s_waitcnt vmcnt(8)
	s_waitcnt lgkmcnt(0)
	s_setprio 1
	s_barrier
	v_mfma_f32_16x16x32_bf16 v[62:65], v[142:145], v[190:193], v[62:65]
	v_mfma_f32_16x16x32_bf16 v[58:61], v[150:153], v[190:193], v[58:61]
	v_mfma_f32_16x16x32_bf16 v[46:49], v[142:145], v[198:201], v[46:49]
	v_mfma_f32_16x16x32_bf16 v[42:45], v[150:153], v[198:201], v[42:45]
	v_mfma_f32_16x16x32_bf16 v[30:33], v[142:145], v[206:209], v[30:33]
	v_mfma_f32_16x16x32_bf16 v[26:29], v[150:153], v[206:209], v[26:29]
	v_mfma_f32_16x16x32_bf16 v[14:17], v[142:145], v[214:217], v[14:17]
	v_mfma_f32_16x16x32_bf16 v[10:13], v[150:153], v[214:217], v[10:13]
	v_mfma_f32_16x16x32_bf16 v[62:65], v[146:149], v[194:197], v[62:65]
	v_mfma_f32_16x16x32_bf16 v[58:61], v[154:157], v[194:197], v[58:61]
	v_mfma_f32_16x16x32_bf16 v[46:49], v[146:149], v[202:205], v[46:49]
	v_mfma_f32_16x16x32_bf16 v[42:45], v[154:157], v[202:205], v[42:45]
	v_mfma_f32_16x16x32_bf16 v[30:33], v[146:149], v[210:213], v[30:33]
	v_mfma_f32_16x16x32_bf16 v[26:29], v[154:157], v[210:213], v[26:29]
	v_mfma_f32_16x16x32_bf16 v[14:17], v[146:149], v[218:221], v[14:17]
	v_mfma_f32_16x16x32_bf16 v[10:13], v[154:157], v[218:221], v[10:13]
	v_mfma_f32_16x16x32_bf16 v[54:57], v[162:165], v[190:193], v[54:57]
	v_mfma_f32_16x16x32_bf16 v[50:53], v[170:173], v[190:193], v[50:53]
	v_mfma_f32_16x16x32_bf16 v[38:41], v[162:165], v[198:201], v[38:41]
	v_mfma_f32_16x16x32_bf16 v[34:37], v[170:173], v[198:201], v[34:37]
	v_mfma_f32_16x16x32_bf16 v[22:25], v[162:165], v[206:209], v[22:25]
	v_mfma_f32_16x16x32_bf16 v[18:21], v[170:173], v[206:209], v[18:21]
	v_mfma_f32_16x16x32_bf16 v[6:9], v[162:165], v[214:217], v[6:9]
	v_mfma_f32_16x16x32_bf16 v[2:5], v[170:173], v[214:217], v[2:5]
	v_mfma_f32_16x16x32_bf16 v[54:57], v[166:169], v[194:197], v[54:57]
	v_mfma_f32_16x16x32_bf16 v[50:53], v[174:177], v[194:197], v[50:53]
	v_mfma_f32_16x16x32_bf16 v[38:41], v[166:169], v[202:205], v[38:41]
	v_mfma_f32_16x16x32_bf16 v[34:37], v[174:177], v[202:205], v[34:37]
	v_mfma_f32_16x16x32_bf16 v[22:25], v[166:169], v[210:213], v[22:25]
	v_mfma_f32_16x16x32_bf16 v[18:21], v[174:177], v[210:213], v[18:21]
	v_mfma_f32_16x16x32_bf16 v[6:9], v[166:169], v[218:221], v[6:9]
	v_mfma_f32_16x16x32_bf16 v[2:5], v[174:177], v[218:221], v[2:5]
	s_barrier
	s_setprio 0
	s_add_i32 s49, s49, 2
	s_add_u32 s38, s38, 0x100
	s_addc_u32 s39, s39, 0
	s_add_u32 s46, s46, 0x100
	s_addc_u32 s47, s47, 0
	s_cmp_gt_u32 s49, 29
	s_cbranch_scc0 .LBB0_1018
	s_and_b64 vcc, exec, s[34:35]
	s_cbranch_vccz .LBB0_1021
	s_barrier

.LBB0_1230:
	s_add_u32 s38, s36, 0xfff80080
	s_addc_u32 s39, s37, -1
	s_add_i32 s64, 0, 0x10000
	s_cmp_eq_u32 s63, 28
	s_cselect_b32 s41, s57, s39
	s_cselect_b32 s40, s58, s38
	v_add_u32_e32 v155, s64, v153
	s_cselect_b32 s39, s59, s62
	s_cselect_b32 s38, s60, s61
	s_add_i32 s74, 0, 0x14000
	ds_read_b128 v[140:143], v155
	ds_read_b128 v[144:147], v155 offset:1024
	ds_read_b128 v[148:151], v155 offset:2048
	ds_read_b128 v[156:159], v155 offset:3072
	v_add_u32_e32 v155, s74, v153
	ds_read_b128 v[160:163], v155
	ds_read_b128 v[164:167], v155 offset:1024
	ds_read_b128 v[168:171], v155 offset:2048
	ds_read_b128 v[172:175], v155 offset:3072
	v_lshl_add_u64 v[218:219], s[36:37], 0, v[136:137]
	s_add_i32 m0, s11, 0xc000
	ds_read_b128 v[176:179], v154
	ds_read_b128 v[190:193], v154 offset:1024
	ds_read_b128 v[194:197], v154 offset:2048
	ds_read_b128 v[198:201], v154 offset:3072
	ds_read_b128 v[202:205], v154 offset:4096
	ds_read_b128 v[206:209], v154 offset:5120
	ds_read_b128 v[210:213], v154 offset:6144
	ds_read_b128 v[214:217], v154 offset:7168
	global_load_lds_dwordx4 v[218:219], off sc0
	v_lshl_add_u64 v[218:219], s[36:37], 0, v[138:139]
	s_add_i32 m0, s11, 0xe000
	s_nop 0
	global_load_lds_dwordx4 v[218:219], off sc0
	s_waitcnt vmcnt(8)
	s_waitcnt lgkmcnt(0)
	s_setprio 1
	s_barrier
	v_mfma_f32_16x16x32_bf16 v[126:129], v[140:143], v[176:179], v[126:129]
	v_mfma_f32_16x16x32_bf16 v[122:125], v[148:151], v[176:179], v[122:125]
	v_mfma_f32_16x16x32_bf16 v[110:113], v[140:143], v[194:197], v[110:113]
	v_mfma_f32_16x16x32_bf16 v[106:109], v[148:151], v[194:197], v[106:109]
	v_mfma_f32_16x16x32_bf16 v[94:97], v[140:143], v[202:205], v[94:97]
	v_mfma_f32_16x16x32_bf16 v[90:93], v[148:151], v[202:205], v[90:93]
	v_mfma_f32_16x16x32_bf16 v[78:81], v[140:143], v[210:213], v[78:81]
	v_mfma_f32_16x16x32_bf16 v[74:77], v[148:151], v[210:213], v[74:77]
	v_mfma_f32_16x16x32_bf16 v[126:129], v[144:147], v[190:193], v[126:129]
	v_mfma_f32_16x16x32_bf16 v[122:125], v[156:159], v[190:193], v[122:125]
	v_mfma_f32_16x16x32_bf16 v[110:113], v[144:147], v[198:201], v[110:113]
	v_mfma_f32_16x16x32_bf16 v[106:109], v[156:159], v[198:201], v[106:109]
	v_mfma_f32_16x16x32_bf16 v[94:97], v[144:147], v[206:209], v[94:97]
	v_mfma_f32_16x16x32_bf16 v[90:93], v[156:159], v[206:209], v[90:93]
	v_mfma_f32_16x16x32_bf16 v[78:81], v[144:147], v[214:217], v[78:81]
	v_mfma_f32_16x16x32_bf16 v[74:77], v[156:159], v[214:217], v[74:77]
	v_mfma_f32_16x16x32_bf16 v[118:121], v[160:163], v[176:179], v[118:121]
	v_mfma_f32_16x16x32_bf16 v[114:117], v[168:171], v[176:179], v[114:117]
	v_mfma_f32_16x16x32_bf16 v[102:105], v[160:163], v[194:197], v[102:105]
	v_mfma_f32_16x16x32_bf16 v[98:101], v[168:171], v[194:197], v[98:101]
	v_mfma_f32_16x16x32_bf16 v[86:89], v[160:163], v[202:205], v[86:89]
	v_mfma_f32_16x16x32_bf16 v[82:85], v[168:171], v[202:205], v[82:85]
	v_mfma_f32_16x16x32_bf16 v[70:73], v[160:163], v[210:213], v[70:73]
	v_mfma_f32_16x16x32_bf16 v[66:69], v[168:171], v[210:213], v[66:69]
	v_mfma_f32_16x16x32_bf16 v[118:121], v[164:167], v[190:193], v[118:121]
	v_mfma_f32_16x16x32_bf16 v[114:117], v[172:175], v[190:193], v[114:117]
	v_mfma_f32_16x16x32_bf16 v[102:105], v[164:167], v[198:201], v[102:105]
	v_mfma_f32_16x16x32_bf16 v[98:101], v[172:175], v[198:201], v[98:101]
	v_mfma_f32_16x16x32_bf16 v[86:89], v[164:167], v[206:209], v[86:89]
	v_mfma_f32_16x16x32_bf16 v[82:85], v[172:175], v[206:209], v[82:85]
	v_mfma_f32_16x16x32_bf16 v[70:73], v[164:167], v[214:217], v[70:73]
	v_mfma_f32_16x16x32_bf16 v[66:69], v[172:175], v[214:217], v[66:69]
	s_barrier
	s_setprio 0
	s_add_i32 s64, s64, s43
	v_lshl_add_u64 v[218:219], s[38:39], 0, v[134:135]
	s_mov_b32 m0, s64
	ds_read_b128 v[176:179], v154 offset:16384
	ds_read_b128 v[190:193], v154 offset:17408
	ds_read_b128 v[194:197], v154 offset:18432
	ds_read_b128 v[198:201], v154 offset:19456
	ds_read_b128 v[202:205], v154 offset:20480
	ds_read_b128 v[206:209], v154 offset:21504
	ds_read_b128 v[210:213], v154 offset:22528
	ds_read_b128 v[214:217], v154 offset:23552
	global_load_lds_dwordx4 v[218:219], off sc0
	s_add_i32 m0, s64, 0x2000
	s_add_u32 s70, s38, 0x80000
	v_lshl_add_u64 v[220:221], s[38:39], 0, v[132:133]
	s_addc_u32 s71, s39, 0
	s_add_i32 s64, s74, s43
	global_load_lds_dwordx4 v[220:221], off sc0
	v_lshl_add_u64 v[222:223], s[70:71], 0, v[134:135]
	s_mov_b32 m0, s64
	v_lshl_add_u64 v[238:239], s[40:41], 0, v[132:133]
	global_load_lds_dwordx4 v[222:223], off sc0
	v_lshl_add_u64 v[222:223], s[70:71], 0, v[132:133]
	s_add_i32 m0, s64, 0x2000
	s_nop 0
	global_load_lds_dwordx4 v[222:223], off sc0
	v_lshl_add_u64 v[222:223], s[40:41], 0, v[134:135]
	s_mov_b32 m0, s11
	s_nop 0
	global_load_lds_dwordx4 v[222:223], off sc0
	s_mov_b32 m0, s45
	s_nop 0
	global_load_lds_dwordx4 v[238:239], off sc0
	s_waitcnt vmcnt(8)
	s_waitcnt lgkmcnt(0)
	s_setprio 1
	s_barrier
	v_mfma_f32_16x16x32_bf16 v[62:65], v[140:143], v[176:179], v[62:65]
	v_mfma_f32_16x16x32_bf16 v[58:61], v[148:151], v[176:179], v[58:61]
	v_mfma_f32_16x16x32_bf16 v[46:49], v[140:143], v[194:197], v[46:49]
	v_mfma_f32_16x16x32_bf16 v[42:45], v[148:151], v[194:197], v[42:45]
	v_mfma_f32_16x16x32_bf16 v[30:33], v[140:143], v[202:205], v[30:33]
	v_mfma_f32_16x16x32_bf16 v[26:29], v[148:151], v[202:205], v[26:29]
	v_mfma_f32_16x16x32_bf16 v[14:17], v[140:143], v[210:213], v[14:17]
	v_mfma_f32_16x16x32_bf16 v[10:13], v[148:151], v[210:213], v[10:13]
	v_mfma_f32_16x16x32_bf16 v[62:65], v[144:147], v[190:193], v[62:65]
	v_mfma_f32_16x16x32_bf16 v[58:61], v[156:159], v[190:193], v[58:61]
	v_mfma_f32_16x16x32_bf16 v[46:49], v[144:147], v[198:201], v[46:49]
	v_mfma_f32_16x16x32_bf16 v[42:45], v[156:159], v[198:201], v[42:45]
	v_mfma_f32_16x16x32_bf16 v[30:33], v[144:147], v[206:209], v[30:33]
	v_mfma_f32_16x16x32_bf16 v[26:29], v[156:159], v[206:209], v[26:29]
	v_mfma_f32_16x16x32_bf16 v[14:17], v[144:147], v[214:217], v[14:17]
	v_mfma_f32_16x16x32_bf16 v[10:13], v[156:159], v[214:217], v[10:13]
	v_mfma_f32_16x16x32_bf16 v[54:57], v[160:163], v[176:179], v[54:57]
	v_mfma_f32_16x16x32_bf16 v[50:53], v[168:171], v[176:179], v[50:53]
	v_mfma_f32_16x16x32_bf16 v[38:41], v[160:163], v[194:197], v[38:41]
	v_mfma_f32_16x16x32_bf16 v[34:37], v[168:171], v[194:197], v[34:37]
	v_mfma_f32_16x16x32_bf16 v[22:25], v[160:163], v[202:205], v[22:25]
	v_mfma_f32_16x16x32_bf16 v[18:21], v[168:171], v[202:205], v[18:21]
	v_mfma_f32_16x16x32_bf16 v[6:9], v[160:163], v[210:213], v[6:9]
	v_mfma_f32_16x16x32_bf16 v[2:5], v[168:171], v[210:213], v[2:5]
	v_mfma_f32_16x16x32_bf16 v[54:57], v[164:167], v[190:193], v[54:57]
	v_mfma_f32_16x16x32_bf16 v[50:53], v[172:175], v[190:193], v[50:53]
	v_mfma_f32_16x16x32_bf16 v[38:41], v[164:167], v[198:201], v[38:41]
	v_mfma_f32_16x16x32_bf16 v[34:37], v[172:175], v[198:201], v[34:37]
	v_mfma_f32_16x16x32_bf16 v[22:25], v[164:167], v[206:209], v[22:25]
	v_mfma_f32_16x16x32_bf16 v[18:21], v[172:175], v[206:209], v[18:21]
	v_mfma_f32_16x16x32_bf16 v[6:9], v[164:167], v[214:217], v[6:9]
	v_mfma_f32_16x16x32_bf16 v[2:5], v[172:175], v[214:217], v[2:5]
	s_barrier
	s_setprio 0
	s_add_i32 s64, 0, 0x18000
	v_add_u32_e32 v155, s64, v153
	s_add_i32 s70, 0, 0x1c000
	ds_read_b128 v[140:143], v155
	ds_read_b128 v[144:147], v155 offset:1024
	ds_read_b128 v[148:151], v155 offset:2048
	ds_read_b128 v[156:159], v155 offset:3072
	v_add_u32_e32 v155, s70, v153
	ds_read_b128 v[160:163], v155
	ds_read_b128 v[164:167], v155 offset:1024
	ds_read_b128 v[168:171], v155 offset:2048
	ds_read_b128 v[172:175], v155 offset:3072
	s_add_u32 s40, s40, 0x80000
	s_addc_u32 s41, s41, 0
	s_mov_b32 m0, s46
	v_lshl_add_u64 v[240:241], s[40:41], 0, v[134:135]
	ds_read_b128 v[176:179], v154 offset:32768
	ds_read_b128 v[190:193], v154 offset:33792
	ds_read_b128 v[194:197], v154 offset:34816
	ds_read_b128 v[198:201], v154 offset:35840
	ds_read_b128 v[202:205], v154 offset:36864
	ds_read_b128 v[206:209], v154 offset:37888
	ds_read_b128 v[210:213], v154 offset:38912
	ds_read_b128 v[214:217], v154 offset:39936
	global_load_lds_dwordx4 v[240:241], off sc0
	v_lshl_add_u64 v[240:241], s[40:41], 0, v[132:133]
	s_mov_b32 m0, s47
	s_nop 0
	global_load_lds_dwordx4 v[240:241], off sc0
	s_waitcnt vmcnt(8)
	s_waitcnt lgkmcnt(0)
	s_setprio 1
	s_barrier
	v_mfma_f32_16x16x32_bf16 v[126:129], v[140:143], v[176:179], v[126:129]
	v_mfma_f32_16x16x32_bf16 v[122:125], v[148:151], v[176:179], v[122:125]
	v_mfma_f32_16x16x32_bf16 v[110:113], v[140:143], v[194:197], v[110:113]
	v_mfma_f32_16x16x32_bf16 v[106:109], v[148:151], v[194:197], v[106:109]
	v_mfma_f32_16x16x32_bf16 v[94:97], v[140:143], v[202:205], v[94:97]
	v_mfma_f32_16x16x32_bf16 v[90:93], v[148:151], v[202:205], v[90:93]
	v_mfma_f32_16x16x32_bf16 v[78:81], v[140:143], v[210:213], v[78:81]
	v_mfma_f32_16x16x32_bf16 v[74:77], v[148:151], v[210:213], v[74:77]
	v_mfma_f32_16x16x32_bf16 v[126:129], v[144:147], v[190:193], v[126:129]
	v_mfma_f32_16x16x32_bf16 v[122:125], v[156:159], v[190:193], v[122:125]
	v_mfma_f32_16x16x32_bf16 v[110:113], v[144:147], v[198:201], v[110:113]
	v_mfma_f32_16x16x32_bf16 v[106:109], v[156:159], v[198:201], v[106:109]
	v_mfma_f32_16x16x32_bf16 v[94:97], v[144:147], v[206:209], v[94:97]
	v_mfma_f32_16x16x32_bf16 v[90:93], v[156:159], v[206:209], v[90:93]
	v_mfma_f32_16x16x32_bf16 v[78:81], v[144:147], v[214:217], v[78:81]
	v_mfma_f32_16x16x32_bf16 v[74:77], v[156:159], v[214:217], v[74:77]
	v_mfma_f32_16x16x32_bf16 v[118:121], v[160:163], v[176:179], v[118:121]
	v_mfma_f32_16x16x32_bf16 v[114:117], v[168:171], v[176:179], v[114:117]
	v_mfma_f32_16x16x32_bf16 v[102:105], v[160:163], v[194:197], v[102:105]
	v_mfma_f32_16x16x32_bf16 v[98:101], v[168:171], v[194:197], v[98:101]
	v_mfma_f32_16x16x32_bf16 v[86:89], v[160:163], v[202:205], v[86:89]
	v_mfma_f32_16x16x32_bf16 v[82:85], v[168:171], v[202:205], v[82:85]
	v_mfma_f32_16x16x32_bf16 v[70:73], v[160:163], v[210:213], v[70:73]
	v_mfma_f32_16x16x32_bf16 v[66:69], v[168:171], v[210:213], v[66:69]
	v_mfma_f32_16x16x32_bf16 v[118:121], v[164:167], v[190:193], v[118:121]
	v_mfma_f32_16x16x32_bf16 v[114:117], v[172:175], v[190:193], v[114:117]
	v_mfma_f32_16x16x32_bf16 v[102:105], v[164:167], v[198:201], v[102:105]
	v_mfma_f32_16x16x32_bf16 v[98:101], v[172:175], v[198:201], v[98:101]
	v_mfma_f32_16x16x32_bf16 v[86:89], v[164:167], v[206:209], v[86:89]
	v_mfma_f32_16x16x32_bf16 v[82:85], v[172:175], v[206:209], v[82:85]
	v_mfma_f32_16x16x32_bf16 v[70:73], v[164:167], v[214:217], v[70:73]
	v_mfma_f32_16x16x32_bf16 v[66:69], v[172:175], v[214:217], v[66:69]
	s_barrier
	s_setprio 0
	s_add_i32 s40, s64, s43
	v_lshl_add_u64 v[218:219], v[218:219], 0, s[16:17]
	s_mov_b32 m0, s40
	ds_read_b128 v[176:179], v154 offset:49152
	ds_read_b128 v[190:193], v154 offset:50176
	ds_read_b128 v[194:197], v154 offset:51200
	ds_read_b128 v[198:201], v154 offset:52224
	ds_read_b128 v[202:205], v154 offset:53248
	ds_read_b128 v[206:209], v154 offset:54272
	ds_read_b128 v[210:213], v154 offset:55296
	ds_read_b128 v[214:217], v154 offset:56320
	global_load_lds_dwordx4 v[218:219], off sc0
	s_add_i32 m0, s40, 0x2000
	s_add_u32 s38, s38, 0x80080
	v_lshl_add_u64 v[218:219], v[220:221], 0, s[16:17]
	s_addc_u32 s39, s39, 0
	s_add_i32 s40, s70, s43
	global_load_lds_dwordx4 v[218:219], off sc0
	v_lshl_add_u64 v[218:219], s[38:39], 0, v[134:135]
	s_mov_b32 m0, s40
	s_nop 0
	global_load_lds_dwordx4 v[218:219], off sc0
	v_lshl_add_u64 v[218:219], s[38:39], 0, v[132:133]
	s_add_i32 m0, s40, 0x2000
	s_nop 0
	global_load_lds_dwordx4 v[218:219], off sc0
	v_lshl_add_u64 v[218:219], v[222:223], 0, s[16:17]
	s_mov_b32 m0, s50
	s_nop 0
	global_load_lds_dwordx4 v[218:219], off sc0
	v_lshl_add_u64 v[218:219], v[238:239], 0, s[16:17]
	s_mov_b32 m0, s51
	s_nop 0
	global_load_lds_dwordx4 v[218:219], off sc0
	s_waitcnt vmcnt(8)
	s_waitcnt lgkmcnt(0)
	s_setprio 1
	s_barrier
	v_mfma_f32_16x16x32_bf16 v[62:65], v[140:143], v[176:179], v[62:65]
	v_mfma_f32_16x16x32_bf16 v[58:61], v[148:151], v[176:179], v[58:61]
	v_mfma_f32_16x16x32_bf16 v[46:49], v[140:143], v[194:197], v[46:49]
	v_mfma_f32_16x16x32_bf16 v[42:45], v[148:151], v[194:197], v[42:45]
	v_mfma_f32_16x16x32_bf16 v[30:33], v[140:143], v[202:205], v[30:33]
	v_mfma_f32_16x16x32_bf16 v[26:29], v[148:151], v[202:205], v[26:29]
	v_mfma_f32_16x16x32_bf16 v[14:17], v[140:143], v[210:213], v[14:17]
	v_mfma_f32_16x16x32_bf16 v[10:13], v[148:151], v[210:213], v[10:13]
	v_mfma_f32_16x16x32_bf16 v[62:65], v[144:147], v[190:193], v[62:65]
	v_mfma_f32_16x16x32_bf16 v[58:61], v[156:159], v[190:193], v[58:61]
	v_mfma_f32_16x16x32_bf16 v[46:49], v[144:147], v[198:201], v[46:49]
	v_mfma_f32_16x16x32_bf16 v[42:45], v[156:159], v[198:201], v[42:45]
	v_mfma_f32_16x16x32_bf16 v[30:33], v[144:147], v[206:209], v[30:33]
	v_mfma_f32_16x16x32_bf16 v[26:29], v[156:159], v[206:209], v[26:29]
	v_mfma_f32_16x16x32_bf16 v[14:17], v[144:147], v[214:217], v[14:17]
	v_mfma_f32_16x16x32_bf16 v[10:13], v[156:159], v[214:217], v[10:13]
	v_mfma_f32_16x16x32_bf16 v[54:57], v[160:163], v[176:179], v[54:57]
	v_mfma_f32_16x16x32_bf16 v[50:53], v[168:171], v[176:179], v[50:53]
	v_mfma_f32_16x16x32_bf16 v[38:41], v[160:163], v[194:197], v[38:41]
	v_mfma_f32_16x16x32_bf16 v[34:37], v[168:171], v[194:197], v[34:37]
	v_mfma_f32_16x16x32_bf16 v[22:25], v[160:163], v[202:205], v[22:25]
	v_mfma_f32_16x16x32_bf16 v[18:21], v[168:171], v[202:205], v[18:21]
	v_mfma_f32_16x16x32_bf16 v[6:9], v[160:163], v[210:213], v[6:9]
	v_mfma_f32_16x16x32_bf16 v[2:5], v[168:171], v[210:213], v[2:5]
	v_mfma_f32_16x16x32_bf16 v[54:57], v[164:167], v[190:193], v[54:57]
	v_mfma_f32_16x16x32_bf16 v[50:53], v[172:175], v[190:193], v[50:53]
	v_mfma_f32_16x16x32_bf16 v[38:41], v[164:167], v[198:201], v[38:41]
	v_mfma_f32_16x16x32_bf16 v[34:37], v[172:175], v[198:201], v[34:37]
	v_mfma_f32_16x16x32_bf16 v[22:25], v[164:167], v[206:209], v[22:25]
	v_mfma_f32_16x16x32_bf16 v[18:21], v[172:175], v[206:209], v[18:21]
	v_mfma_f32_16x16x32_bf16 v[6:9], v[164:167], v[214:217], v[6:9]
	v_mfma_f32_16x16x32_bf16 v[2:5], v[172:175], v[214:217], v[2:5]
	s_barrier
	s_setprio 0
	s_add_i32 s63, s63, 2
	s_add_u32 s36, s36, 0x100
	s_addc_u32 s37, s37, 0
	s_add_u32 s61, s61, 0x100
	s_addc_u32 s62, s62, 0
	s_cmp_gt_u32 s63, 29
	s_cbranch_scc0 .LBB0_1230
	s_and_b64 vcc, exec, s[30:31]
	s_cbranch_vccz .LBB0_1233
	s_barrier

.LBB0_1583:
	s_add_u32 s46, s48, 0xfff80080
	s_addc_u32 s47, s49, -1
	s_add_i32 s68, 0, 0x10000
	s_cmp_eq_u32 s67, 28
	s_cselect_b32 s51, s35, s47
	s_cselect_b32 s50, s39, s46
	s_cselect_b32 s47, s31, s66
	s_cselect_b32 s46, s45, s64
	s_add_i32 s70, 0, 0x14000
	v_add_u32_e32 v162, s68, v152
	v_add_u32_e32 v178, s70, v152
	ds_read_b128 v[144:147], v162
	ds_read_b128 v[154:157], v162 offset:1024
	ds_read_b128 v[158:161], v162 offset:2048
	ds_read_b128 v[162:165], v162 offset:3072
	ds_read_b128 v[166:169], v178
	ds_read_b128 v[170:173], v178 offset:1024
	ds_read_b128 v[174:177], v178 offset:2048
	ds_read_b128 v[190:193], v178 offset:3072
	v_lshl_add_u64 v[178:179], s[48:49], 0, v[140:141]
	s_add_i32 m0, s56, 0xc000
	ds_read_b128 v[194:197], v153
	ds_read_b128 v[198:201], v153 offset:1024
	ds_read_b128 v[202:205], v153 offset:2048
	ds_read_b128 v[206:209], v153 offset:3072
	ds_read_b128 v[210:213], v153 offset:4096
	ds_read_b128 v[214:217], v153 offset:5120
	ds_read_b128 v[218:221], v153 offset:6144
	ds_read_b128 v[238:241], v153 offset:7168
	global_load_lds_dwordx4 v[178:179], off sc0
	v_lshl_add_u64 v[178:179], s[48:49], 0, v[142:143]
	s_add_i32 m0, s56, 0xe000
	s_nop 0
	global_load_lds_dwordx4 v[178:179], off sc0
	s_waitcnt vmcnt(8)
	s_waitcnt lgkmcnt(0)
	s_setprio 1
	s_barrier
	v_mfma_f32_16x16x32_bf16 v[126:129], v[144:147], v[194:197], v[126:129]
	v_mfma_f32_16x16x32_bf16 v[114:117], v[158:161], v[194:197], v[114:117]
	v_mfma_f32_16x16x32_bf16 v[106:109], v[144:147], v[202:205], v[106:109]
	v_mfma_f32_16x16x32_bf16 v[98:101], v[158:161], v[202:205], v[98:101]
	v_mfma_f32_16x16x32_bf16 v[90:93], v[144:147], v[210:213], v[90:93]
	v_mfma_f32_16x16x32_bf16 v[82:85], v[158:161], v[210:213], v[82:85]
	v_mfma_f32_16x16x32_bf16 v[74:77], v[144:147], v[218:221], v[74:77]
	v_mfma_f32_16x16x32_bf16 v[54:57], v[158:161], v[218:221], v[54:57]
	v_mfma_f32_16x16x32_bf16 v[126:129], v[154:157], v[198:201], v[126:129]
	v_mfma_f32_16x16x32_bf16 v[114:117], v[162:165], v[198:201], v[114:117]
	v_mfma_f32_16x16x32_bf16 v[106:109], v[154:157], v[206:209], v[106:109]
	v_mfma_f32_16x16x32_bf16 v[98:101], v[162:165], v[206:209], v[98:101]
	v_mfma_f32_16x16x32_bf16 v[90:93], v[154:157], v[214:217], v[90:93]
	v_mfma_f32_16x16x32_bf16 v[82:85], v[162:165], v[214:217], v[82:85]
	v_mfma_f32_16x16x32_bf16 v[74:77], v[154:157], v[238:241], v[74:77]
	v_mfma_f32_16x16x32_bf16 v[54:57], v[162:165], v[238:241], v[54:57]
	v_mfma_f32_16x16x32_bf16 v[118:121], v[166:169], v[194:197], v[118:121]
	v_mfma_f32_16x16x32_bf16 v[122:125], v[174:177], v[194:197], v[122:125]
	v_mfma_f32_16x16x32_bf16 v[102:105], v[166:169], v[202:205], v[102:105]
	v_mfma_f32_16x16x32_bf16 v[110:113], v[174:177], v[202:205], v[110:113]
	v_mfma_f32_16x16x32_bf16 v[86:89], v[166:169], v[210:213], v[86:89]
	v_mfma_f32_16x16x32_bf16 v[94:97], v[174:177], v[210:213], v[94:97]
	v_mfma_f32_16x16x32_bf16 v[70:73], v[166:169], v[218:221], v[70:73]
	v_mfma_f32_16x16x32_bf16 v[78:81], v[174:177], v[218:221], v[78:81]
	v_mfma_f32_16x16x32_bf16 v[118:121], v[170:173], v[198:201], v[118:121]
	v_mfma_f32_16x16x32_bf16 v[122:125], v[190:193], v[198:201], v[122:125]
	v_mfma_f32_16x16x32_bf16 v[102:105], v[170:173], v[206:209], v[102:105]
	v_mfma_f32_16x16x32_bf16 v[110:113], v[190:193], v[206:209], v[110:113]
	v_mfma_f32_16x16x32_bf16 v[86:89], v[170:173], v[214:217], v[86:89]
	v_mfma_f32_16x16x32_bf16 v[94:97], v[190:193], v[214:217], v[94:97]
	v_mfma_f32_16x16x32_bf16 v[70:73], v[170:173], v[238:241], v[70:73]
	v_mfma_f32_16x16x32_bf16 v[78:81], v[190:193], v[238:241], v[78:81]
	s_barrier
	s_setprio 0
	s_add_i32 s68, s68, s8
	v_lshl_add_u64 v[178:179], s[46:47], 0, v[134:135]
	s_mov_b32 m0, s68
	ds_read_b128 v[194:197], v153 offset:16384
	ds_read_b128 v[198:201], v153 offset:17408
	ds_read_b128 v[202:205], v153 offset:18432
	ds_read_b128 v[206:209], v153 offset:19456
	ds_read_b128 v[210:213], v153 offset:20480
	ds_read_b128 v[214:217], v153 offset:21504
	ds_read_b128 v[218:221], v153 offset:22528
	ds_read_b128 v[238:241], v153 offset:23552
	global_load_lds_dwordx4 v[178:179], off sc0
	s_add_i32 m0, s68, 0x2000
	s_add_u32 s68, s46, 0x80000
	v_lshl_add_u64 v[222:223], s[46:47], 0, v[138:139]
	s_addc_u32 s69, s47, 0
	s_add_i32 s70, s70, s8
	global_load_lds_dwordx4 v[222:223], off sc0
	v_lshl_add_u64 v[242:243], s[68:69], 0, v[134:135]
	s_mov_b32 m0, s70
	v_lshl_add_u64 v[244:245], s[50:51], 0, v[136:137]
	global_load_lds_dwordx4 v[242:243], off sc0
	v_lshl_add_u64 v[242:243], s[68:69], 0, v[138:139]
	s_add_i32 m0, s70, 0x2000
	s_nop 0
	global_load_lds_dwordx4 v[242:243], off sc0
	v_lshl_add_u64 v[242:243], s[50:51], 0, v[132:133]
	s_mov_b32 m0, s56
	s_nop 0
	global_load_lds_dwordx4 v[242:243], off sc0
	s_mov_b32 m0, s57
	s_nop 0
	global_load_lds_dwordx4 v[244:245], off sc0
	s_waitcnt vmcnt(8)
	s_waitcnt lgkmcnt(0)
	s_setprio 1
	s_barrier
	v_mfma_f32_16x16x32_bf16 v[50:53], v[144:147], v[194:197], v[50:53]
	v_mfma_f32_16x16x32_bf16 v[38:41], v[158:161], v[194:197], v[38:41]
	v_mfma_f32_16x16x32_bf16 v[22:25], v[144:147], v[202:205], v[22:25]
	v_mfma_f32_16x16x32_bf16 v[42:45], v[158:161], v[202:205], v[42:45]
	v_mfma_f32_16x16x32_bf16 v[30:33], v[144:147], v[210:213], v[30:33]
	v_mfma_f32_16x16x32_bf16 v[18:21], v[158:161], v[210:213], v[18:21]
	v_mfma_f32_16x16x32_bf16 v[10:13], v[144:147], v[218:221], v[10:13]
	v_mfma_f32_16x16x32_bf16 v[2:5], v[158:161], v[218:221], v[2:5]
	v_mfma_f32_16x16x32_bf16 v[50:53], v[154:157], v[198:201], v[50:53]
	v_mfma_f32_16x16x32_bf16 v[38:41], v[162:165], v[198:201], v[38:41]
	v_mfma_f32_16x16x32_bf16 v[22:25], v[154:157], v[206:209], v[22:25]
	v_mfma_f32_16x16x32_bf16 v[42:45], v[162:165], v[206:209], v[42:45]
	v_mfma_f32_16x16x32_bf16 v[30:33], v[154:157], v[214:217], v[30:33]
	v_mfma_f32_16x16x32_bf16 v[18:21], v[162:165], v[214:217], v[18:21]
	v_mfma_f32_16x16x32_bf16 v[10:13], v[154:157], v[238:241], v[10:13]
	v_mfma_f32_16x16x32_bf16 v[2:5], v[162:165], v[238:241], v[2:5]
	v_mfma_f32_16x16x32_bf16 v[46:49], v[166:169], v[194:197], v[46:49]
	v_mfma_f32_16x16x32_bf16 v[58:61], v[174:177], v[194:197], v[58:61]
	v_mfma_f32_16x16x32_bf16 v[62:65], v[166:169], v[202:205], v[62:65]
	v_mfma_f32_16x16x32_bf16 v[66:69], v[174:177], v[202:205], v[66:69]
	v_mfma_f32_16x16x32_bf16 v[26:29], v[166:169], v[210:213], v[26:29]
	v_mfma_f32_16x16x32_bf16 v[34:37], v[174:177], v[210:213], v[34:37]
	v_mfma_f32_16x16x32_bf16 v[6:9], v[166:169], v[218:221], v[6:9]
	v_mfma_f32_16x16x32_bf16 v[14:17], v[174:177], v[218:221], v[14:17]
	v_mfma_f32_16x16x32_bf16 v[46:49], v[170:173], v[198:201], v[46:49]
	v_mfma_f32_16x16x32_bf16 v[58:61], v[190:193], v[198:201], v[58:61]
	v_mfma_f32_16x16x32_bf16 v[62:65], v[170:173], v[206:209], v[62:65]
	v_mfma_f32_16x16x32_bf16 v[66:69], v[190:193], v[206:209], v[66:69]
	v_mfma_f32_16x16x32_bf16 v[26:29], v[170:173], v[214:217], v[26:29]
	v_mfma_f32_16x16x32_bf16 v[34:37], v[190:193], v[214:217], v[34:37]
	v_mfma_f32_16x16x32_bf16 v[6:9], v[170:173], v[238:241], v[6:9]
	v_mfma_f32_16x16x32_bf16 v[14:17], v[190:193], v[238:241], v[14:17]
	s_barrier
	s_setprio 0
	s_add_i32 s68, 0, 0x18000
	s_add_i32 s69, 0, 0x1c000
	v_add_u32_e32 v162, s68, v152
	v_add_u32_e32 v190, s69, v152
	ds_read_b128 v[144:147], v162
	ds_read_b128 v[154:157], v162 offset:1024
	ds_read_b128 v[158:161], v162 offset:2048
	ds_read_b128 v[162:165], v162 offset:3072
	ds_read_b128 v[166:169], v190
	ds_read_b128 v[170:173], v190 offset:1024
	ds_read_b128 v[174:177], v190 offset:2048
	ds_read_b128 v[190:193], v190 offset:3072
	s_add_u32 s50, s50, 0x80000
	s_addc_u32 s51, s51, 0
	s_mov_b32 m0, s58
	v_lshl_add_u64 v[246:247], s[50:51], 0, v[132:133]
	ds_read_b128 v[194:197], v153 offset:32768
	ds_read_b128 v[198:201], v153 offset:33792
	ds_read_b128 v[202:205], v153 offset:34816
	ds_read_b128 v[206:209], v153 offset:35840
	ds_read_b128 v[210:213], v153 offset:36864
	ds_read_b128 v[214:217], v153 offset:37888
	ds_read_b128 v[218:221], v153 offset:38912
	ds_read_b128 v[238:241], v153 offset:39936
	global_load_lds_dwordx4 v[246:247], off sc0
	v_lshl_add_u64 v[246:247], s[50:51], 0, v[136:137]
	s_mov_b32 m0, s59
	s_nop 0
	global_load_lds_dwordx4 v[246:247], off sc0
	s_waitcnt vmcnt(8)
	s_waitcnt lgkmcnt(0)
	s_setprio 1
	s_barrier
	v_mfma_f32_16x16x32_bf16 v[126:129], v[144:147], v[194:197], v[126:129]
	v_mfma_f32_16x16x32_bf16 v[114:117], v[158:161], v[194:197], v[114:117]
	v_mfma_f32_16x16x32_bf16 v[106:109], v[144:147], v[202:205], v[106:109]
	v_mfma_f32_16x16x32_bf16 v[98:101], v[158:161], v[202:205], v[98:101]
	v_mfma_f32_16x16x32_bf16 v[90:93], v[144:147], v[210:213], v[90:93]
	v_mfma_f32_16x16x32_bf16 v[82:85], v[158:161], v[210:213], v[82:85]
	v_mfma_f32_16x16x32_bf16 v[74:77], v[144:147], v[218:221], v[74:77]
	v_mfma_f32_16x16x32_bf16 v[54:57], v[158:161], v[218:221], v[54:57]
	v_mfma_f32_16x16x32_bf16 v[126:129], v[154:157], v[198:201], v[126:129]
	v_mfma_f32_16x16x32_bf16 v[114:117], v[162:165], v[198:201], v[114:117]
	v_mfma_f32_16x16x32_bf16 v[106:109], v[154:157], v[206:209], v[106:109]
	v_mfma_f32_16x16x32_bf16 v[98:101], v[162:165], v[206:209], v[98:101]
	v_mfma_f32_16x16x32_bf16 v[90:93], v[154:157], v[214:217], v[90:93]
	v_mfma_f32_16x16x32_bf16 v[82:85], v[162:165], v[214:217], v[82:85]
	v_mfma_f32_16x16x32_bf16 v[74:77], v[154:157], v[238:241], v[74:77]
	v_mfma_f32_16x16x32_bf16 v[54:57], v[162:165], v[238:241], v[54:57]
	v_mfma_f32_16x16x32_bf16 v[118:121], v[166:169], v[194:197], v[118:121]
	v_mfma_f32_16x16x32_bf16 v[122:125], v[174:177], v[194:197], v[122:125]
	v_mfma_f32_16x16x32_bf16 v[102:105], v[166:169], v[202:205], v[102:105]
	v_mfma_f32_16x16x32_bf16 v[110:113], v[174:177], v[202:205], v[110:113]
	v_mfma_f32_16x16x32_bf16 v[86:89], v[166:169], v[210:213], v[86:89]
	v_mfma_f32_16x16x32_bf16 v[94:97], v[174:177], v[210:213], v[94:97]
	v_mfma_f32_16x16x32_bf16 v[70:73], v[166:169], v[218:221], v[70:73]
	v_mfma_f32_16x16x32_bf16 v[78:81], v[174:177], v[218:221], v[78:81]
	v_mfma_f32_16x16x32_bf16 v[118:121], v[170:173], v[198:201], v[118:121]
	v_mfma_f32_16x16x32_bf16 v[122:125], v[190:193], v[198:201], v[122:125]
	v_mfma_f32_16x16x32_bf16 v[102:105], v[170:173], v[206:209], v[102:105]
	v_mfma_f32_16x16x32_bf16 v[110:113], v[190:193], v[206:209], v[110:113]
	v_mfma_f32_16x16x32_bf16 v[86:89], v[170:173], v[214:217], v[86:89]
	v_mfma_f32_16x16x32_bf16 v[94:97], v[190:193], v[214:217], v[94:97]
	v_mfma_f32_16x16x32_bf16 v[70:73], v[170:173], v[238:241], v[70:73]
	v_mfma_f32_16x16x32_bf16 v[78:81], v[190:193], v[238:241], v[78:81]
	s_barrier
	s_setprio 0
	s_add_i32 s50, s68, s8
	v_lshl_add_u64 v[178:179], v[178:179], 0, s[16:17]
	s_mov_b32 m0, s50
	ds_read_b128 v[194:197], v153 offset:49152
	ds_read_b128 v[198:201], v153 offset:50176
	ds_read_b128 v[202:205], v153 offset:51200
	ds_read_b128 v[206:209], v153 offset:52224
	ds_read_b128 v[210:213], v153 offset:53248
	ds_read_b128 v[214:217], v153 offset:54272
	ds_read_b128 v[218:221], v153 offset:55296
	ds_read_b128 v[238:241], v153 offset:56320
	global_load_lds_dwordx4 v[178:179], off sc0
	s_add_i32 m0, s50, 0x2000
	s_add_u32 s46, s46, 0x80080
	v_lshl_add_u64 v[178:179], v[222:223], 0, s[16:17]
	s_addc_u32 s47, s47, 0
	s_add_i32 s50, s69, s8
	global_load_lds_dwordx4 v[178:179], off sc0
	v_lshl_add_u64 v[178:179], s[46:47], 0, v[134:135]
	s_mov_b32 m0, s50
	s_nop 0
	global_load_lds_dwordx4 v[178:179], off sc0
	v_lshl_add_u64 v[178:179], s[46:47], 0, v[138:139]
	s_add_i32 m0, s50, 0x2000
	s_nop 0
	global_load_lds_dwordx4 v[178:179], off sc0
	v_lshl_add_u64 v[178:179], v[242:243], 0, s[16:17]
	s_mov_b32 m0, s60
	s_nop 0
	global_load_lds_dwordx4 v[178:179], off sc0
	v_lshl_add_u64 v[178:179], v[244:245], 0, s[16:17]
	s_mov_b32 m0, s61
	s_nop 0
	global_load_lds_dwordx4 v[178:179], off sc0
	s_waitcnt vmcnt(8)
	s_waitcnt lgkmcnt(0)
	s_setprio 1
	s_barrier
	v_mfma_f32_16x16x32_bf16 v[50:53], v[144:147], v[194:197], v[50:53]
	v_mfma_f32_16x16x32_bf16 v[38:41], v[158:161], v[194:197], v[38:41]
	v_mfma_f32_16x16x32_bf16 v[22:25], v[144:147], v[202:205], v[22:25]
	v_mfma_f32_16x16x32_bf16 v[42:45], v[158:161], v[202:205], v[42:45]
	v_mfma_f32_16x16x32_bf16 v[30:33], v[144:147], v[210:213], v[30:33]
	v_mfma_f32_16x16x32_bf16 v[18:21], v[158:161], v[210:213], v[18:21]
	v_mfma_f32_16x16x32_bf16 v[10:13], v[144:147], v[218:221], v[10:13]
	v_mfma_f32_16x16x32_bf16 v[2:5], v[158:161], v[218:221], v[2:5]
	v_mfma_f32_16x16x32_bf16 v[50:53], v[154:157], v[198:201], v[50:53]
	v_mfma_f32_16x16x32_bf16 v[38:41], v[162:165], v[198:201], v[38:41]
	v_mfma_f32_16x16x32_bf16 v[22:25], v[154:157], v[206:209], v[22:25]
	v_mfma_f32_16x16x32_bf16 v[42:45], v[162:165], v[206:209], v[42:45]
	v_mfma_f32_16x16x32_bf16 v[30:33], v[154:157], v[214:217], v[30:33]
	v_mfma_f32_16x16x32_bf16 v[18:21], v[162:165], v[214:217], v[18:21]
	v_mfma_f32_16x16x32_bf16 v[10:13], v[154:157], v[238:241], v[10:13]
	v_mfma_f32_16x16x32_bf16 v[2:5], v[162:165], v[238:241], v[2:5]
	v_mfma_f32_16x16x32_bf16 v[46:49], v[166:169], v[194:197], v[46:49]
	v_mfma_f32_16x16x32_bf16 v[58:61], v[174:177], v[194:197], v[58:61]
	v_mfma_f32_16x16x32_bf16 v[62:65], v[166:169], v[202:205], v[62:65]
	v_mfma_f32_16x16x32_bf16 v[66:69], v[174:177], v[202:205], v[66:69]
	v_mfma_f32_16x16x32_bf16 v[26:29], v[166:169], v[210:213], v[26:29]
	v_mfma_f32_16x16x32_bf16 v[34:37], v[174:177], v[210:213], v[34:37]
	v_mfma_f32_16x16x32_bf16 v[6:9], v[166:169], v[218:221], v[6:9]
	v_mfma_f32_16x16x32_bf16 v[14:17], v[174:177], v[218:221], v[14:17]
	v_mfma_f32_16x16x32_bf16 v[46:49], v[170:173], v[198:201], v[46:49]
	v_mfma_f32_16x16x32_bf16 v[58:61], v[190:193], v[198:201], v[58:61]
	v_mfma_f32_16x16x32_bf16 v[62:65], v[170:173], v[206:209], v[62:65]
	v_mfma_f32_16x16x32_bf16 v[66:69], v[190:193], v[206:209], v[66:69]
	v_mfma_f32_16x16x32_bf16 v[26:29], v[170:173], v[214:217], v[26:29]
	v_mfma_f32_16x16x32_bf16 v[34:37], v[190:193], v[214:217], v[34:37]
	v_mfma_f32_16x16x32_bf16 v[6:9], v[170:173], v[238:241], v[6:9]
	v_mfma_f32_16x16x32_bf16 v[14:17], v[190:193], v[238:241], v[14:17]
	s_barrier
	s_setprio 0
	s_add_i32 s67, s67, 2
	s_add_u32 s48, s48, 0x100
	s_addc_u32 s49, s49, 0
	s_add_u32 s64, s64, 0x100
	s_addc_u32 s66, s66, 0
	s_cmp_gt_u32 s67, 29
	s_cbranch_scc0 .LBB0_1583
	s_and_b64 vcc, exec, s[28:29]
	s_cbranch_vccz .LBB0_1586
	s_barrier

.LBB0_1685:
	s_add_u32 s42, s40, 0xfff80080
	s_addc_u32 s43, s41, -1
	s_and_b64 s[26:27], s[26:27], exec
	s_cselect_b32 s43, s19, s43
	s_cselect_b32 s42, s45, s42
	s_cselect_b32 s27, s50, s39
	s_cselect_b32 s26, s51, s37
	s_add_i32 s47, 0, 0x10000
	s_add_i32 s69, 0, 0x14000
	v_add_u32_e32 v146, s47, v239
	v_add_u32_e32 v162, s69, v239
	ds_read_b128 v[114:117], v146
	ds_read_b128 v[118:121], v146 offset:1024
	ds_read_b128 v[122:125], v146 offset:2048
	ds_read_b128 v[146:149], v146 offset:3072
	ds_read_b128 v[150:153], v162
	ds_read_b128 v[154:157], v162 offset:1024
	ds_read_b128 v[158:161], v162 offset:2048
	ds_read_b128 v[162:165], v162 offset:3072
	v_lshl_add_u64 v[178:179], s[40:41], 0, v[202:203]
	s_add_i32 m0, s6, 0xc000
	ds_read_b128 v[166:169], v240
	ds_read_b128 v[170:173], v240 offset:1024
	ds_read_b128 v[174:177], v240 offset:2048
	ds_read_b128 v[206:209], v240 offset:3072
	ds_read_b128 v[210:213], v240 offset:4096
	ds_read_b128 v[214:217], v240 offset:5120
	ds_read_b128 v[218:221], v240 offset:6144
	ds_read_b128 v[242:245], v240 offset:7168
	global_load_lds_dwordx4 v[178:179], off sc0
	v_lshl_add_u64 v[178:179], s[40:41], 0, v[204:205]
	s_add_i32 m0, s6, 0xe000
	s_nop 0
	global_load_lds_dwordx4 v[178:179], off sc0
	s_waitcnt vmcnt(8)
	s_waitcnt lgkmcnt(0)
	s_setprio 1
	s_barrier
	v_mfma_f32_16x16x32_bf16 v[142:145], v[114:117], v[166:169], v[142:145]
	v_mfma_f32_16x16x32_bf16 v[62:65], v[122:125], v[166:169], v[62:65]
	v_mfma_f32_16x16x32_bf16 v[134:137], v[114:117], v[174:177], v[134:137]
	v_mfma_f32_16x16x32_bf16 v[54:57], v[122:125], v[174:177], v[54:57]
	v_mfma_f32_16x16x32_bf16 v[126:129], v[114:117], v[210:213], v[126:129]
	v_mfma_f32_16x16x32_bf16 v[46:49], v[122:125], v[210:213], v[46:49]
	v_mfma_f32_16x16x32_bf16 v[102:105], v[114:117], v[218:221], v[102:105]
	v_mfma_f32_16x16x32_bf16 v[38:41], v[122:125], v[218:221], v[38:41]
	v_mfma_f32_16x16x32_bf16 v[142:145], v[118:121], v[170:173], v[142:145]
	v_mfma_f32_16x16x32_bf16 v[62:65], v[146:149], v[170:173], v[62:65]
	v_mfma_f32_16x16x32_bf16 v[134:137], v[118:121], v[206:209], v[134:137]
	v_mfma_f32_16x16x32_bf16 v[54:57], v[146:149], v[206:209], v[54:57]
	v_mfma_f32_16x16x32_bf16 v[126:129], v[118:121], v[214:217], v[126:129]
	v_mfma_f32_16x16x32_bf16 v[46:49], v[146:149], v[214:217], v[46:49]
	v_mfma_f32_16x16x32_bf16 v[102:105], v[118:121], v[242:245], v[102:105]
	v_mfma_f32_16x16x32_bf16 v[38:41], v[146:149], v[242:245], v[38:41]
	v_mfma_f32_16x16x32_bf16 v[138:141], v[150:153], v[166:169], v[138:141]
	v_mfma_f32_16x16x32_bf16 v[58:61], v[158:161], v[166:169], v[58:61]
	v_mfma_f32_16x16x32_bf16 v[130:133], v[150:153], v[174:177], v[130:133]
	v_mfma_f32_16x16x32_bf16 v[50:53], v[158:161], v[174:177], v[50:53]
	v_mfma_f32_16x16x32_bf16 v[106:109], v[150:153], v[210:213], v[106:109]
	v_mfma_f32_16x16x32_bf16 v[42:45], v[158:161], v[210:213], v[42:45]
	v_mfma_f32_16x16x32_bf16 v[98:101], v[150:153], v[218:221], v[98:101]
	v_mfma_f32_16x16x32_bf16 v[34:37], v[158:161], v[218:221], v[34:37]
	v_mfma_f32_16x16x32_bf16 v[138:141], v[154:157], v[170:173], v[138:141]
	v_mfma_f32_16x16x32_bf16 v[58:61], v[162:165], v[170:173], v[58:61]
	v_mfma_f32_16x16x32_bf16 v[130:133], v[154:157], v[206:209], v[130:133]
	v_mfma_f32_16x16x32_bf16 v[50:53], v[162:165], v[206:209], v[50:53]
	v_mfma_f32_16x16x32_bf16 v[106:109], v[154:157], v[214:217], v[106:109]
	v_mfma_f32_16x16x32_bf16 v[42:45], v[162:165], v[214:217], v[42:45]
	v_mfma_f32_16x16x32_bf16 v[98:101], v[154:157], v[242:245], v[98:101]
	v_mfma_f32_16x16x32_bf16 v[34:37], v[162:165], v[242:245], v[34:37]
	s_barrier
	s_setprio 0
	s_add_i32 s47, s47, s23
	v_lshl_add_u64 v[178:179], s[26:27], 0, v[180:181]
	s_mov_b32 m0, s47
	ds_read_b128 v[166:169], v240 offset:16384
	ds_read_b128 v[170:173], v240 offset:17408
	ds_read_b128 v[174:177], v240 offset:18432
	ds_read_b128 v[206:209], v240 offset:19456
	ds_read_b128 v[210:213], v240 offset:20480
	ds_read_b128 v[214:217], v240 offset:21504
	ds_read_b128 v[218:221], v240 offset:22528
	ds_read_b128 v[242:245], v240 offset:23552
	global_load_lds_dwordx4 v[178:179], off sc0
	s_add_i32 m0, s47, 0x2000
	s_add_u32 s48, s26, 0x80000
	v_lshl_add_u64 v[222:223], s[26:27], 0, v[196:197]
	s_addc_u32 s49, s27, 0
	s_add_i32 s47, s69, s23
	global_load_lds_dwordx4 v[222:223], off sc0
	v_lshl_add_u64 v[246:247], s[48:49], 0, v[180:181]
	s_mov_b32 m0, s47
	v_lshl_add_u64 v[248:249], s[42:43], 0, v[194:195]
	global_load_lds_dwordx4 v[246:247], off sc0
	v_lshl_add_u64 v[246:247], s[48:49], 0, v[196:197]
	s_add_i32 m0, s47, 0x2000
	s_nop 0
	global_load_lds_dwordx4 v[246:247], off sc0
	v_lshl_add_u64 v[246:247], s[42:43], 0, v[192:193]
	s_mov_b32 m0, s6
	s_nop 0
	global_load_lds_dwordx4 v[246:247], off sc0
	s_mov_b32 m0, s9
	s_nop 0
	global_load_lds_dwordx4 v[248:249], off sc0
	s_waitcnt vmcnt(8)
	s_waitcnt lgkmcnt(0)
	s_setprio 1
	s_barrier
	v_mfma_f32_16x16x32_bf16 v[94:97], v[114:117], v[166:169], v[94:97]
	v_mfma_f32_16x16x32_bf16 v[30:33], v[122:125], v[166:169], v[30:33]
	v_mfma_f32_16x16x32_bf16 v[86:89], v[114:117], v[174:177], v[86:89]
	v_mfma_f32_16x16x32_bf16 v[22:25], v[122:125], v[174:177], v[22:25]
	v_mfma_f32_16x16x32_bf16 v[78:81], v[114:117], v[210:213], v[78:81]
	v_mfma_f32_16x16x32_bf16 v[14:17], v[122:125], v[210:213], v[14:17]
	v_mfma_f32_16x16x32_bf16 v[70:73], v[114:117], v[218:221], v[70:73]
	v_mfma_f32_16x16x32_bf16 v[6:9], v[122:125], v[218:221], v[6:9]
	v_mfma_f32_16x16x32_bf16 v[94:97], v[118:121], v[170:173], v[94:97]
	v_mfma_f32_16x16x32_bf16 v[30:33], v[146:149], v[170:173], v[30:33]
	v_mfma_f32_16x16x32_bf16 v[86:89], v[118:121], v[206:209], v[86:89]
	v_mfma_f32_16x16x32_bf16 v[22:25], v[146:149], v[206:209], v[22:25]
	v_mfma_f32_16x16x32_bf16 v[78:81], v[118:121], v[214:217], v[78:81]
	v_mfma_f32_16x16x32_bf16 v[14:17], v[146:149], v[214:217], v[14:17]
	v_mfma_f32_16x16x32_bf16 v[70:73], v[118:121], v[242:245], v[70:73]
	v_mfma_f32_16x16x32_bf16 v[6:9], v[146:149], v[242:245], v[6:9]
	v_mfma_f32_16x16x32_bf16 v[90:93], v[150:153], v[166:169], v[90:93]
	v_mfma_f32_16x16x32_bf16 v[26:29], v[158:161], v[166:169], v[26:29]
	v_mfma_f32_16x16x32_bf16 v[82:85], v[150:153], v[174:177], v[82:85]
	v_mfma_f32_16x16x32_bf16 v[18:21], v[158:161], v[174:177], v[18:21]
	v_mfma_f32_16x16x32_bf16 v[74:77], v[150:153], v[210:213], v[74:77]
	v_mfma_f32_16x16x32_bf16 v[10:13], v[158:161], v[210:213], v[10:13]
	v_mfma_f32_16x16x32_bf16 v[66:69], v[150:153], v[218:221], v[66:69]
	v_mfma_f32_16x16x32_bf16 v[2:5], v[158:161], v[218:221], v[2:5]
	v_mfma_f32_16x16x32_bf16 v[90:93], v[154:157], v[170:173], v[90:93]
	v_mfma_f32_16x16x32_bf16 v[26:29], v[162:165], v[170:173], v[26:29]
	v_mfma_f32_16x16x32_bf16 v[82:85], v[154:157], v[206:209], v[82:85]
	v_mfma_f32_16x16x32_bf16 v[18:21], v[162:165], v[206:209], v[18:21]
	v_mfma_f32_16x16x32_bf16 v[74:77], v[154:157], v[214:217], v[74:77]
	v_mfma_f32_16x16x32_bf16 v[10:13], v[162:165], v[214:217], v[10:13]
	v_mfma_f32_16x16x32_bf16 v[66:69], v[154:157], v[242:245], v[66:69]
	v_mfma_f32_16x16x32_bf16 v[2:5], v[162:165], v[242:245], v[2:5]
	s_barrier
	s_setprio 0
	s_add_i32 s47, 0, 0x18000
	s_add_i32 s48, 0, 0x1c000
	v_add_u32_e32 v146, s47, v239
	v_add_u32_e32 v162, s48, v239
	ds_read_b128 v[114:117], v146
	ds_read_b128 v[118:121], v146 offset:1024
	ds_read_b128 v[122:125], v146 offset:2048
	ds_read_b128 v[146:149], v146 offset:3072
	ds_read_b128 v[150:153], v162
	ds_read_b128 v[154:157], v162 offset:1024
	ds_read_b128 v[158:161], v162 offset:2048
	ds_read_b128 v[162:165], v162 offset:3072
	s_add_u32 s42, s42, 0x80000
	s_addc_u32 s43, s43, 0
	s_mov_b32 m0, s21
	v_lshl_add_u64 v[250:251], s[42:43], 0, v[192:193]
	ds_read_b128 v[166:169], v240 offset:32768
	ds_read_b128 v[170:173], v240 offset:33792
	ds_read_b128 v[174:177], v240 offset:34816
	ds_read_b128 v[206:209], v240 offset:35840
	ds_read_b128 v[210:213], v240 offset:36864
	ds_read_b128 v[214:217], v240 offset:37888
	ds_read_b128 v[218:221], v240 offset:38912
	ds_read_b128 v[242:245], v240 offset:39936
	global_load_lds_dwordx4 v[250:251], off sc0
	v_lshl_add_u64 v[250:251], s[42:43], 0, v[194:195]
	s_mov_b32 m0, s7
	s_nop 0
	global_load_lds_dwordx4 v[250:251], off sc0
	s_waitcnt vmcnt(8)
	s_waitcnt lgkmcnt(0)
	s_setprio 1
	s_barrier
	v_mfma_f32_16x16x32_bf16 v[142:145], v[114:117], v[166:169], v[142:145]
	v_mfma_f32_16x16x32_bf16 v[62:65], v[122:125], v[166:169], v[62:65]
	v_mfma_f32_16x16x32_bf16 v[134:137], v[114:117], v[174:177], v[134:137]
	v_mfma_f32_16x16x32_bf16 v[54:57], v[122:125], v[174:177], v[54:57]
	v_mfma_f32_16x16x32_bf16 v[126:129], v[114:117], v[210:213], v[126:129]
	v_mfma_f32_16x16x32_bf16 v[46:49], v[122:125], v[210:213], v[46:49]
	v_mfma_f32_16x16x32_bf16 v[102:105], v[114:117], v[218:221], v[102:105]
	v_mfma_f32_16x16x32_bf16 v[38:41], v[122:125], v[218:221], v[38:41]
	v_mfma_f32_16x16x32_bf16 v[142:145], v[118:121], v[170:173], v[142:145]
	v_mfma_f32_16x16x32_bf16 v[62:65], v[146:149], v[170:173], v[62:65]
	v_mfma_f32_16x16x32_bf16 v[134:137], v[118:121], v[206:209], v[134:137]
	v_mfma_f32_16x16x32_bf16 v[54:57], v[146:149], v[206:209], v[54:57]
	v_mfma_f32_16x16x32_bf16 v[126:129], v[118:121], v[214:217], v[126:129]
	v_mfma_f32_16x16x32_bf16 v[46:49], v[146:149], v[214:217], v[46:49]
	v_mfma_f32_16x16x32_bf16 v[102:105], v[118:121], v[242:245], v[102:105]
	v_mfma_f32_16x16x32_bf16 v[38:41], v[146:149], v[242:245], v[38:41]
	v_mfma_f32_16x16x32_bf16 v[138:141], v[150:153], v[166:169], v[138:141]
	v_mfma_f32_16x16x32_bf16 v[58:61], v[158:161], v[166:169], v[58:61]
	v_mfma_f32_16x16x32_bf16 v[130:133], v[150:153], v[174:177], v[130:133]
	v_mfma_f32_16x16x32_bf16 v[50:53], v[158:161], v[174:177], v[50:53]
	v_mfma_f32_16x16x32_bf16 v[106:109], v[150:153], v[210:213], v[106:109]
	v_mfma_f32_16x16x32_bf16 v[42:45], v[158:161], v[210:213], v[42:45]
	v_mfma_f32_16x16x32_bf16 v[98:101], v[150:153], v[218:221], v[98:101]
	v_mfma_f32_16x16x32_bf16 v[34:37], v[158:161], v[218:221], v[34:37]
	v_mfma_f32_16x16x32_bf16 v[138:141], v[154:157], v[170:173], v[138:141]
	v_mfma_f32_16x16x32_bf16 v[58:61], v[162:165], v[170:173], v[58:61]
	v_mfma_f32_16x16x32_bf16 v[130:133], v[154:157], v[206:209], v[130:133]
	v_mfma_f32_16x16x32_bf16 v[50:53], v[162:165], v[206:209], v[50:53]
	v_mfma_f32_16x16x32_bf16 v[106:109], v[154:157], v[214:217], v[106:109]
	v_mfma_f32_16x16x32_bf16 v[42:45], v[162:165], v[214:217], v[42:45]
	v_mfma_f32_16x16x32_bf16 v[98:101], v[154:157], v[242:245], v[98:101]
	v_mfma_f32_16x16x32_bf16 v[34:37], v[162:165], v[242:245], v[34:37]
	s_barrier
	s_setprio 0
	s_add_i32 s42, s47, s23
	v_lshl_add_u64 v[178:179], v[178:179], 0, s[16:17]
	s_mov_b32 m0, s42
	ds_read_b128 v[166:169], v240 offset:49152
	ds_read_b128 v[170:173], v240 offset:50176
	ds_read_b128 v[174:177], v240 offset:51200
	ds_read_b128 v[206:209], v240 offset:52224
	ds_read_b128 v[210:213], v240 offset:53248
	ds_read_b128 v[214:217], v240 offset:54272
	ds_read_b128 v[218:221], v240 offset:55296
	ds_read_b128 v[242:245], v240 offset:56320
	global_load_lds_dwordx4 v[178:179], off sc0
	s_add_i32 m0, s42, 0x2000
	s_add_u32 s26, s26, 0x80080
	v_lshl_add_u64 v[178:179], v[222:223], 0, s[16:17]
	s_addc_u32 s27, s27, 0
	s_add_i32 s42, s48, s23
	global_load_lds_dwordx4 v[178:179], off sc0
	v_lshl_add_u64 v[178:179], s[26:27], 0, v[180:181]
	s_mov_b32 m0, s42
	s_nop 0
	global_load_lds_dwordx4 v[178:179], off sc0
	v_lshl_add_u64 v[178:179], s[26:27], 0, v[196:197]
	s_add_i32 m0, s42, 0x2000
	s_nop 0
	global_load_lds_dwordx4 v[178:179], off sc0
	v_lshl_add_u64 v[178:179], v[246:247], 0, s[16:17]
	s_mov_b32 m0, s54
	s_nop 0
	global_load_lds_dwordx4 v[178:179], off sc0
	v_lshl_add_u64 v[178:179], v[248:249], 0, s[16:17]
	s_mov_b32 m0, s55
	s_nop 0
	global_load_lds_dwordx4 v[178:179], off sc0
	s_waitcnt vmcnt(8)
	s_waitcnt lgkmcnt(0)
	s_setprio 1
	s_barrier
	v_mfma_f32_16x16x32_bf16 v[94:97], v[114:117], v[166:169], v[94:97]
	v_mfma_f32_16x16x32_bf16 v[30:33], v[122:125], v[166:169], v[30:33]
	v_mfma_f32_16x16x32_bf16 v[86:89], v[114:117], v[174:177], v[86:89]
	v_mfma_f32_16x16x32_bf16 v[22:25], v[122:125], v[174:177], v[22:25]
	v_mfma_f32_16x16x32_bf16 v[78:81], v[114:117], v[210:213], v[78:81]
	v_mfma_f32_16x16x32_bf16 v[14:17], v[122:125], v[210:213], v[14:17]
	v_mfma_f32_16x16x32_bf16 v[70:73], v[114:117], v[218:221], v[70:73]
	v_mfma_f32_16x16x32_bf16 v[6:9], v[122:125], v[218:221], v[6:9]
	v_mfma_f32_16x16x32_bf16 v[94:97], v[118:121], v[170:173], v[94:97]
	v_mfma_f32_16x16x32_bf16 v[30:33], v[146:149], v[170:173], v[30:33]
	v_mfma_f32_16x16x32_bf16 v[86:89], v[118:121], v[206:209], v[86:89]
	v_mfma_f32_16x16x32_bf16 v[22:25], v[146:149], v[206:209], v[22:25]
	v_mfma_f32_16x16x32_bf16 v[78:81], v[118:121], v[214:217], v[78:81]
	v_mfma_f32_16x16x32_bf16 v[14:17], v[146:149], v[214:217], v[14:17]
	v_mfma_f32_16x16x32_bf16 v[70:73], v[118:121], v[242:245], v[70:73]
	v_mfma_f32_16x16x32_bf16 v[6:9], v[146:149], v[242:245], v[6:9]
	v_mfma_f32_16x16x32_bf16 v[90:93], v[150:153], v[166:169], v[90:93]
	v_mfma_f32_16x16x32_bf16 v[26:29], v[158:161], v[166:169], v[26:29]
	v_mfma_f32_16x16x32_bf16 v[82:85], v[150:153], v[174:177], v[82:85]
	v_mfma_f32_16x16x32_bf16 v[18:21], v[158:161], v[174:177], v[18:21]
	v_mfma_f32_16x16x32_bf16 v[74:77], v[150:153], v[210:213], v[74:77]
	v_mfma_f32_16x16x32_bf16 v[10:13], v[158:161], v[210:213], v[10:13]
	v_mfma_f32_16x16x32_bf16 v[66:69], v[150:153], v[218:221], v[66:69]
	v_mfma_f32_16x16x32_bf16 v[2:5], v[158:161], v[218:221], v[2:5]
	v_mfma_f32_16x16x32_bf16 v[90:93], v[154:157], v[170:173], v[90:93]
	v_mfma_f32_16x16x32_bf16 v[26:29], v[162:165], v[170:173], v[26:29]
	v_mfma_f32_16x16x32_bf16 v[82:85], v[154:157], v[206:209], v[82:85]
	v_mfma_f32_16x16x32_bf16 v[18:21], v[162:165], v[206:209], v[18:21]
	v_mfma_f32_16x16x32_bf16 v[74:77], v[154:157], v[214:217], v[74:77]
	v_mfma_f32_16x16x32_bf16 v[10:13], v[162:165], v[214:217], v[10:13]
	v_mfma_f32_16x16x32_bf16 v[66:69], v[154:157], v[242:245], v[66:69]
	v_mfma_f32_16x16x32_bf16 v[2:5], v[162:165], v[242:245], v[2:5]
	s_barrier
	s_setprio 0
	s_add_i32 s46, s46, 2
	s_add_u32 s40, s40, 0x100
	s_addc_u32 s41, s41, 0
	s_add_u32 s37, s37, 0x100
	s_addc_u32 s39, s39, 0
	s_cmp_gt_u32 s46, 29
	s_cbranch_scc1 .LBB0_1688

.LBB0_1761:
	s_add_u32 s26, s38, 0xfff80080
	s_addc_u32 s27, s39, -1
	s_add_i32 s64, 0, 0x10000
	s_cmp_eq_u32 s63, 28
	s_cselect_b32 s41, s57, s27
	s_cselect_b32 s40, s58, s26
	v_add_u32_e32 v155, s64, v153
	s_cselect_b32 s27, s59, s62
	s_cselect_b32 s26, s60, s61
	s_add_i32 s68, 0, 0x14000
	ds_read_b128 v[138:141], v155
	ds_read_b128 v[142:145], v155 offset:1024
	ds_read_b128 v[146:149], v155 offset:2048
	ds_read_b128 v[156:159], v155 offset:3072
	v_add_u32_e32 v155, s68, v153
	ds_read_b128 v[160:163], v155
	ds_read_b128 v[164:167], v155 offset:1024
	ds_read_b128 v[168:171], v155 offset:2048
	ds_read_b128 v[172:175], v155 offset:3072
	v_lshl_add_u64 v[220:221], s[38:39], 0, v[134:135]
	s_add_i32 m0, s3, 0xc000
	ds_read_b128 v[176:179], v154
	ds_read_b128 v[192:195], v154 offset:1024
	ds_read_b128 v[196:199], v154 offset:2048
	ds_read_b128 v[200:203], v154 offset:3072
	ds_read_b128 v[204:207], v154 offset:4096
	ds_read_b128 v[208:211], v154 offset:5120
	ds_read_b128 v[212:215], v154 offset:6144
	ds_read_b128 v[216:219], v154 offset:7168
	global_load_lds_dwordx4 v[220:221], off sc0
	v_lshl_add_u64 v[220:221], s[38:39], 0, v[136:137]
	s_add_i32 m0, s3, 0xe000
	s_nop 0
	global_load_lds_dwordx4 v[220:221], off sc0
	s_waitcnt vmcnt(8)
	s_waitcnt lgkmcnt(0)
	s_setprio 1
	s_barrier
	v_mfma_f32_16x16x32_bf16 v[126:129], v[138:141], v[176:179], v[126:129]
	v_mfma_f32_16x16x32_bf16 v[122:125], v[146:149], v[176:179], v[122:125]
	v_mfma_f32_16x16x32_bf16 v[110:113], v[138:141], v[196:199], v[110:113]
	v_mfma_f32_16x16x32_bf16 v[106:109], v[146:149], v[196:199], v[106:109]
	v_mfma_f32_16x16x32_bf16 v[94:97], v[138:141], v[204:207], v[94:97]
	v_mfma_f32_16x16x32_bf16 v[90:93], v[146:149], v[204:207], v[90:93]
	v_mfma_f32_16x16x32_bf16 v[78:81], v[138:141], v[212:215], v[78:81]
	v_mfma_f32_16x16x32_bf16 v[74:77], v[146:149], v[212:215], v[74:77]
	v_mfma_f32_16x16x32_bf16 v[126:129], v[142:145], v[192:195], v[126:129]
	v_mfma_f32_16x16x32_bf16 v[122:125], v[156:159], v[192:195], v[122:125]
	v_mfma_f32_16x16x32_bf16 v[110:113], v[142:145], v[200:203], v[110:113]
	v_mfma_f32_16x16x32_bf16 v[106:109], v[156:159], v[200:203], v[106:109]
	v_mfma_f32_16x16x32_bf16 v[94:97], v[142:145], v[208:211], v[94:97]
	v_mfma_f32_16x16x32_bf16 v[90:93], v[156:159], v[208:211], v[90:93]
	v_mfma_f32_16x16x32_bf16 v[78:81], v[142:145], v[216:219], v[78:81]
	v_mfma_f32_16x16x32_bf16 v[74:77], v[156:159], v[216:219], v[74:77]
	v_mfma_f32_16x16x32_bf16 v[118:121], v[160:163], v[176:179], v[118:121]
	v_mfma_f32_16x16x32_bf16 v[114:117], v[168:171], v[176:179], v[114:117]
	v_mfma_f32_16x16x32_bf16 v[102:105], v[160:163], v[196:199], v[102:105]
	v_mfma_f32_16x16x32_bf16 v[98:101], v[168:171], v[196:199], v[98:101]
	v_mfma_f32_16x16x32_bf16 v[86:89], v[160:163], v[204:207], v[86:89]
	v_mfma_f32_16x16x32_bf16 v[82:85], v[168:171], v[204:207], v[82:85]
	v_mfma_f32_16x16x32_bf16 v[70:73], v[160:163], v[212:215], v[70:73]
	v_mfma_f32_16x16x32_bf16 v[66:69], v[168:171], v[212:215], v[66:69]
	v_mfma_f32_16x16x32_bf16 v[118:121], v[164:167], v[192:195], v[118:121]
	v_mfma_f32_16x16x32_bf16 v[114:117], v[172:175], v[192:195], v[114:117]
	v_mfma_f32_16x16x32_bf16 v[102:105], v[164:167], v[200:203], v[102:105]
	v_mfma_f32_16x16x32_bf16 v[98:101], v[172:175], v[200:203], v[98:101]
	v_mfma_f32_16x16x32_bf16 v[86:89], v[164:167], v[208:211], v[86:89]
	v_mfma_f32_16x16x32_bf16 v[82:85], v[172:175], v[208:211], v[82:85]
	v_mfma_f32_16x16x32_bf16 v[70:73], v[164:167], v[216:219], v[70:73]
	v_mfma_f32_16x16x32_bf16 v[66:69], v[172:175], v[216:219], v[66:69]
	s_barrier
	s_setprio 0
	s_add_i32 s64, s64, s43
	v_lshl_add_u64 v[220:221], s[26:27], 0, v[132:133]
	s_mov_b32 m0, s64
	ds_read_b128 v[176:179], v154 offset:16384
	ds_read_b128 v[192:195], v154 offset:17408
	ds_read_b128 v[196:199], v154 offset:18432
	ds_read_b128 v[200:203], v154 offset:19456
	ds_read_b128 v[204:207], v154 offset:20480
	ds_read_b128 v[208:211], v154 offset:21504
	ds_read_b128 v[212:215], v154 offset:22528
	ds_read_b128 v[216:219], v154 offset:23552
	global_load_lds_dwordx4 v[220:221], off sc0
	s_add_i32 m0, s64, 0x2000
	s_add_u32 s66, s26, 0x80000
	v_lshl_add_u64 v[222:223], s[26:27], 0, v[130:131]
	s_addc_u32 s67, s27, 0
	s_add_i32 s64, s68, s43
	global_load_lds_dwordx4 v[222:223], off sc0
	v_lshl_add_u64 v[238:239], s[66:67], 0, v[132:133]
	s_mov_b32 m0, s64
	v_lshl_add_u64 v[240:241], s[40:41], 0, v[130:131]
	global_load_lds_dwordx4 v[238:239], off sc0
	v_lshl_add_u64 v[238:239], s[66:67], 0, v[130:131]
	s_add_i32 m0, s64, 0x2000
	s_nop 0
	global_load_lds_dwordx4 v[238:239], off sc0
	v_lshl_add_u64 v[238:239], s[40:41], 0, v[132:133]
	s_mov_b32 m0, s3
	s_nop 0
	global_load_lds_dwordx4 v[238:239], off sc0
	s_mov_b32 m0, s45
	s_nop 0
	global_load_lds_dwordx4 v[240:241], off sc0
	s_waitcnt vmcnt(8)
	s_waitcnt lgkmcnt(0)
	s_setprio 1
	s_barrier
	v_mfma_f32_16x16x32_bf16 v[62:65], v[138:141], v[176:179], v[62:65]
	v_mfma_f32_16x16x32_bf16 v[58:61], v[146:149], v[176:179], v[58:61]
	v_mfma_f32_16x16x32_bf16 v[46:49], v[138:141], v[196:199], v[46:49]
	v_mfma_f32_16x16x32_bf16 v[42:45], v[146:149], v[196:199], v[42:45]
	v_mfma_f32_16x16x32_bf16 v[30:33], v[138:141], v[204:207], v[30:33]
	v_mfma_f32_16x16x32_bf16 v[26:29], v[146:149], v[204:207], v[26:29]
	v_mfma_f32_16x16x32_bf16 v[14:17], v[138:141], v[212:215], v[14:17]
	v_mfma_f32_16x16x32_bf16 v[10:13], v[146:149], v[212:215], v[10:13]
	v_mfma_f32_16x16x32_bf16 v[62:65], v[142:145], v[192:195], v[62:65]
	v_mfma_f32_16x16x32_bf16 v[58:61], v[156:159], v[192:195], v[58:61]
	v_mfma_f32_16x16x32_bf16 v[46:49], v[142:145], v[200:203], v[46:49]
	v_mfma_f32_16x16x32_bf16 v[42:45], v[156:159], v[200:203], v[42:45]
	v_mfma_f32_16x16x32_bf16 v[30:33], v[142:145], v[208:211], v[30:33]
	v_mfma_f32_16x16x32_bf16 v[26:29], v[156:159], v[208:211], v[26:29]
	v_mfma_f32_16x16x32_bf16 v[14:17], v[142:145], v[216:219], v[14:17]
	v_mfma_f32_16x16x32_bf16 v[10:13], v[156:159], v[216:219], v[10:13]
	v_mfma_f32_16x16x32_bf16 v[54:57], v[160:163], v[176:179], v[54:57]
	v_mfma_f32_16x16x32_bf16 v[50:53], v[168:171], v[176:179], v[50:53]
	v_mfma_f32_16x16x32_bf16 v[38:41], v[160:163], v[196:199], v[38:41]
	v_mfma_f32_16x16x32_bf16 v[34:37], v[168:171], v[196:199], v[34:37]
	v_mfma_f32_16x16x32_bf16 v[22:25], v[160:163], v[204:207], v[22:25]
	v_mfma_f32_16x16x32_bf16 v[18:21], v[168:171], v[204:207], v[18:21]
	v_mfma_f32_16x16x32_bf16 v[6:9], v[160:163], v[212:215], v[6:9]
	v_mfma_f32_16x16x32_bf16 v[2:5], v[168:171], v[212:215], v[2:5]
	v_mfma_f32_16x16x32_bf16 v[54:57], v[164:167], v[192:195], v[54:57]
	v_mfma_f32_16x16x32_bf16 v[50:53], v[172:175], v[192:195], v[50:53]
	v_mfma_f32_16x16x32_bf16 v[38:41], v[164:167], v[200:203], v[38:41]
	v_mfma_f32_16x16x32_bf16 v[34:37], v[172:175], v[200:203], v[34:37]
	v_mfma_f32_16x16x32_bf16 v[22:25], v[164:167], v[208:211], v[22:25]
	v_mfma_f32_16x16x32_bf16 v[18:21], v[172:175], v[208:211], v[18:21]
	v_mfma_f32_16x16x32_bf16 v[6:9], v[164:167], v[216:219], v[6:9]
	v_mfma_f32_16x16x32_bf16 v[2:5], v[172:175], v[216:219], v[2:5]
	s_barrier
	s_setprio 0
	s_add_i32 s64, 0, 0x18000
	v_add_u32_e32 v155, s64, v153
	s_add_i32 s66, 0, 0x1c000
	ds_read_b128 v[138:141], v155
	ds_read_b128 v[142:145], v155 offset:1024
	ds_read_b128 v[146:149], v155 offset:2048
	ds_read_b128 v[156:159], v155 offset:3072
	v_add_u32_e32 v155, s66, v153
	ds_read_b128 v[160:163], v155
	ds_read_b128 v[164:167], v155 offset:1024
	ds_read_b128 v[168:171], v155 offset:2048
	ds_read_b128 v[172:175], v155 offset:3072
	s_add_u32 s40, s40, 0x80000
	s_addc_u32 s41, s41, 0
	s_mov_b32 m0, s46
	v_lshl_add_u64 v[242:243], s[40:41], 0, v[132:133]
	ds_read_b128 v[176:179], v154 offset:32768
	ds_read_b128 v[192:195], v154 offset:33792
	ds_read_b128 v[196:199], v154 offset:34816
	ds_read_b128 v[200:203], v154 offset:35840
	ds_read_b128 v[204:207], v154 offset:36864
	ds_read_b128 v[208:211], v154 offset:37888
	ds_read_b128 v[212:215], v154 offset:38912
	ds_read_b128 v[216:219], v154 offset:39936
	global_load_lds_dwordx4 v[242:243], off sc0
	v_lshl_add_u64 v[242:243], s[40:41], 0, v[130:131]
	s_mov_b32 m0, s47
	s_nop 0
	global_load_lds_dwordx4 v[242:243], off sc0
	s_waitcnt vmcnt(8)
	s_waitcnt lgkmcnt(0)
	s_setprio 1
	s_barrier
	v_mfma_f32_16x16x32_bf16 v[126:129], v[138:141], v[176:179], v[126:129]
	v_mfma_f32_16x16x32_bf16 v[122:125], v[146:149], v[176:179], v[122:125]
	v_mfma_f32_16x16x32_bf16 v[110:113], v[138:141], v[196:199], v[110:113]
	v_mfma_f32_16x16x32_bf16 v[106:109], v[146:149], v[196:199], v[106:109]
	v_mfma_f32_16x16x32_bf16 v[94:97], v[138:141], v[204:207], v[94:97]
	v_mfma_f32_16x16x32_bf16 v[90:93], v[146:149], v[204:207], v[90:93]
	v_mfma_f32_16x16x32_bf16 v[78:81], v[138:141], v[212:215], v[78:81]
	v_mfma_f32_16x16x32_bf16 v[74:77], v[146:149], v[212:215], v[74:77]
	v_mfma_f32_16x16x32_bf16 v[126:129], v[142:145], v[192:195], v[126:129]
	v_mfma_f32_16x16x32_bf16 v[122:125], v[156:159], v[192:195], v[122:125]
	v_mfma_f32_16x16x32_bf16 v[110:113], v[142:145], v[200:203], v[110:113]
	v_mfma_f32_16x16x32_bf16 v[106:109], v[156:159], v[200:203], v[106:109]
	v_mfma_f32_16x16x32_bf16 v[94:97], v[142:145], v[208:211], v[94:97]
	v_mfma_f32_16x16x32_bf16 v[90:93], v[156:159], v[208:211], v[90:93]
	v_mfma_f32_16x16x32_bf16 v[78:81], v[142:145], v[216:219], v[78:81]
	v_mfma_f32_16x16x32_bf16 v[74:77], v[156:159], v[216:219], v[74:77]
	v_mfma_f32_16x16x32_bf16 v[118:121], v[160:163], v[176:179], v[118:121]
	v_mfma_f32_16x16x32_bf16 v[114:117], v[168:171], v[176:179], v[114:117]
	v_mfma_f32_16x16x32_bf16 v[102:105], v[160:163], v[196:199], v[102:105]
	v_mfma_f32_16x16x32_bf16 v[98:101], v[168:171], v[196:199], v[98:101]
	v_mfma_f32_16x16x32_bf16 v[86:89], v[160:163], v[204:207], v[86:89]
	v_mfma_f32_16x16x32_bf16 v[82:85], v[168:171], v[204:207], v[82:85]
	v_mfma_f32_16x16x32_bf16 v[70:73], v[160:163], v[212:215], v[70:73]
	v_mfma_f32_16x16x32_bf16 v[66:69], v[168:171], v[212:215], v[66:69]
	v_mfma_f32_16x16x32_bf16 v[118:121], v[164:167], v[192:195], v[118:121]
	v_mfma_f32_16x16x32_bf16 v[114:117], v[172:175], v[192:195], v[114:117]
	v_mfma_f32_16x16x32_bf16 v[102:105], v[164:167], v[200:203], v[102:105]
	v_mfma_f32_16x16x32_bf16 v[98:101], v[172:175], v[200:203], v[98:101]
	v_mfma_f32_16x16x32_bf16 v[86:89], v[164:167], v[208:211], v[86:89]
	v_mfma_f32_16x16x32_bf16 v[82:85], v[172:175], v[208:211], v[82:85]
	v_mfma_f32_16x16x32_bf16 v[70:73], v[164:167], v[216:219], v[70:73]
	v_mfma_f32_16x16x32_bf16 v[66:69], v[172:175], v[216:219], v[66:69]
	s_barrier
	s_setprio 0
	s_add_i32 s40, s64, s43
	v_lshl_add_u64 v[220:221], v[220:221], 0, s[16:17]
	s_mov_b32 m0, s40
	ds_read_b128 v[176:179], v154 offset:49152
	ds_read_b128 v[192:195], v154 offset:50176
	ds_read_b128 v[196:199], v154 offset:51200
	ds_read_b128 v[200:203], v154 offset:52224
	ds_read_b128 v[204:207], v154 offset:53248
	ds_read_b128 v[208:211], v154 offset:54272
	ds_read_b128 v[212:215], v154 offset:55296
	ds_read_b128 v[216:219], v154 offset:56320
	global_load_lds_dwordx4 v[220:221], off sc0
	s_add_i32 m0, s40, 0x2000
	s_add_u32 s26, s26, 0x80080
	v_lshl_add_u64 v[220:221], v[222:223], 0, s[16:17]
	s_addc_u32 s27, s27, 0
	s_add_i32 s40, s66, s43
	global_load_lds_dwordx4 v[220:221], off sc0
	v_lshl_add_u64 v[220:221], s[26:27], 0, v[132:133]
	s_mov_b32 m0, s40
	s_nop 0
	global_load_lds_dwordx4 v[220:221], off sc0
	v_lshl_add_u64 v[220:221], s[26:27], 0, v[130:131]
	s_add_i32 m0, s40, 0x2000
	s_nop 0
	global_load_lds_dwordx4 v[220:221], off sc0
	v_lshl_add_u64 v[220:221], v[238:239], 0, s[16:17]
	s_mov_b32 m0, s50
	s_nop 0
	global_load_lds_dwordx4 v[220:221], off sc0
	v_lshl_add_u64 v[220:221], v[240:241], 0, s[16:17]
	s_mov_b32 m0, s51
	s_nop 0
	global_load_lds_dwordx4 v[220:221], off sc0
	s_waitcnt vmcnt(8)
	s_waitcnt lgkmcnt(0)
	s_setprio 1
	s_barrier
	v_mfma_f32_16x16x32_bf16 v[62:65], v[138:141], v[176:179], v[62:65]
	v_mfma_f32_16x16x32_bf16 v[58:61], v[146:149], v[176:179], v[58:61]
	v_mfma_f32_16x16x32_bf16 v[46:49], v[138:141], v[196:199], v[46:49]
	v_mfma_f32_16x16x32_bf16 v[42:45], v[146:149], v[196:199], v[42:45]
	v_mfma_f32_16x16x32_bf16 v[30:33], v[138:141], v[204:207], v[30:33]
	v_mfma_f32_16x16x32_bf16 v[26:29], v[146:149], v[204:207], v[26:29]
	v_mfma_f32_16x16x32_bf16 v[14:17], v[138:141], v[212:215], v[14:17]
	v_mfma_f32_16x16x32_bf16 v[10:13], v[146:149], v[212:215], v[10:13]
	v_mfma_f32_16x16x32_bf16 v[62:65], v[142:145], v[192:195], v[62:65]
	v_mfma_f32_16x16x32_bf16 v[58:61], v[156:159], v[192:195], v[58:61]
	v_mfma_f32_16x16x32_bf16 v[46:49], v[142:145], v[200:203], v[46:49]
	v_mfma_f32_16x16x32_bf16 v[42:45], v[156:159], v[200:203], v[42:45]
	v_mfma_f32_16x16x32_bf16 v[30:33], v[142:145], v[208:211], v[30:33]
	v_mfma_f32_16x16x32_bf16 v[26:29], v[156:159], v[208:211], v[26:29]
	v_mfma_f32_16x16x32_bf16 v[14:17], v[142:145], v[216:219], v[14:17]
	v_mfma_f32_16x16x32_bf16 v[10:13], v[156:159], v[216:219], v[10:13]
	v_mfma_f32_16x16x32_bf16 v[54:57], v[160:163], v[176:179], v[54:57]
	v_mfma_f32_16x16x32_bf16 v[50:53], v[168:171], v[176:179], v[50:53]
	v_mfma_f32_16x16x32_bf16 v[38:41], v[160:163], v[196:199], v[38:41]
	v_mfma_f32_16x16x32_bf16 v[34:37], v[168:171], v[196:199], v[34:37]
	v_mfma_f32_16x16x32_bf16 v[22:25], v[160:163], v[204:207], v[22:25]
	v_mfma_f32_16x16x32_bf16 v[18:21], v[168:171], v[204:207], v[18:21]
	v_mfma_f32_16x16x32_bf16 v[6:9], v[160:163], v[212:215], v[6:9]
	v_mfma_f32_16x16x32_bf16 v[2:5], v[168:171], v[212:215], v[2:5]
	v_mfma_f32_16x16x32_bf16 v[54:57], v[164:167], v[192:195], v[54:57]
	v_mfma_f32_16x16x32_bf16 v[50:53], v[172:175], v[192:195], v[50:53]
	v_mfma_f32_16x16x32_bf16 v[38:41], v[164:167], v[200:203], v[38:41]
	v_mfma_f32_16x16x32_bf16 v[34:37], v[172:175], v[200:203], v[34:37]
	v_mfma_f32_16x16x32_bf16 v[22:25], v[164:167], v[208:211], v[22:25]
	v_mfma_f32_16x16x32_bf16 v[18:21], v[172:175], v[208:211], v[18:21]
	v_mfma_f32_16x16x32_bf16 v[6:9], v[164:167], v[216:219], v[6:9]
	v_mfma_f32_16x16x32_bf16 v[2:5], v[172:175], v[216:219], v[2:5]
	s_barrier
	s_setprio 0
	s_add_i32 s63, s63, 2
	s_add_u32 s38, s38, 0x100
	s_addc_u32 s39, s39, 0
	s_add_u32 s61, s61, 0x100
	s_addc_u32 s62, s62, 0
	s_cmp_gt_u32 s63, 29
	s_cbranch_scc0 .LBB0_1761
	s_and_b64 vcc, exec, s[34:35]
	s_cbranch_vccz .LBB0_1764
	s_barrier

.LBB0_2241:
	s_add_u32 s28, s26, 0x100
	s_addc_u32 s29, s27, 0
	s_add_i32 s58, 0, 0x10000
	s_cmpk_eq_i32 s57, 0x52
	s_cselect_b32 s35, s23, s29
	s_cselect_b32 s34, s22, s28
	s_cselect_b32 s31, s25, s39
	s_cselect_b32 s30, s24, s38
	s_add_i32 s59, 0, 0x14000
	v_add_u32_e32 v166, s58, v156
	v_add_u32_e32 v178, s59, v156
	ds_read_b128 v[148:151], v166
	ds_read_b128 v[158:161], v166 offset:1024
	ds_read_b128 v[162:165], v166 offset:2048
	ds_read_b128 v[166:169], v166 offset:3072
	ds_read_b128 v[170:173], v178
	ds_read_b128 v[174:177], v178 offset:1024
	ds_read_b128 v[190:193], v178 offset:2048
	ds_read_b128 v[194:197], v178 offset:3072
	v_lshl_add_u64 v[178:179], s[26:27], 0, v[144:145]
	s_add_i32 m0, s43, 0xc000
	ds_read_b128 v[198:201], v157
	ds_read_b128 v[202:205], v157 offset:1024
	ds_read_b128 v[206:209], v157 offset:2048
	ds_read_b128 v[210:213], v157 offset:3072
	ds_read_b128 v[214:217], v157 offset:4096
	ds_read_b128 v[218:221], v157 offset:5120
	ds_read_b128 v[238:241], v157 offset:6144
	ds_read_b128 v[242:245], v157 offset:7168
	global_load_lds_dwordx4 v[178:179], off sc0
	v_lshl_add_u64 v[178:179], s[26:27], 0, v[146:147]
	s_add_i32 m0, s43, 0xe000
	s_nop 0
	global_load_lds_dwordx4 v[178:179], off sc0
	s_waitcnt vmcnt(8)
	s_waitcnt lgkmcnt(0)
	s_setprio 1
	s_barrier
	v_mfma_f32_16x16x32_bf16 v[126:129], v[148:151], v[198:201], v[126:129]
	v_mfma_f32_16x16x32_bf16 v[114:117], v[162:165], v[198:201], v[114:117]
	v_mfma_f32_16x16x32_bf16 v[106:109], v[148:151], v[206:209], v[106:109]
	v_mfma_f32_16x16x32_bf16 v[98:101], v[162:165], v[206:209], v[98:101]
	v_mfma_f32_16x16x32_bf16 v[90:93], v[148:151], v[214:217], v[90:93]
	v_mfma_f32_16x16x32_bf16 v[82:85], v[162:165], v[214:217], v[82:85]
	v_mfma_f32_16x16x32_bf16 v[74:77], v[148:151], v[238:241], v[74:77]
	v_mfma_f32_16x16x32_bf16 v[54:57], v[162:165], v[238:241], v[54:57]
	v_mfma_f32_16x16x32_bf16 v[126:129], v[158:161], v[202:205], v[126:129]
	v_mfma_f32_16x16x32_bf16 v[114:117], v[166:169], v[202:205], v[114:117]
	v_mfma_f32_16x16x32_bf16 v[106:109], v[158:161], v[210:213], v[106:109]
	v_mfma_f32_16x16x32_bf16 v[98:101], v[166:169], v[210:213], v[98:101]
	v_mfma_f32_16x16x32_bf16 v[90:93], v[158:161], v[218:221], v[90:93]
	v_mfma_f32_16x16x32_bf16 v[82:85], v[166:169], v[218:221], v[82:85]
	v_mfma_f32_16x16x32_bf16 v[74:77], v[158:161], v[242:245], v[74:77]
	v_mfma_f32_16x16x32_bf16 v[54:57], v[166:169], v[242:245], v[54:57]
	v_mfma_f32_16x16x32_bf16 v[118:121], v[170:173], v[198:201], v[118:121]
	v_mfma_f32_16x16x32_bf16 v[122:125], v[190:193], v[198:201], v[122:125]
	v_mfma_f32_16x16x32_bf16 v[102:105], v[170:173], v[206:209], v[102:105]
	v_mfma_f32_16x16x32_bf16 v[110:113], v[190:193], v[206:209], v[110:113]
	v_mfma_f32_16x16x32_bf16 v[86:89], v[170:173], v[214:217], v[86:89]
	v_mfma_f32_16x16x32_bf16 v[94:97], v[190:193], v[214:217], v[94:97]
	v_mfma_f32_16x16x32_bf16 v[70:73], v[170:173], v[238:241], v[70:73]
	v_mfma_f32_16x16x32_bf16 v[78:81], v[190:193], v[238:241], v[78:81]
	v_mfma_f32_16x16x32_bf16 v[118:121], v[174:177], v[202:205], v[118:121]
	v_mfma_f32_16x16x32_bf16 v[122:125], v[194:197], v[202:205], v[122:125]
	v_mfma_f32_16x16x32_bf16 v[102:105], v[174:177], v[210:213], v[102:105]
	v_mfma_f32_16x16x32_bf16 v[110:113], v[194:197], v[210:213], v[110:113]
	v_mfma_f32_16x16x32_bf16 v[86:89], v[174:177], v[218:221], v[86:89]
	v_mfma_f32_16x16x32_bf16 v[94:97], v[194:197], v[218:221], v[94:97]
	v_mfma_f32_16x16x32_bf16 v[70:73], v[174:177], v[242:245], v[70:73]
	v_mfma_f32_16x16x32_bf16 v[78:81], v[194:197], v[242:245], v[78:81]
	s_barrier
	s_setprio 0
	s_add_i32 s26, s58, s40
	v_lshl_add_u64 v[178:179], s[30:31], 0, v[136:137]
	s_mov_b32 m0, s26
	ds_read_b128 v[198:201], v157 offset:16384
	ds_read_b128 v[202:205], v157 offset:17408
	ds_read_b128 v[206:209], v157 offset:18432
	ds_read_b128 v[210:213], v157 offset:19456
	ds_read_b128 v[214:217], v157 offset:20480
	ds_read_b128 v[218:221], v157 offset:21504
	ds_read_b128 v[238:241], v157 offset:22528
	ds_read_b128 v[242:245], v157 offset:23552
	global_load_lds_dwordx4 v[178:179], off sc0
	s_add_i32 m0, s26, 0x2000
	s_add_u32 s26, s30, 0x158000
	v_lshl_add_u64 v[222:223], s[30:31], 0, v[140:141]
	s_addc_u32 s27, s31, 0
	s_add_i32 s58, s59, s40
	global_load_lds_dwordx4 v[222:223], off sc0
	v_lshl_add_u64 v[246:247], s[26:27], 0, v[136:137]
	s_mov_b32 m0, s58
	v_lshl_add_u64 v[248:249], s[34:35], 0, v[138:139]
	global_load_lds_dwordx4 v[246:247], off sc0
	v_lshl_add_u64 v[246:247], s[26:27], 0, v[140:141]
	s_add_i32 m0, s58, 0x2000
	s_nop 0
	global_load_lds_dwordx4 v[246:247], off sc0
	v_lshl_add_u64 v[246:247], s[34:35], 0, v[134:135]
	s_mov_b32 m0, s43
	s_nop 0
	global_load_lds_dwordx4 v[246:247], off sc0
	s_mov_b32 m0, s44
	s_nop 0
	global_load_lds_dwordx4 v[248:249], off sc0
	s_waitcnt vmcnt(8)
	s_waitcnt lgkmcnt(0)
	s_setprio 1
	s_barrier
	v_mfma_f32_16x16x32_bf16 v[50:53], v[148:151], v[198:201], v[50:53]
	v_mfma_f32_16x16x32_bf16 v[38:41], v[162:165], v[198:201], v[38:41]
	v_mfma_f32_16x16x32_bf16 v[22:25], v[148:151], v[206:209], v[22:25]
	v_mfma_f32_16x16x32_bf16 v[42:45], v[162:165], v[206:209], v[42:45]
	v_mfma_f32_16x16x32_bf16 v[30:33], v[148:151], v[214:217], v[30:33]
	v_mfma_f32_16x16x32_bf16 v[18:21], v[162:165], v[214:217], v[18:21]
	v_mfma_f32_16x16x32_bf16 v[10:13], v[148:151], v[238:241], v[10:13]
	v_mfma_f32_16x16x32_bf16 v[2:5], v[162:165], v[238:241], v[2:5]
	v_mfma_f32_16x16x32_bf16 v[50:53], v[158:161], v[202:205], v[50:53]
	v_mfma_f32_16x16x32_bf16 v[38:41], v[166:169], v[202:205], v[38:41]
	v_mfma_f32_16x16x32_bf16 v[22:25], v[158:161], v[210:213], v[22:25]
	v_mfma_f32_16x16x32_bf16 v[42:45], v[166:169], v[210:213], v[42:45]
	v_mfma_f32_16x16x32_bf16 v[30:33], v[158:161], v[218:221], v[30:33]
	v_mfma_f32_16x16x32_bf16 v[18:21], v[166:169], v[218:221], v[18:21]
	v_mfma_f32_16x16x32_bf16 v[10:13], v[158:161], v[242:245], v[10:13]
	v_mfma_f32_16x16x32_bf16 v[2:5], v[166:169], v[242:245], v[2:5]
	v_mfma_f32_16x16x32_bf16 v[46:49], v[170:173], v[198:201], v[46:49]
	v_mfma_f32_16x16x32_bf16 v[58:61], v[190:193], v[198:201], v[58:61]
	v_mfma_f32_16x16x32_bf16 v[62:65], v[170:173], v[206:209], v[62:65]
	v_mfma_f32_16x16x32_bf16 v[66:69], v[190:193], v[206:209], v[66:69]
	v_mfma_f32_16x16x32_bf16 v[26:29], v[170:173], v[214:217], v[26:29]
	v_mfma_f32_16x16x32_bf16 v[34:37], v[190:193], v[214:217], v[34:37]
	v_mfma_f32_16x16x32_bf16 v[6:9], v[170:173], v[238:241], v[6:9]
	v_mfma_f32_16x16x32_bf16 v[14:17], v[190:193], v[238:241], v[14:17]
	v_mfma_f32_16x16x32_bf16 v[46:49], v[174:177], v[202:205], v[46:49]
	v_mfma_f32_16x16x32_bf16 v[58:61], v[194:197], v[202:205], v[58:61]
	v_mfma_f32_16x16x32_bf16 v[62:65], v[174:177], v[210:213], v[62:65]
	v_mfma_f32_16x16x32_bf16 v[66:69], v[194:197], v[210:213], v[66:69]
	v_mfma_f32_16x16x32_bf16 v[26:29], v[174:177], v[218:221], v[26:29]
	v_mfma_f32_16x16x32_bf16 v[34:37], v[194:197], v[218:221], v[34:37]
	v_mfma_f32_16x16x32_bf16 v[6:9], v[174:177], v[242:245], v[6:9]
	v_mfma_f32_16x16x32_bf16 v[14:17], v[194:197], v[242:245], v[14:17]
	s_barrier
	s_setprio 0
	s_add_i32 s58, 0, 0x18000
	s_add_i32 s59, 0, 0x1c000
	v_add_u32_e32 v166, s58, v156
	v_add_u32_e32 v194, s59, v156
	ds_read_b128 v[148:151], v166
	ds_read_b128 v[158:161], v166 offset:1024
	ds_read_b128 v[162:165], v166 offset:2048
	ds_read_b128 v[166:169], v166 offset:3072
	ds_read_b128 v[170:173], v194
	ds_read_b128 v[174:177], v194 offset:1024
	ds_read_b128 v[190:193], v194 offset:2048
	ds_read_b128 v[194:197], v194 offset:3072
	s_add_u32 s26, s34, 0x158000
	s_addc_u32 s27, s35, 0
	s_mov_b32 m0, s45
	v_lshl_add_u64 v[250:251], s[26:27], 0, v[134:135]
	ds_read_b128 v[198:201], v157 offset:32768
	ds_read_b128 v[202:205], v157 offset:33792
	ds_read_b128 v[206:209], v157 offset:34816
	ds_read_b128 v[210:213], v157 offset:35840
	ds_read_b128 v[214:217], v157 offset:36864
	ds_read_b128 v[218:221], v157 offset:37888
	ds_read_b128 v[238:241], v157 offset:38912
	ds_read_b128 v[242:245], v157 offset:39936
	global_load_lds_dwordx4 v[250:251], off sc0
	v_lshl_add_u64 v[250:251], s[26:27], 0, v[138:139]
	s_mov_b32 m0, s47
	s_nop 0
	global_load_lds_dwordx4 v[250:251], off sc0
	s_waitcnt vmcnt(8)
	s_waitcnt lgkmcnt(0)
	s_setprio 1
	s_barrier
	v_mfma_f32_16x16x32_bf16 v[126:129], v[148:151], v[198:201], v[126:129]
	v_mfma_f32_16x16x32_bf16 v[114:117], v[162:165], v[198:201], v[114:117]
	v_mfma_f32_16x16x32_bf16 v[106:109], v[148:151], v[206:209], v[106:109]
	v_mfma_f32_16x16x32_bf16 v[98:101], v[162:165], v[206:209], v[98:101]
	v_mfma_f32_16x16x32_bf16 v[90:93], v[148:151], v[214:217], v[90:93]
	v_mfma_f32_16x16x32_bf16 v[82:85], v[162:165], v[214:217], v[82:85]
	v_mfma_f32_16x16x32_bf16 v[74:77], v[148:151], v[238:241], v[74:77]
	v_mfma_f32_16x16x32_bf16 v[54:57], v[162:165], v[238:241], v[54:57]
	v_mfma_f32_16x16x32_bf16 v[126:129], v[158:161], v[202:205], v[126:129]
	v_mfma_f32_16x16x32_bf16 v[114:117], v[166:169], v[202:205], v[114:117]
	v_mfma_f32_16x16x32_bf16 v[106:109], v[158:161], v[210:213], v[106:109]
	v_mfma_f32_16x16x32_bf16 v[98:101], v[166:169], v[210:213], v[98:101]
	v_mfma_f32_16x16x32_bf16 v[90:93], v[158:161], v[218:221], v[90:93]
	v_mfma_f32_16x16x32_bf16 v[82:85], v[166:169], v[218:221], v[82:85]
	v_mfma_f32_16x16x32_bf16 v[74:77], v[158:161], v[242:245], v[74:77]
	v_mfma_f32_16x16x32_bf16 v[54:57], v[166:169], v[242:245], v[54:57]
	v_mfma_f32_16x16x32_bf16 v[118:121], v[170:173], v[198:201], v[118:121]
	v_mfma_f32_16x16x32_bf16 v[122:125], v[190:193], v[198:201], v[122:125]
	v_mfma_f32_16x16x32_bf16 v[102:105], v[170:173], v[206:209], v[102:105]
	v_mfma_f32_16x16x32_bf16 v[110:113], v[190:193], v[206:209], v[110:113]
	v_mfma_f32_16x16x32_bf16 v[86:89], v[170:173], v[214:217], v[86:89]
	v_mfma_f32_16x16x32_bf16 v[94:97], v[190:193], v[214:217], v[94:97]
	v_mfma_f32_16x16x32_bf16 v[70:73], v[170:173], v[238:241], v[70:73]
	v_mfma_f32_16x16x32_bf16 v[78:81], v[190:193], v[238:241], v[78:81]
	v_mfma_f32_16x16x32_bf16 v[118:121], v[174:177], v[202:205], v[118:121]
	v_mfma_f32_16x16x32_bf16 v[122:125], v[194:197], v[202:205], v[122:125]
	v_mfma_f32_16x16x32_bf16 v[102:105], v[174:177], v[210:213], v[102:105]
	v_mfma_f32_16x16x32_bf16 v[110:113], v[194:197], v[210:213], v[110:113]
	v_mfma_f32_16x16x32_bf16 v[86:89], v[174:177], v[218:221], v[86:89]
	v_mfma_f32_16x16x32_bf16 v[94:97], v[194:197], v[218:221], v[94:97]
	v_mfma_f32_16x16x32_bf16 v[70:73], v[174:177], v[242:245], v[70:73]
	v_mfma_f32_16x16x32_bf16 v[78:81], v[194:197], v[242:245], v[78:81]
	s_barrier
	s_setprio 0
	s_add_i32 s26, s58, s40
	v_lshl_add_u64 v[178:179], v[178:179], 0, s[16:17]
	s_mov_b32 m0, s26
	ds_read_b128 v[198:201], v157 offset:49152
	ds_read_b128 v[202:205], v157 offset:50176
	ds_read_b128 v[206:209], v157 offset:51200
	ds_read_b128 v[210:213], v157 offset:52224
	ds_read_b128 v[214:217], v157 offset:53248
	ds_read_b128 v[218:221], v157 offset:54272
	ds_read_b128 v[238:241], v157 offset:55296
	ds_read_b128 v[242:245], v157 offset:56320
	global_load_lds_dwordx4 v[178:179], off sc0
	s_add_i32 m0, s26, 0x2000
	s_add_u32 s26, s30, 0x158080
	v_lshl_add_u64 v[178:179], v[222:223], 0, s[16:17]
	s_addc_u32 s27, s31, 0
	s_add_i32 s30, s59, s40
	global_load_lds_dwordx4 v[178:179], off sc0
	v_lshl_add_u64 v[178:179], s[26:27], 0, v[136:137]
	s_mov_b32 m0, s30
	s_nop 0
	global_load_lds_dwordx4 v[178:179], off sc0
	v_lshl_add_u64 v[178:179], s[26:27], 0, v[140:141]
	s_add_i32 m0, s30, 0x2000
	s_nop 0
	global_load_lds_dwordx4 v[178:179], off sc0
	v_lshl_add_u64 v[178:179], v[246:247], 0, s[16:17]
	s_mov_b32 m0, s48
	s_nop 0
	global_load_lds_dwordx4 v[178:179], off sc0
	v_lshl_add_u64 v[178:179], v[248:249], 0, s[16:17]
	s_mov_b32 m0, s49
	s_nop 0
	global_load_lds_dwordx4 v[178:179], off sc0
	s_waitcnt vmcnt(8)
	s_waitcnt lgkmcnt(0)
	s_setprio 1
	s_barrier
	v_mfma_f32_16x16x32_bf16 v[50:53], v[148:151], v[198:201], v[50:53]
	v_mfma_f32_16x16x32_bf16 v[38:41], v[162:165], v[198:201], v[38:41]
	v_mfma_f32_16x16x32_bf16 v[22:25], v[148:151], v[206:209], v[22:25]
	v_mfma_f32_16x16x32_bf16 v[42:45], v[162:165], v[206:209], v[42:45]
	v_mfma_f32_16x16x32_bf16 v[30:33], v[148:151], v[214:217], v[30:33]
	v_mfma_f32_16x16x32_bf16 v[18:21], v[162:165], v[214:217], v[18:21]
	v_mfma_f32_16x16x32_bf16 v[10:13], v[148:151], v[238:241], v[10:13]
	v_mfma_f32_16x16x32_bf16 v[2:5], v[162:165], v[238:241], v[2:5]
	v_mfma_f32_16x16x32_bf16 v[50:53], v[158:161], v[202:205], v[50:53]
	v_mfma_f32_16x16x32_bf16 v[38:41], v[166:169], v[202:205], v[38:41]
	v_mfma_f32_16x16x32_bf16 v[22:25], v[158:161], v[210:213], v[22:25]
	v_mfma_f32_16x16x32_bf16 v[42:45], v[166:169], v[210:213], v[42:45]
	v_mfma_f32_16x16x32_bf16 v[30:33], v[158:161], v[218:221], v[30:33]
	v_mfma_f32_16x16x32_bf16 v[18:21], v[166:169], v[218:221], v[18:21]
	v_mfma_f32_16x16x32_bf16 v[10:13], v[158:161], v[242:245], v[10:13]
	v_mfma_f32_16x16x32_bf16 v[2:5], v[166:169], v[242:245], v[2:5]
	v_mfma_f32_16x16x32_bf16 v[46:49], v[170:173], v[198:201], v[46:49]
	v_mfma_f32_16x16x32_bf16 v[58:61], v[190:193], v[198:201], v[58:61]
	v_mfma_f32_16x16x32_bf16 v[62:65], v[170:173], v[206:209], v[62:65]
	v_mfma_f32_16x16x32_bf16 v[66:69], v[190:193], v[206:209], v[66:69]
	v_mfma_f32_16x16x32_bf16 v[26:29], v[170:173], v[214:217], v[26:29]
	v_mfma_f32_16x16x32_bf16 v[34:37], v[190:193], v[214:217], v[34:37]
	v_mfma_f32_16x16x32_bf16 v[6:9], v[170:173], v[238:241], v[6:9]
	v_mfma_f32_16x16x32_bf16 v[14:17], v[190:193], v[238:241], v[14:17]
	v_mfma_f32_16x16x32_bf16 v[46:49], v[174:177], v[202:205], v[46:49]
	v_mfma_f32_16x16x32_bf16 v[58:61], v[194:197], v[202:205], v[58:61]
	v_mfma_f32_16x16x32_bf16 v[62:65], v[174:177], v[210:213], v[62:65]
	v_mfma_f32_16x16x32_bf16 v[66:69], v[194:197], v[210:213], v[66:69]
	v_mfma_f32_16x16x32_bf16 v[26:29], v[174:177], v[218:221], v[26:29]
	v_mfma_f32_16x16x32_bf16 v[34:37], v[194:197], v[218:221], v[34:37]
	v_mfma_f32_16x16x32_bf16 v[6:9], v[174:177], v[242:245], v[6:9]
	v_mfma_f32_16x16x32_bf16 v[14:17], v[194:197], v[242:245], v[14:17]
	s_barrier
	s_setprio 0
	s_add_i32 s57, s57, 2
	s_add_u32 s38, s38, 0x100
	s_addc_u32 s39, s39, 0
	s_cmpk_gt_u32 s57, 0x53
	s_mov_b64 s[26:27], s[28:29]
	s_cbranch_scc0 .LBB0_2241
	s_and_b64 vcc, exec, s[18:19]
	s_cbranch_vccz .LBB0_2244
	s_barrier

.LBB0_2293:
	s_add_u32 s30, s28, 0x100
	s_addc_u32 s31, s29, 0
	s_add_i32 s46, 0, 0x10000
	s_cmpk_eq_i32 s45, 0x52
	s_cselect_b32 s39, s25, s31
	s_cselect_b32 s38, s24, s30
	s_cselect_b32 s35, s27, s44
	s_cselect_b32 s34, s26, s43
	s_add_i32 s47, 0, 0x14000
	v_add_u32_e32 v142, s46, v200
	v_add_u32_e32 v176, s47, v200
	ds_read_b128 v[130:133], v142
	ds_read_b128 v[134:137], v142 offset:1024
	ds_read_b128 v[138:141], v142 offset:2048
	ds_read_b128 v[142:145], v142 offset:3072
	ds_read_b128 v[164:167], v176
	ds_read_b128 v[168:171], v176 offset:1024
	ds_read_b128 v[172:175], v176 offset:2048
	ds_read_b128 v[176:179], v176 offset:3072
	v_lshl_add_u64 v[222:223], s[28:29], 0, v[160:161]
	s_add_i32 m0, s56, 0xc000
	ds_read_b128 v[190:193], v201
	ds_read_b128 v[202:205], v201 offset:1024
	ds_read_b128 v[206:209], v201 offset:2048
	ds_read_b128 v[210:213], v201 offset:3072
	ds_read_b128 v[214:217], v201 offset:4096
	ds_read_b128 v[218:221], v201 offset:5120
	ds_read_b128 v[238:241], v201 offset:6144
	ds_read_b128 v[242:245], v201 offset:7168
	global_load_lds_dwordx4 v[222:223], off sc0
	v_lshl_add_u64 v[222:223], s[28:29], 0, v[162:163]
	s_add_i32 m0, s56, 0xe000
	s_nop 0
	global_load_lds_dwordx4 v[222:223], off sc0
	s_waitcnt vmcnt(8)
	s_waitcnt lgkmcnt(0)
	s_setprio 1
	s_barrier
	v_mfma_f32_16x16x32_bf16 v[118:121], v[130:133], v[190:193], v[118:121]
	v_mfma_f32_16x16x32_bf16 v[114:117], v[138:141], v[190:193], v[114:117]
	v_mfma_f32_16x16x32_bf16 v[98:101], v[130:133], v[206:209], v[98:101]
	v_mfma_f32_16x16x32_bf16 v[102:105], v[138:141], v[206:209], v[102:105]
	v_mfma_f32_16x16x32_bf16 v[70:73], v[130:133], v[214:217], v[70:73]
	v_mfma_f32_16x16x32_bf16 v[74:77], v[138:141], v[214:217], v[74:77]
	v_mfma_f32_16x16x32_bf16 v[30:33], v[130:133], v[238:241], v[30:33]
	v_mfma_f32_16x16x32_bf16 v[34:37], v[138:141], v[238:241], v[34:37]
	v_mfma_f32_16x16x32_bf16 v[118:121], v[134:137], v[202:205], v[118:121]
	v_mfma_f32_16x16x32_bf16 v[114:117], v[142:145], v[202:205], v[114:117]
	v_mfma_f32_16x16x32_bf16 v[98:101], v[134:137], v[210:213], v[98:101]
	v_mfma_f32_16x16x32_bf16 v[102:105], v[142:145], v[210:213], v[102:105]
	v_mfma_f32_16x16x32_bf16 v[70:73], v[134:137], v[218:221], v[70:73]
	v_mfma_f32_16x16x32_bf16 v[74:77], v[142:145], v[218:221], v[74:77]
	v_mfma_f32_16x16x32_bf16 v[30:33], v[134:137], v[242:245], v[30:33]
	v_mfma_f32_16x16x32_bf16 v[34:37], v[142:145], v[242:245], v[34:37]
	v_mfma_f32_16x16x32_bf16 v[126:129], v[164:167], v[190:193], v[126:129]
	v_mfma_f32_16x16x32_bf16 v[122:125], v[172:175], v[190:193], v[122:125]
	v_mfma_f32_16x16x32_bf16 v[106:109], v[164:167], v[206:209], v[106:109]
	v_mfma_f32_16x16x32_bf16 v[110:113], v[172:175], v[206:209], v[110:113]
	v_mfma_f32_16x16x32_bf16 v[82:85], v[164:167], v[214:217], v[82:85]
	v_mfma_f32_16x16x32_bf16 v[86:89], v[172:175], v[214:217], v[86:89]
	v_mfma_f32_16x16x32_bf16 v[54:57], v[164:167], v[238:241], v[54:57]
	v_mfma_f32_16x16x32_bf16 v[58:61], v[172:175], v[238:241], v[58:61]
	v_mfma_f32_16x16x32_bf16 v[126:129], v[168:171], v[202:205], v[126:129]
	v_mfma_f32_16x16x32_bf16 v[122:125], v[176:179], v[202:205], v[122:125]
	v_mfma_f32_16x16x32_bf16 v[106:109], v[168:171], v[210:213], v[106:109]
	v_mfma_f32_16x16x32_bf16 v[110:113], v[176:179], v[210:213], v[110:113]
	v_mfma_f32_16x16x32_bf16 v[82:85], v[168:171], v[218:221], v[82:85]
	v_mfma_f32_16x16x32_bf16 v[86:89], v[176:179], v[218:221], v[86:89]
	v_mfma_f32_16x16x32_bf16 v[54:57], v[168:171], v[242:245], v[54:57]
	v_mfma_f32_16x16x32_bf16 v[58:61], v[176:179], v[242:245], v[58:61]
	s_barrier
	s_setprio 0
	s_add_i32 s28, s46, s21
	v_lshl_add_u64 v[222:223], s[34:35], 0, v[150:151]
	s_mov_b32 m0, s28
	ds_read_b128 v[190:193], v201 offset:16384
	ds_read_b128 v[202:205], v201 offset:17408
	ds_read_b128 v[206:209], v201 offset:18432
	ds_read_b128 v[210:213], v201 offset:19456
	ds_read_b128 v[214:217], v201 offset:20480
	ds_read_b128 v[218:221], v201 offset:21504
	ds_read_b128 v[238:241], v201 offset:22528
	ds_read_b128 v[242:245], v201 offset:23552
	global_load_lds_dwordx4 v[222:223], off sc0
	s_add_i32 m0, s28, 0x2000
	s_add_u32 s28, s34, 0x158000
	v_lshl_add_u64 v[246:247], s[34:35], 0, v[154:155]
	s_addc_u32 s29, s35, 0
	s_add_i32 s46, s47, s21
	global_load_lds_dwordx4 v[246:247], off sc0
	v_lshl_add_u64 v[248:249], s[28:29], 0, v[150:151]
	s_mov_b32 m0, s46
	v_lshl_add_u64 v[250:251], s[38:39], 0, v[152:153]
	global_load_lds_dwordx4 v[248:249], off sc0
	v_lshl_add_u64 v[248:249], s[28:29], 0, v[154:155]
	s_add_i32 m0, s46, 0x2000
	s_nop 0
	global_load_lds_dwordx4 v[248:249], off sc0
	v_lshl_add_u64 v[248:249], s[38:39], 0, v[148:149]
	s_mov_b32 m0, s56
	s_nop 0
	global_load_lds_dwordx4 v[248:249], off sc0
	s_mov_b32 m0, s57
	s_nop 0
	global_load_lds_dwordx4 v[250:251], off sc0
	s_waitcnt vmcnt(8)
	s_waitcnt lgkmcnt(0)
	s_setprio 1
	s_barrier
	v_mfma_f32_16x16x32_bf16 v[22:25], v[130:133], v[190:193], v[22:25]
	v_mfma_f32_16x16x32_bf16 v[26:29], v[138:141], v[190:193], v[26:29]
	v_mfma_f32_16x16x32_bf16 v[10:13], v[130:133], v[206:209], v[10:13]
	v_mfma_f32_16x16x32_bf16 v[78:81], v[138:141], v[206:209], v[78:81]
	v_mfma_f32_16x16x32_bf16 v[38:41], v[130:133], v[214:217], v[38:41]
	v_mfma_f32_16x16x32_bf16 v[42:45], v[138:141], v[214:217], v[42:45]
	v_mfma_f32_16x16x32_bf16 v[2:5], v[130:133], v[238:241], v[2:5]
	v_mfma_f32_16x16x32_bf16 v[6:9], v[138:141], v[238:241], v[6:9]
	v_mfma_f32_16x16x32_bf16 v[22:25], v[134:137], v[202:205], v[22:25]
	v_mfma_f32_16x16x32_bf16 v[26:29], v[142:145], v[202:205], v[26:29]
	v_mfma_f32_16x16x32_bf16 v[10:13], v[134:137], v[210:213], v[10:13]
	v_mfma_f32_16x16x32_bf16 v[78:81], v[142:145], v[210:213], v[78:81]
	v_mfma_f32_16x16x32_bf16 v[38:41], v[134:137], v[218:221], v[38:41]
	v_mfma_f32_16x16x32_bf16 v[42:45], v[142:145], v[218:221], v[42:45]
	v_mfma_f32_16x16x32_bf16 v[2:5], v[134:137], v[242:245], v[2:5]
	v_mfma_f32_16x16x32_bf16 v[6:9], v[142:145], v[242:245], v[6:9]
	v_mfma_f32_16x16x32_bf16 v[46:49], v[164:167], v[190:193], v[46:49]
	v_mfma_f32_16x16x32_bf16 v[50:53], v[172:175], v[190:193], v[50:53]
	v_mfma_f32_16x16x32_bf16 v[90:93], v[164:167], v[206:209], v[90:93]
	v_mfma_f32_16x16x32_bf16 v[94:97], v[172:175], v[206:209], v[94:97]
	v_mfma_f32_16x16x32_bf16 v[62:65], v[164:167], v[214:217], v[62:65]
	v_mfma_f32_16x16x32_bf16 v[66:69], v[172:175], v[214:217], v[66:69]
	v_mfma_f32_16x16x32_bf16 v[14:17], v[164:167], v[238:241], v[14:17]
	v_mfma_f32_16x16x32_bf16 v[18:21], v[172:175], v[238:241], v[18:21]
	v_mfma_f32_16x16x32_bf16 v[46:49], v[168:171], v[202:205], v[46:49]
	v_mfma_f32_16x16x32_bf16 v[50:53], v[176:179], v[202:205], v[50:53]
	v_mfma_f32_16x16x32_bf16 v[90:93], v[168:171], v[210:213], v[90:93]
	v_mfma_f32_16x16x32_bf16 v[94:97], v[176:179], v[210:213], v[94:97]
	v_mfma_f32_16x16x32_bf16 v[62:65], v[168:171], v[218:221], v[62:65]
	v_mfma_f32_16x16x32_bf16 v[66:69], v[176:179], v[218:221], v[66:69]
	v_mfma_f32_16x16x32_bf16 v[14:17], v[168:171], v[242:245], v[14:17]
	v_mfma_f32_16x16x32_bf16 v[18:21], v[176:179], v[242:245], v[18:21]
	s_barrier
	s_setprio 0
	s_add_i32 s46, 0, 0x18000
	s_add_i32 s47, 0, 0x1c000
	v_add_u32_e32 v142, s46, v200
	v_add_u32_e32 v176, s47, v200
	ds_read_b128 v[130:133], v142
	ds_read_b128 v[134:137], v142 offset:1024
	ds_read_b128 v[138:141], v142 offset:2048
	ds_read_b128 v[142:145], v142 offset:3072
	ds_read_b128 v[164:167], v176
	ds_read_b128 v[168:171], v176 offset:1024
	ds_read_b128 v[172:175], v176 offset:2048
	ds_read_b128 v[176:179], v176 offset:3072
	s_add_u32 s28, s38, 0x158000
	s_addc_u32 s29, s39, 0
	s_mov_b32 m0, s58
	v_lshl_add_u64 v[252:253], s[28:29], 0, v[148:149]
	ds_read_b128 v[190:193], v201 offset:32768
	ds_read_b128 v[202:205], v201 offset:33792
	ds_read_b128 v[206:209], v201 offset:34816
	ds_read_b128 v[210:213], v201 offset:35840
	ds_read_b128 v[214:217], v201 offset:36864
	ds_read_b128 v[218:221], v201 offset:37888
	ds_read_b128 v[238:241], v201 offset:38912
	ds_read_b128 v[242:245], v201 offset:39936
	global_load_lds_dwordx4 v[252:253], off sc0
	v_lshl_add_u64 v[252:253], s[28:29], 0, v[152:153]
	s_mov_b32 m0, s59
	s_nop 0
	global_load_lds_dwordx4 v[252:253], off sc0
	s_waitcnt vmcnt(8)
	s_waitcnt lgkmcnt(0)
	s_setprio 1
	s_barrier
	v_mfma_f32_16x16x32_bf16 v[118:121], v[130:133], v[190:193], v[118:121]
	v_mfma_f32_16x16x32_bf16 v[114:117], v[138:141], v[190:193], v[114:117]
	v_mfma_f32_16x16x32_bf16 v[98:101], v[130:133], v[206:209], v[98:101]
	v_mfma_f32_16x16x32_bf16 v[102:105], v[138:141], v[206:209], v[102:105]
	v_mfma_f32_16x16x32_bf16 v[70:73], v[130:133], v[214:217], v[70:73]
	v_mfma_f32_16x16x32_bf16 v[74:77], v[138:141], v[214:217], v[74:77]
	v_mfma_f32_16x16x32_bf16 v[30:33], v[130:133], v[238:241], v[30:33]
	v_mfma_f32_16x16x32_bf16 v[34:37], v[138:141], v[238:241], v[34:37]
	v_mfma_f32_16x16x32_bf16 v[118:121], v[134:137], v[202:205], v[118:121]
	v_mfma_f32_16x16x32_bf16 v[114:117], v[142:145], v[202:205], v[114:117]
	v_mfma_f32_16x16x32_bf16 v[98:101], v[134:137], v[210:213], v[98:101]
	v_mfma_f32_16x16x32_bf16 v[102:105], v[142:145], v[210:213], v[102:105]
	v_mfma_f32_16x16x32_bf16 v[70:73], v[134:137], v[218:221], v[70:73]
	v_mfma_f32_16x16x32_bf16 v[74:77], v[142:145], v[218:221], v[74:77]
	v_mfma_f32_16x16x32_bf16 v[30:33], v[134:137], v[242:245], v[30:33]
	v_mfma_f32_16x16x32_bf16 v[34:37], v[142:145], v[242:245], v[34:37]
	v_mfma_f32_16x16x32_bf16 v[126:129], v[164:167], v[190:193], v[126:129]
	v_mfma_f32_16x16x32_bf16 v[122:125], v[172:175], v[190:193], v[122:125]
	v_mfma_f32_16x16x32_bf16 v[106:109], v[164:167], v[206:209], v[106:109]
	v_mfma_f32_16x16x32_bf16 v[110:113], v[172:175], v[206:209], v[110:113]
	v_mfma_f32_16x16x32_bf16 v[82:85], v[164:167], v[214:217], v[82:85]
	v_mfma_f32_16x16x32_bf16 v[86:89], v[172:175], v[214:217], v[86:89]
	v_mfma_f32_16x16x32_bf16 v[54:57], v[164:167], v[238:241], v[54:57]
	v_mfma_f32_16x16x32_bf16 v[58:61], v[172:175], v[238:241], v[58:61]
	v_mfma_f32_16x16x32_bf16 v[126:129], v[168:171], v[202:205], v[126:129]
	v_mfma_f32_16x16x32_bf16 v[122:125], v[176:179], v[202:205], v[122:125]
	v_mfma_f32_16x16x32_bf16 v[106:109], v[168:171], v[210:213], v[106:109]
	v_mfma_f32_16x16x32_bf16 v[110:113], v[176:179], v[210:213], v[110:113]
	v_mfma_f32_16x16x32_bf16 v[82:85], v[168:171], v[218:221], v[82:85]
	v_mfma_f32_16x16x32_bf16 v[86:89], v[176:179], v[218:221], v[86:89]
	v_mfma_f32_16x16x32_bf16 v[54:57], v[168:171], v[242:245], v[54:57]
	v_mfma_f32_16x16x32_bf16 v[58:61], v[176:179], v[242:245], v[58:61]
	s_barrier
	s_setprio 0
	s_add_i32 s28, s46, s21
	v_lshl_add_u64 v[222:223], v[222:223], 0, s[16:17]
	s_mov_b32 m0, s28
	ds_read_b128 v[190:193], v201 offset:49152
	ds_read_b128 v[202:205], v201 offset:50176
	ds_read_b128 v[206:209], v201 offset:51200
	ds_read_b128 v[210:213], v201 offset:52224
	ds_read_b128 v[214:217], v201 offset:53248
	ds_read_b128 v[218:221], v201 offset:54272
	ds_read_b128 v[238:241], v201 offset:55296
	ds_read_b128 v[242:245], v201 offset:56320
	global_load_lds_dwordx4 v[222:223], off sc0
	s_add_i32 m0, s28, 0x2000
	s_add_u32 s28, s34, 0x158080
	v_lshl_add_u64 v[222:223], v[246:247], 0, s[16:17]
	s_addc_u32 s29, s35, 0
	s_add_i32 s34, s47, s21
	global_load_lds_dwordx4 v[222:223], off sc0
	v_lshl_add_u64 v[222:223], s[28:29], 0, v[150:151]
	s_mov_b32 m0, s34
	s_nop 0
	global_load_lds_dwordx4 v[222:223], off sc0
	v_lshl_add_u64 v[222:223], s[28:29], 0, v[154:155]
	s_add_i32 m0, s34, 0x2000
	s_nop 0
	global_load_lds_dwordx4 v[222:223], off sc0
	v_lshl_add_u64 v[222:223], v[248:249], 0, s[16:17]
	s_mov_b32 m0, s60
	s_nop 0
	global_load_lds_dwordx4 v[222:223], off sc0
	v_lshl_add_u64 v[222:223], v[250:251], 0, s[16:17]
	s_mov_b32 m0, s61
	s_nop 0
	global_load_lds_dwordx4 v[222:223], off sc0
	s_waitcnt vmcnt(8)
	s_waitcnt lgkmcnt(0)
	s_setprio 1
	s_barrier
	v_mfma_f32_16x16x32_bf16 v[22:25], v[130:133], v[190:193], v[22:25]
	v_mfma_f32_16x16x32_bf16 v[26:29], v[138:141], v[190:193], v[26:29]
	v_mfma_f32_16x16x32_bf16 v[10:13], v[130:133], v[206:209], v[10:13]
	v_mfma_f32_16x16x32_bf16 v[78:81], v[138:141], v[206:209], v[78:81]
	v_mfma_f32_16x16x32_bf16 v[38:41], v[130:133], v[214:217], v[38:41]
	v_mfma_f32_16x16x32_bf16 v[42:45], v[138:141], v[214:217], v[42:45]
	v_mfma_f32_16x16x32_bf16 v[2:5], v[130:133], v[238:241], v[2:5]
	v_mfma_f32_16x16x32_bf16 v[6:9], v[138:141], v[238:241], v[6:9]
	v_mfma_f32_16x16x32_bf16 v[22:25], v[134:137], v[202:205], v[22:25]
	v_mfma_f32_16x16x32_bf16 v[26:29], v[142:145], v[202:205], v[26:29]
	v_mfma_f32_16x16x32_bf16 v[10:13], v[134:137], v[210:213], v[10:13]
	v_mfma_f32_16x16x32_bf16 v[78:81], v[142:145], v[210:213], v[78:81]
	v_mfma_f32_16x16x32_bf16 v[38:41], v[134:137], v[218:221], v[38:41]
	v_mfma_f32_16x16x32_bf16 v[42:45], v[142:145], v[218:221], v[42:45]
	v_mfma_f32_16x16x32_bf16 v[2:5], v[134:137], v[242:245], v[2:5]
	v_mfma_f32_16x16x32_bf16 v[6:9], v[142:145], v[242:245], v[6:9]
	v_mfma_f32_16x16x32_bf16 v[46:49], v[164:167], v[190:193], v[46:49]
	v_mfma_f32_16x16x32_bf16 v[50:53], v[172:175], v[190:193], v[50:53]
	v_mfma_f32_16x16x32_bf16 v[90:93], v[164:167], v[206:209], v[90:93]
	v_mfma_f32_16x16x32_bf16 v[94:97], v[172:175], v[206:209], v[94:97]
	v_mfma_f32_16x16x32_bf16 v[62:65], v[164:167], v[214:217], v[62:65]
	v_mfma_f32_16x16x32_bf16 v[66:69], v[172:175], v[214:217], v[66:69]
	v_mfma_f32_16x16x32_bf16 v[14:17], v[164:167], v[238:241], v[14:17]
	v_mfma_f32_16x16x32_bf16 v[18:21], v[172:175], v[238:241], v[18:21]
	v_mfma_f32_16x16x32_bf16 v[46:49], v[168:171], v[202:205], v[46:49]
	v_mfma_f32_16x16x32_bf16 v[50:53], v[176:179], v[202:205], v[50:53]
	v_mfma_f32_16x16x32_bf16 v[90:93], v[168:171], v[210:213], v[90:93]
	v_mfma_f32_16x16x32_bf16 v[94:97], v[176:179], v[210:213], v[94:97]
	v_mfma_f32_16x16x32_bf16 v[62:65], v[168:171], v[218:221], v[62:65]
	v_mfma_f32_16x16x32_bf16 v[66:69], v[176:179], v[218:221], v[66:69]
	v_mfma_f32_16x16x32_bf16 v[14:17], v[168:171], v[242:245], v[14:17]
	v_mfma_f32_16x16x32_bf16 v[18:21], v[176:179], v[242:245], v[18:21]
	s_barrier
	s_setprio 0
	s_add_i32 s45, s45, 2
	s_add_u32 s43, s43, 0x100
	s_addc_u32 s44, s44, 0
	s_cmpk_gt_u32 s45, 0x53
	s_mov_b64 s[28:29], s[30:31]
	s_cbranch_scc0 .LBB0_2293
	s_and_b64 vcc, exec, s[22:23]
	s_cbranch_vccz .LBB0_2296
	s_barrier
